# GEMM unit loops: first load segment fragment reads issued at the top of the unit header (overlaps next-tile index arithmetic)
# speedup vs baseline: 1.0006x; 1.0006x over previous
; #define PG8_STAGE(bufoff, gbase, voff) do { _Pragma("unroll") for (int _i = 0; _i < 2; ++_i) \
;         __builtin_amdgcn_global_load_lds((const unsigned*)((const char*)(gbase) + (voff)[_i]), (PG8_LAS unsigned*)(lds + (bufoff) + ldsw + _i * 8192), 16, 0, 0); } while (0)
; #define PG8_LDA(dst, b, h) do { _Pragma("unroll") for (int m = 0; m < 4; ++m) _Pragma("unroll") for (int k = 0; k < 2; ++k) dst[m][k] = *(const PG8_LAS bf16x8*)(lds + PG8_SA(b, h) + aoff + m * 2048 + k * 1024); } while (0)
; #define PG8_WAIT_V(n) asm volatile("s_waitcnt vmcnt(" #n ")" ::: "memory")
;     __host__ __device__ bool next(int i, Unit& u) const {
;         if (i >= nI) return false;
;         const long L = (long)(rev ? nI - 1 - i : i) * G + c; if (L >= nwg) return false;
;         int wgid = (int)L; { const int q = nwg / NXCD, r = nwg % NXCD, xcd = wgid % NXCD, off = wgid / NXCD; wgid = (xcd < r ? xcd * (q + 1) : r * (q + 1) + (xcd - r) * q) + off; }
;         const int nig = WGM * nN, gid = wgid / nig, fm = gid * WGM, gsz = (nM - fm) < WGM ? (nM - fm) : WGM;
;         u.pm = fm + ((wgid % nig) % gsz); u.pn = (wgid % nig) / gsz; return true;
;     }
; template <class Epi, class Sched, bool ALIGN_EPI = false, bool SP2 = false>
; __device__ __forceinline__ void gemm_phase(PG8_LAS unsigned char* lds, const Gemm g, const Sched& S, const Epi& E) {
;     ...
;         const bool has_next = S.next(ui + 1, nxt);
;         const char* nA = has_next ? (const char*)g.A + (size_t)nxt.pm * tstep : cA; const char* nB = has_next ? (const char*)g.Bt + (size_t)nxt.pn * tstep : cB;
;         for (int t = 0; t < nt; t += 2) {
;             const bool last = (t == nt - 2);
;             const char* a1 = cA + (size_t)(t + 1) * kstep;
;             const char* a2 = last ? nA : cA + (size_t)(t + 2) * kstep; const char* b2 = last ? nB : cB + (size_t)(t + 2) * kstep;
;             const char* a3 = a2 + kstep; const char* b3 = b2 + kstep;
;             if (last && has_next) S.a_ready(nxt);
;             if constexpr (SP2) {
;             PG8_LDB(B0, 0, 0); PG8_LDB(B1, 0, 1); PG8_SCHED; PG8_LDA(At, 0, 0); PG8_STAGE(PG8_SA(1, 1), a1 + hstep, voffA);
;             PG8_WAIT_V(8); PG8_WAIT_L(0); PG8_BAR; PG8_MMA(0, 0, At, B0); PG8_MMA(0, 1, At, B1); PG8_BAR; PG8_SCHED;
;             PG8_LDA(At, 0, 1); PG8_STAGE(PG8_SB(0, 0), b2, voffB); PG8_STAGE(PG8_SB(0, 1), b2 + hstep, voffB); PG8_STAGE(PG8_SA(0, 0), a2, voffA);
.LBB0_87:
	ds_read_b128 v[128:131], v183
	ds_read_b128 v[132:135], v183 offset:1024
	ds_read_b128 v[136:139], v183 offset:2048
	ds_read_b128 v[140:143], v183 offset:3072
	ds_read_b128 v[192:195], v185
	ds_read_b128 v[196:199], v185 offset:1024
	ds_read_b128 v[200:203], v185 offset:2048
	ds_read_b128 v[204:207], v185 offset:3072
	ds_read_b128 v[208:211], v186
	ds_read_b128 v[212:215], v186 offset:1024
	ds_read_b128 v[216:219], v186 offset:2048
	ds_read_b128 v[220:223], v186 offset:3072
	ds_read_b128 v[224:227], v186 offset:4096
	ds_read_b128 v[232:235], v186 offset:5120
	ds_read_b128 v[236:239], v186 offset:6144
	ds_read_b128 v[240:243], v186 offset:7168
	s_add_i32 s22, s23, 1
	s_cmp_ge_i32 s22, s82
	s_mov_b64 s[58:59], 0
	s_cbranch_scc1 .LBB0_90
	s_sub_i32 s23, s96, s23
	s_and_b64 s[24:25], s[8:9], exec
	s_cselect_b32 s23, s23, s22
	s_mul_hi_i32 s24, s23, s74
	s_mul_i32 s23, s23, s74
	s_add_u32 s60, s23, s2
	s_addc_u32 s61, s24, s97
	v_cmp_gt_i64_e32 vcc, s[60:61], v[168:169]
	s_cbranch_vccnz .LBB0_90
	s_ashr_i32 s23, s60, 31
	s_lshr_b32 s23, s23, 29
	s_add_i32 s23, s60, s23
	s_ashr_i32 s24, s23, 3
	s_and_b32 s23, s23, -8
	s_sub_i32 s23, s60, s23
	s_cmp_lt_i32 s23, 0
	s_movk_i32 s25, 0x241
	s_cselect_b32 s25, s25, 0x240
	s_mul_i32 s23, s23, s25
	s_add_i32 s23, s23, s24
	s_mul_hi_i32 s24, s23, 0x38e38e39
	s_lshr_b32 s25, s24, 31
	s_ashr_i32 s24, s24, 4
	s_add_i32 s24, s24, s25
	s_lshl_b32 s25, s24, 3
	s_sub_i32 s26, 0x200, s25
	s_min_i32 s26, s26, 8
	s_abs_i32 s27, s26
	v_cvt_f32_u32_e32 v0, s27
	s_sub_i32 s29, 0, s27
	s_mulk_i32 s24, 0x48
	s_sub_i32 s23, s23, s24
	v_rcp_iflag_f32_e32 v0, v0
	s_abs_i32 s24, s23
	s_xor_b32 s28, s23, s26
	s_ashr_i32 s28, s28, 31
	v_mul_f32_e32 v0, 0x4f7ffffe, v0
	v_cvt_u32_f32_e32 v0, v0
	s_mov_b64 s[58:59], -1
	v_readfirstlane_b32 s30, v0
	s_mul_i32 s29, s29, s30
	s_mul_hi_u32 s29, s30, s29
	s_add_i32 s30, s30, s29
	s_mul_hi_u32 s29, s24, s30
	s_mul_i32 s30, s29, s27
	s_sub_i32 s24, s24, s30
	s_add_i32 s31, s29, 1
	s_sub_i32 s30, s24, s27
	s_cmp_ge_u32 s24, s27
	s_cselect_b32 s29, s31, s29
	s_cselect_b32 s24, s30, s24
	s_add_i32 s30, s29, 1
	s_cmp_ge_u32 s24, s27
	s_cselect_b32 s24, s30, s29
	s_xor_b32 s24, s24, s28
	s_sub_i32 s52, s24, s28
	s_mul_i32 s24, s52, s26
	s_sub_i32 s23, s23, s24
	s_add_i32 s54, s25, s23
.LBB0_90:
	s_ashr_i32 s55, s54, 31
	s_lshl_b64 s[24:25], s[54:55], 19
	s_add_u32 s60, s70, s24
	s_addc_u32 s61, s71, s25
	s_and_b64 s[24:25], s[58:59], exec
	s_cselect_b32 s23, s61, s77
	s_cselect_b32 s24, s60, s76
	s_ashr_i32 s53, s52, 31
	s_lshl_b64 s[26:27], s[52:53], 19
	s_add_u32 s62, s83, s26
	s_addc_u32 s63, s84, s27
	s_and_b64 s[26:27], s[58:59], exec
	s_cselect_b32 s25, s63, s79
	s_cselect_b32 s26, s62, s78
	s_add_u32 s76, s76, 0x40080
	s_addc_u32 s77, s77, 0
	s_add_u32 s27, s78, 0x100
	s_addc_u32 s28, s79, 0
	s_mov_b32 s29, -2
	s_add_u32 s30, s76, 0xfffc0080
	s_addc_u32 s31, s77, -1
	s_cmp_eq_u32 s29, 12
	s_cselect_b32 s81, s23, s31
	s_cselect_b32 s80, s24, s30
	s_cselect_b32 s79, s25, s28
	s_cselect_b32 s78, s26, s27
	v_lshl_add_u64 v[172:173], s[76:77], 0, v[158:159]
	s_add_i32 m0, s87, 0xc000
	global_load_lds_dwordx4 v[172:173], off
	v_lshl_add_u64 v[172:173], s[76:77], 0, v[160:161]
	s_add_i32 m0, s87, 0xe000
	s_nop 0
	global_load_lds_dwordx4 v[172:173], off
	s_waitcnt vmcnt(8)
	s_waitcnt lgkmcnt(0)
	s_barrier
	s_setprio 1
	s_waitcnt lgkmcnt(0)
	v_mfma_f32_16x16x32_bf16 v[124:127], v[128:131], v[208:211], 0
	v_mfma_f32_16x16x32_bf16 v[120:123], v[136:139], v[208:211], 0
	v_mfma_f32_16x16x32_bf16 v[112:115], v[128:131], v[216:219], 0
	v_mfma_f32_16x16x32_bf16 v[108:111], v[136:139], v[216:219], 0
	v_mfma_f32_16x16x32_bf16 v[96:99], v[128:131], v[224:227], 0
	v_mfma_f32_16x16x32_bf16 v[88:91], v[136:139], v[224:227], 0
	v_mfma_f32_16x16x32_bf16 v[80:83], v[128:131], v[236:239], 0
	v_mfma_f32_16x16x32_bf16 v[72:75], v[136:139], v[236:239], 0
	v_mfma_f32_16x16x32_bf16 v[124:127], v[132:135], v[212:215], v[124:127]
	v_mfma_f32_16x16x32_bf16 v[120:123], v[140:143], v[212:215], v[120:123]
	v_mfma_f32_16x16x32_bf16 v[112:115], v[132:135], v[220:223], v[112:115]
	v_mfma_f32_16x16x32_bf16 v[108:111], v[140:143], v[220:223], v[108:111]
	v_mfma_f32_16x16x32_bf16 v[96:99], v[132:135], v[232:235], v[96:99]
	v_mfma_f32_16x16x32_bf16 v[88:91], v[140:143], v[232:235], v[88:91]
	v_mfma_f32_16x16x32_bf16 v[80:83], v[132:135], v[240:243], v[80:83]
	v_mfma_f32_16x16x32_bf16 v[72:75], v[140:143], v[240:243], v[72:75]
	s_setprio 0
	s_setprio 1
	v_mfma_f32_16x16x32_bf16 v[116:119], v[192:195], v[208:211], 0
	v_mfma_f32_16x16x32_bf16 v[104:107], v[200:203], v[208:211], 0
	v_mfma_f32_16x16x32_bf16 v[100:103], v[192:195], v[216:219], 0
	v_mfma_f32_16x16x32_bf16 v[92:95], v[200:203], v[216:219], 0
	v_mfma_f32_16x16x32_bf16 v[84:87], v[192:195], v[224:227], 0
	v_mfma_f32_16x16x32_bf16 v[76:79], v[200:203], v[224:227], 0
	v_mfma_f32_16x16x32_bf16 v[68:71], v[192:195], v[236:239], 0
	v_mfma_f32_16x16x32_bf16 v[64:67], v[200:203], v[236:239], 0
	v_mfma_f32_16x16x32_bf16 v[116:119], v[196:199], v[212:215], v[116:119]
	v_mfma_f32_16x16x32_bf16 v[104:107], v[204:207], v[212:215], v[104:107]
	v_mfma_f32_16x16x32_bf16 v[100:103], v[196:199], v[220:223], v[100:103]
	v_mfma_f32_16x16x32_bf16 v[92:95], v[204:207], v[220:223], v[92:95]
	v_mfma_f32_16x16x32_bf16 v[84:87], v[196:199], v[232:235], v[84:87]
	v_mfma_f32_16x16x32_bf16 v[76:79], v[204:207], v[232:235], v[76:79]
	v_mfma_f32_16x16x32_bf16 v[68:71], v[196:199], v[240:243], v[68:71]
	v_mfma_f32_16x16x32_bf16 v[64:67], v[204:207], v[240:243], v[64:67]
	s_setprio 0
	s_barrier
; #define PG8_STAGE(bufoff, gbase, voff) do { _Pragma("unroll") for (int _i = 0; _i < 2; ++_i) \
;         __builtin_amdgcn_global_load_lds((const unsigned*)((const char*)(gbase) + (voff)[_i]), (PG8_LAS unsigned*)(lds + (bufoff) + ldsw + _i * 8192), 16, 0, 0); } while (0)
; #define PG8_LDA(dst, b, h) do { _Pragma("unroll") for (int m = 0; m < 4; ++m) _Pragma("unroll") for (int k = 0; k < 2; ++k) dst[m][k] = *(const PG8_LAS bf16x8*)(lds + PG8_SA(b, h) + aoff + m * 2048 + k * 1024); } while (0)
; #define PG8_LDB(dst, b, h) do { _Pragma("unroll") for (int n = 0; n < 2; ++n) _Pragma("unroll") for (int k = 0; k < 2; ++k) dst[n][k] = *(const PG8_LAS bf16x8*)(lds + PG8_SB(b, h) + boff + n * 2048 + k * 1024); } while (0)
; #define PG8_MMA(ai, bj, At, Bt) do { __builtin_amdgcn_s_setprio(1); _Pragma("unroll") for (int m = 0; m < 4; ++m) _Pragma("unroll") for (int n = 0; n < 2; ++n) _Pragma("unroll") for (int k = 0; k < 2; ++k) \
;         acc[ai][bj][m][n] = __builtin_amdgcn_mfma_f32_16x16x32_bf16(Bt[n][k], At[m][k], acc[ai][bj][m][n], 0, 0, 0); __builtin_amdgcn_s_setprio(0); } while (0)
; #define PG8_WAIT_V(n) asm volatile("s_waitcnt vmcnt(" #n ")" ::: "memory")
; #define PG8_WAIT_L(n) asm volatile("s_waitcnt lgkmcnt(" #n ")" ::: "memory")
; #define PG8_BAR __builtin_amdgcn_s_barrier()
; #define PG8_SCHED __builtin_amdgcn_sched_barrier(0)
; template <class Epi, class Sched, bool ALIGN_EPI = false, bool SP2 = false>
; __device__ __forceinline__ void gemm_phase(PG8_LAS unsigned char* lds, const Gemm g, const Sched& S, const Epi& E) {
;     ...
;             PG8_LDA(At, 0, 1); PG8_STAGE(PG8_SB(0, 0), b2, voffB); PG8_STAGE(PG8_SB(0, 1), b2 + hstep, voffB); PG8_STAGE(PG8_SA(0, 0), a2, voffA);
;             PG8_WAIT_V(8); PG8_WAIT_L(0); PG8_BAR; PG8_MMA(1, 0, At, B0); PG8_MMA(1, 1, At, B1); PG8_BAR; PG8_SCHED;
;             PG8_LDB(B0, 1, 0); PG8_LDB(B1, 1, 1); PG8_SCHED; PG8_LDA(At, 1, 0); PG8_STAGE(PG8_SA(0, 1), a2 + hstep, voffA);
;             PG8_WAIT_V(8); PG8_WAIT_L(0); PG8_BAR; PG8_MMA(0, 0, At, B0); PG8_MMA(0, 1, At, B1); PG8_BAR; PG8_SCHED;
	s_add_i32 s30, s33, s86
	v_lshl_add_u64 v[172:173], s[78:79], 0, v[146:147]
	s_mov_b32 m0, s30
	ds_read_b128 v[208:211], v186 offset:16384
	ds_read_b128 v[212:215], v186 offset:17408
	ds_read_b128 v[216:219], v186 offset:18432
	ds_read_b128 v[220:223], v186 offset:19456
	ds_read_b128 v[224:227], v186 offset:20480
	ds_read_b128 v[232:235], v186 offset:21504
	ds_read_b128 v[236:239], v186 offset:22528
	ds_read_b128 v[240:243], v186 offset:23552
	global_load_lds_dwordx4 v[172:173], off
	s_add_i32 m0, s30, 0x2000
	s_add_u32 s30, s78, 0x40000
	v_lshl_add_u64 v[228:229], s[78:79], 0, v[150:151]
	s_addc_u32 s31, s79, 0
	s_add_i32 s53, s16, s86
	global_load_lds_dwordx4 v[228:229], off
	v_lshl_add_u64 v[244:245], s[30:31], 0, v[146:147]
	s_mov_b32 m0, s53
	v_lshl_add_u64 v[246:247], s[80:81], 0, v[148:149]
	global_load_lds_dwordx4 v[244:245], off
	v_lshl_add_u64 v[244:245], s[30:31], 0, v[150:151]
	s_add_i32 m0, s53, 0x2000
	s_nop 0
	global_load_lds_dwordx4 v[244:245], off
	v_lshl_add_u64 v[244:245], s[80:81], 0, v[144:145]
	s_mov_b32 m0, s87
	s_nop 0
	global_load_lds_dwordx4 v[244:245], off
	s_mov_b32 m0, s88
	s_nop 0
	global_load_lds_dwordx4 v[246:247], off
	s_waitcnt vmcnt(8)
	s_waitcnt lgkmcnt(0)
	s_barrier
	s_setprio 1
	s_waitcnt lgkmcnt(0)
	v_mfma_f32_16x16x32_bf16 v[60:63], v[128:131], v[208:211], 0
	v_mfma_f32_16x16x32_bf16 v[56:59], v[136:139], v[208:211], 0
	v_mfma_f32_16x16x32_bf16 v[48:51], v[128:131], v[216:219], 0
	v_mfma_f32_16x16x32_bf16 v[44:47], v[136:139], v[216:219], 0
	v_mfma_f32_16x16x32_bf16 v[32:35], v[128:131], v[224:227], 0
	v_mfma_f32_16x16x32_bf16 v[28:31], v[136:139], v[224:227], 0
	v_mfma_f32_16x16x32_bf16 v[16:19], v[128:131], v[236:239], 0
	v_mfma_f32_16x16x32_bf16 v[12:15], v[136:139], v[236:239], 0
	v_mfma_f32_16x16x32_bf16 v[60:63], v[132:135], v[212:215], v[60:63]
	v_mfma_f32_16x16x32_bf16 v[56:59], v[140:143], v[212:215], v[56:59]
	v_mfma_f32_16x16x32_bf16 v[48:51], v[132:135], v[220:223], v[48:51]
	v_mfma_f32_16x16x32_bf16 v[44:47], v[140:143], v[220:223], v[44:47]
	v_mfma_f32_16x16x32_bf16 v[32:35], v[132:135], v[232:235], v[32:35]
	v_mfma_f32_16x16x32_bf16 v[28:31], v[140:143], v[232:235], v[28:31]
	v_mfma_f32_16x16x32_bf16 v[16:19], v[132:135], v[240:243], v[16:19]
	v_mfma_f32_16x16x32_bf16 v[12:15], v[140:143], v[240:243], v[12:15]
	s_setprio 0
	s_setprio 1
	v_mfma_f32_16x16x32_bf16 v[52:55], v[192:195], v[208:211], 0
	v_mfma_f32_16x16x32_bf16 v[40:43], v[200:203], v[208:211], 0
	v_mfma_f32_16x16x32_bf16 v[36:39], v[192:195], v[216:219], 0
	v_mfma_f32_16x16x32_bf16 v[24:27], v[200:203], v[216:219], 0
	v_mfma_f32_16x16x32_bf16 v[20:23], v[192:195], v[224:227], 0
	v_mfma_f32_16x16x32_bf16 v[8:11], v[200:203], v[224:227], 0
	v_mfma_f32_16x16x32_bf16 v[4:7], v[192:195], v[236:239], 0
	v_mfma_f32_16x16x32_bf16 v[0:3], v[200:203], v[236:239], 0
	v_mfma_f32_16x16x32_bf16 v[52:55], v[196:199], v[212:215], v[52:55]
	v_mfma_f32_16x16x32_bf16 v[40:43], v[204:207], v[212:215], v[40:43]
	v_mfma_f32_16x16x32_bf16 v[36:39], v[196:199], v[220:223], v[36:39]
	v_mfma_f32_16x16x32_bf16 v[24:27], v[204:207], v[220:223], v[24:27]
	v_mfma_f32_16x16x32_bf16 v[20:23], v[196:199], v[232:235], v[20:23]
	v_mfma_f32_16x16x32_bf16 v[8:11], v[204:207], v[232:235], v[8:11]
	v_mfma_f32_16x16x32_bf16 v[4:7], v[196:199], v[240:243], v[4:7]
	v_mfma_f32_16x16x32_bf16 v[0:3], v[204:207], v[240:243], v[0:3]
	s_setprio 0
	s_barrier
	s_add_i32 s53, 0, 0x18000
	s_add_i32 s55, 0, 0x1c000
	v_add_u32_e32 v140, s53, v177
	v_add_u32_e32 v163, s55, v177
	ds_read_b128 v[128:131], v140
	ds_read_b128 v[132:135], v140 offset:1024
	ds_read_b128 v[136:139], v140 offset:2048
	ds_read_b128 v[140:143], v140 offset:3072
	ds_read_b128 v[192:195], v163
	ds_read_b128 v[196:199], v163 offset:1024
	ds_read_b128 v[200:203], v163 offset:2048
	ds_read_b128 v[204:207], v163 offset:3072
	s_add_u32 s30, s80, 0x40000
	s_addc_u32 s31, s81, 0
	s_mov_b32 m0, s89
	v_lshl_add_u64 v[248:249], s[30:31], 0, v[144:145]
	ds_read_b128 v[208:211], v186 offset:32768
	ds_read_b128 v[212:215], v186 offset:33792
	ds_read_b128 v[216:219], v186 offset:34816
	ds_read_b128 v[220:223], v186 offset:35840
	ds_read_b128 v[224:227], v186 offset:36864
	ds_read_b128 v[232:235], v186 offset:37888
	ds_read_b128 v[236:239], v186 offset:38912
	ds_read_b128 v[240:243], v186 offset:39936
	global_load_lds_dwordx4 v[248:249], off
	v_lshl_add_u64 v[248:249], s[30:31], 0, v[148:149]
	s_mov_b32 m0, s90
	s_nop 0
	global_load_lds_dwordx4 v[248:249], off
	s_waitcnt vmcnt(8)
	s_waitcnt lgkmcnt(0)
	s_barrier
; #define PG8_STAGE(bufoff, gbase, voff) do { _Pragma("unroll") for (int _i = 0; _i < 2; ++_i) \
;         __builtin_amdgcn_global_load_lds((const unsigned*)((const char*)(gbase) + (voff)[_i]), (PG8_LAS unsigned*)(lds + (bufoff) + ldsw + _i * 8192), 16, 0, 0); } while (0)
; #define PG8_LDA(dst, b, h) do { _Pragma("unroll") for (int m = 0; m < 4; ++m) _Pragma("unroll") for (int k = 0; k < 2; ++k) dst[m][k] = *(const PG8_LAS bf16x8*)(lds + PG8_SA(b, h) + aoff + m * 2048 + k * 1024); } while (0)
; #define PG8_LDB(dst, b, h) do { _Pragma("unroll") for (int n = 0; n < 2; ++n) _Pragma("unroll") for (int k = 0; k < 2; ++k) dst[n][k] = *(const PG8_LAS bf16x8*)(lds + PG8_SB(b, h) + boff + n * 2048 + k * 1024); } while (0)
; #define PG8_MMA(ai, bj, At, Bt) do { __builtin_amdgcn_s_setprio(1); _Pragma("unroll") for (int m = 0; m < 4; ++m) _Pragma("unroll") for (int n = 0; n < 2; ++n) _Pragma("unroll") for (int k = 0; k < 2; ++k) \
;         acc[ai][bj][m][n] = __builtin_amdgcn_mfma_f32_16x16x32_bf16(Bt[n][k], At[m][k], acc[ai][bj][m][n], 0, 0, 0); __builtin_amdgcn_s_setprio(0); } while (0)
; #define PG8_WAIT_V(n) asm volatile("s_waitcnt vmcnt(" #n ")" ::: "memory")
; #define PG8_WAIT_L(n) asm volatile("s_waitcnt lgkmcnt(" #n ")" ::: "memory")
; #define PG8_BAR __builtin_amdgcn_s_barrier()
; #define PG8_SCHED __builtin_amdgcn_sched_barrier(0)
; template <class Epi, class Sched, bool ALIGN_EPI = false, bool SP2 = false>
; __device__ __forceinline__ void gemm_phase(PG8_LAS unsigned char* lds, const Gemm g, const Sched& S, const Epi& E) {
;     ...
;             PG8_LDB(B0, 1, 0); PG8_LDB(B1, 1, 1); PG8_SCHED; PG8_LDA(At, 1, 0); PG8_STAGE(PG8_SA(0, 1), a2 + hstep, voffA);
;             PG8_WAIT_V(8); PG8_WAIT_L(0); PG8_BAR; PG8_MMA(0, 0, At, B0); PG8_MMA(0, 1, At, B1); PG8_BAR; PG8_SCHED;
;             PG8_LDA(At, 1, 1); PG8_STAGE(PG8_SB(1, 0), b3, voffB); PG8_STAGE(PG8_SB(1, 1), b3 + hstep, voffB); PG8_STAGE(PG8_SA(1, 0), a3, voffA);
;             PG8_WAIT_V(8); PG8_WAIT_L(0); PG8_BAR; PG8_MMA(1, 0, At, B0); PG8_MMA(1, 1, At, B1); PG8_BAR; PG8_SCHED;
	s_setprio 1
	s_waitcnt lgkmcnt(0)
	v_mfma_f32_16x16x32_bf16 v[124:127], v[128:131], v[208:211], v[124:127]
	v_mfma_f32_16x16x32_bf16 v[120:123], v[136:139], v[208:211], v[120:123]
	v_mfma_f32_16x16x32_bf16 v[112:115], v[128:131], v[216:219], v[112:115]
	v_mfma_f32_16x16x32_bf16 v[108:111], v[136:139], v[216:219], v[108:111]
	v_mfma_f32_16x16x32_bf16 v[96:99], v[128:131], v[224:227], v[96:99]
	v_mfma_f32_16x16x32_bf16 v[88:91], v[136:139], v[224:227], v[88:91]
	v_mfma_f32_16x16x32_bf16 v[80:83], v[128:131], v[236:239], v[80:83]
	v_mfma_f32_16x16x32_bf16 v[72:75], v[136:139], v[236:239], v[72:75]
	v_mfma_f32_16x16x32_bf16 v[124:127], v[132:135], v[212:215], v[124:127]
	v_mfma_f32_16x16x32_bf16 v[120:123], v[140:143], v[212:215], v[120:123]
	v_mfma_f32_16x16x32_bf16 v[112:115], v[132:135], v[220:223], v[112:115]
	v_mfma_f32_16x16x32_bf16 v[108:111], v[140:143], v[220:223], v[108:111]
	v_mfma_f32_16x16x32_bf16 v[96:99], v[132:135], v[232:235], v[96:99]
	v_mfma_f32_16x16x32_bf16 v[88:91], v[140:143], v[232:235], v[88:91]
	v_mfma_f32_16x16x32_bf16 v[80:83], v[132:135], v[240:243], v[80:83]
	v_mfma_f32_16x16x32_bf16 v[72:75], v[140:143], v[240:243], v[72:75]
	s_setprio 0
	s_setprio 1
	v_mfma_f32_16x16x32_bf16 v[116:119], v[192:195], v[208:211], v[116:119]
	v_mfma_f32_16x16x32_bf16 v[104:107], v[200:203], v[208:211], v[104:107]
	v_mfma_f32_16x16x32_bf16 v[100:103], v[192:195], v[216:219], v[100:103]
	v_mfma_f32_16x16x32_bf16 v[92:95], v[200:203], v[216:219], v[92:95]
	v_mfma_f32_16x16x32_bf16 v[84:87], v[192:195], v[224:227], v[84:87]
	v_mfma_f32_16x16x32_bf16 v[76:79], v[200:203], v[224:227], v[76:79]
	v_mfma_f32_16x16x32_bf16 v[68:71], v[192:195], v[236:239], v[68:71]
	v_mfma_f32_16x16x32_bf16 v[64:67], v[200:203], v[236:239], v[64:67]
	v_mfma_f32_16x16x32_bf16 v[116:119], v[196:199], v[212:215], v[116:119]
	v_mfma_f32_16x16x32_bf16 v[104:107], v[204:207], v[212:215], v[104:107]
	v_mfma_f32_16x16x32_bf16 v[100:103], v[196:199], v[220:223], v[100:103]
	v_mfma_f32_16x16x32_bf16 v[92:95], v[204:207], v[220:223], v[92:95]
	v_mfma_f32_16x16x32_bf16 v[84:87], v[196:199], v[232:235], v[84:87]
	v_mfma_f32_16x16x32_bf16 v[76:79], v[204:207], v[232:235], v[76:79]
	v_mfma_f32_16x16x32_bf16 v[68:71], v[196:199], v[240:243], v[68:71]
	v_mfma_f32_16x16x32_bf16 v[64:67], v[204:207], v[240:243], v[64:67]
	s_setprio 0
	s_barrier
	s_add_i32 s30, s53, s86
	v_lshl_add_u64 v[172:173], v[172:173], 0, s[18:19]
	s_mov_b32 m0, s30
	ds_read_b128 v[208:211], v186 offset:49152
	ds_read_b128 v[212:215], v186 offset:50176
	ds_read_b128 v[216:219], v186 offset:51200
	ds_read_b128 v[220:223], v186 offset:52224
	ds_read_b128 v[224:227], v186 offset:53248
	ds_read_b128 v[232:235], v186 offset:54272
	ds_read_b128 v[236:239], v186 offset:55296
	ds_read_b128 v[240:243], v186 offset:56320
	global_load_lds_dwordx4 v[172:173], off
	s_add_i32 m0, s30, 0x2000
	s_add_u32 s30, s78, 0x40080
	v_lshl_add_u64 v[172:173], v[228:229], 0, s[18:19]
	s_addc_u32 s31, s79, 0
	s_add_i32 s53, s55, s86
	global_load_lds_dwordx4 v[172:173], off
	v_lshl_add_u64 v[172:173], s[30:31], 0, v[146:147]
	s_mov_b32 m0, s53
	s_nop 0
	global_load_lds_dwordx4 v[172:173], off
	v_lshl_add_u64 v[172:173], s[30:31], 0, v[150:151]
	s_add_i32 m0, s53, 0x2000
	s_nop 0
	global_load_lds_dwordx4 v[172:173], off
	v_lshl_add_u64 v[172:173], v[244:245], 0, s[18:19]
	s_mov_b32 m0, s93
	s_nop 0
	global_load_lds_dwordx4 v[172:173], off
	v_lshl_add_u64 v[172:173], v[246:247], 0, s[18:19]
	s_mov_b32 m0, s94
	s_nop 0
	global_load_lds_dwordx4 v[172:173], off
	s_waitcnt vmcnt(8)
	s_waitcnt lgkmcnt(0)
	s_barrier
	s_setprio 1
	s_waitcnt lgkmcnt(0)
	v_mfma_f32_16x16x32_bf16 v[60:63], v[128:131], v[208:211], v[60:63]
	v_mfma_f32_16x16x32_bf16 v[56:59], v[136:139], v[208:211], v[56:59]
	v_mfma_f32_16x16x32_bf16 v[48:51], v[128:131], v[216:219], v[48:51]
	v_mfma_f32_16x16x32_bf16 v[44:47], v[136:139], v[216:219], v[44:47]
	v_mfma_f32_16x16x32_bf16 v[32:35], v[128:131], v[224:227], v[32:35]
	v_mfma_f32_16x16x32_bf16 v[28:31], v[136:139], v[224:227], v[28:31]
	v_mfma_f32_16x16x32_bf16 v[16:19], v[128:131], v[236:239], v[16:19]
	v_mfma_f32_16x16x32_bf16 v[12:15], v[136:139], v[236:239], v[12:15]
	v_mfma_f32_16x16x32_bf16 v[60:63], v[132:135], v[212:215], v[60:63]
	v_mfma_f32_16x16x32_bf16 v[56:59], v[140:143], v[212:215], v[56:59]
	v_mfma_f32_16x16x32_bf16 v[48:51], v[132:135], v[220:223], v[48:51]
	v_mfma_f32_16x16x32_bf16 v[44:47], v[140:143], v[220:223], v[44:47]
	v_mfma_f32_16x16x32_bf16 v[32:35], v[132:135], v[232:235], v[32:35]
	v_mfma_f32_16x16x32_bf16 v[28:31], v[140:143], v[232:235], v[28:31]
	v_mfma_f32_16x16x32_bf16 v[16:19], v[132:135], v[240:243], v[16:19]
	v_mfma_f32_16x16x32_bf16 v[12:15], v[140:143], v[240:243], v[12:15]
	s_setprio 0
	s_setprio 1
	v_mfma_f32_16x16x32_bf16 v[52:55], v[192:195], v[208:211], v[52:55]
	v_mfma_f32_16x16x32_bf16 v[40:43], v[200:203], v[208:211], v[40:43]
	v_mfma_f32_16x16x32_bf16 v[36:39], v[192:195], v[216:219], v[36:39]
	v_mfma_f32_16x16x32_bf16 v[24:27], v[200:203], v[216:219], v[24:27]
	v_mfma_f32_16x16x32_bf16 v[20:23], v[192:195], v[224:227], v[20:23]
	v_mfma_f32_16x16x32_bf16 v[8:11], v[200:203], v[224:227], v[8:11]
	v_mfma_f32_16x16x32_bf16 v[4:7], v[192:195], v[236:239], v[4:7]
	v_mfma_f32_16x16x32_bf16 v[0:3], v[200:203], v[236:239], v[0:3]
	v_mfma_f32_16x16x32_bf16 v[52:55], v[196:199], v[212:215], v[52:55]
	v_mfma_f32_16x16x32_bf16 v[40:43], v[204:207], v[212:215], v[40:43]
	v_mfma_f32_16x16x32_bf16 v[36:39], v[196:199], v[220:223], v[36:39]
	v_mfma_f32_16x16x32_bf16 v[24:27], v[204:207], v[220:223], v[24:27]
	v_mfma_f32_16x16x32_bf16 v[20:23], v[196:199], v[232:235], v[20:23]
	v_mfma_f32_16x16x32_bf16 v[8:11], v[204:207], v[232:235], v[8:11]
	v_mfma_f32_16x16x32_bf16 v[4:7], v[196:199], v[240:243], v[4:7]
	v_mfma_f32_16x16x32_bf16 v[0:3], v[204:207], v[240:243], v[0:3]
	s_setprio 0
	s_barrier
	s_add_i32 s29, s29, 2
	s_add_u32 s76, s76, 0x100
	s_addc_u32 s77, s77, 0
	s_add_u32 s27, s27, 0x100
	s_addc_u32 s28, s28, 0
	s_cmp_gt_u32 s29, 13

; #define PG8_STAGE(bufoff, gbase, voff) do { _Pragma("unroll") for (int _i = 0; _i < 2; ++_i) \
;         __builtin_amdgcn_global_load_lds((const unsigned*)((const char*)(gbase) + (voff)[_i]), (PG8_LAS unsigned*)(lds + (bufoff) + ldsw + _i * 8192), 16, 0, 0); } while (0)
; #define PG8_LDA(dst, b, h) do { _Pragma("unroll") for (int m = 0; m < 4; ++m) _Pragma("unroll") for (int k = 0; k < 2; ++k) dst[m][k] = *(const PG8_LAS bf16x8*)(lds + PG8_SA(b, h) + aoff + m * 2048 + k * 1024); } while (0)
; #define PG8_LDB(dst, b, h) do { _Pragma("unroll") for (int n = 0; n < 2; ++n) _Pragma("unroll") for (int k = 0; k < 2; ++k) dst[n][k] = *(const PG8_LAS bf16x8*)(lds + PG8_SB(b, h) + boff + n * 2048 + k * 1024); } while (0)
; #define PG8_SCHED __builtin_amdgcn_sched_barrier(0)
;     __host__ __device__ bool next(int i, Unit& u) const {
;         if (i >= nI) return false;
;         const long L = (long)(rev ? nI - 1 - i : i) * G + c; if (L >= nwg) return false;
;         int wgid = (int)L; { const int q = nwg / NXCD, r = nwg % NXCD, xcd = wgid % NXCD, off = wgid / NXCD; wgid = (xcd < r ? xcd * (q + 1) : r * (q + 1) + (xcd - r) * q) + off; }
;         const int nig = WGM * nN, gid = wgid / nig, fm = gid * WGM, gsz = (nM - fm) < WGM ? (nM - fm) : WGM;
;         u.pm = fm + ((wgid % nig) % gsz); u.pn = (wgid % nig) / gsz; return true;
;     }
; template <class Epi, class Sched, bool ALIGN_EPI = false, bool SP2 = false>
; __device__ __forceinline__ void gemm_phase(PG8_LAS unsigned char* lds, const Gemm g, const Sched& S, const Epi& E) {
;     ...
;             PG8_LDB(B0, 0, 0); PG8_LDB(B1, 0, 1); PG8_SCHED; PG8_LDA(At, 0, 0); PG8_STAGE(PG8_SA(1, 1), a1 + hstep, voffA);
.LBB0_385:
	ds_read_b128 v[124:127], v234
	ds_read_b128 v[132:135], v234 offset:1024
	ds_read_b128 v[136:139], v234 offset:2048
	ds_read_b128 v[140:143], v234 offset:3072
	ds_read_b128 v[144:147], v235
	ds_read_b128 v[148:151], v235 offset:1024
	ds_read_b128 v[152:155], v235 offset:2048
	ds_read_b128 v[156:159], v235 offset:3072
	ds_read_b128 v[160:163], v236
	ds_read_b128 v[164:167], v236 offset:1024
	ds_read_b128 v[168:171], v236 offset:2048
	ds_read_b128 v[172:175], v236 offset:3072
	ds_read_b128 v[176:179], v236 offset:4096
	ds_read_b128 v[180:183], v236 offset:5120
	ds_read_b128 v[198:201], v236 offset:6144
	ds_read_b128 v[202:205], v236 offset:7168
	s_add_i32 s58, s37, 1
	s_cmp_ge_i32 s58, s22
	s_mov_b64 s[40:41], 0
	s_cbranch_scc1 .LBB0_392
	s_sub_i32 s37, s54, s37
	s_and_b64 s[40:41], s[8:9], exec
	s_cselect_b32 s37, s37, s58
	s_mul_hi_i32 s39, s37, s74
	s_mul_i32 s37, s37, s74
	s_add_u32 s42, s37, s2
	s_addc_u32 s43, s39, s55
	v_cmp_gt_i64_e32 vcc, s[42:43], v[196:197]
	s_mov_b64 s[40:41], 0
	s_cbranch_vccnz .LBB0_392
	s_ashr_i32 s36, s42, 31
	s_lshr_b32 s36, s36, 29
	s_add_i32 s38, s42, s36
	s_and_b32 s36, s38, -8
	s_sub_i32 s39, s42, s36
	s_cmp_gt_i32 s39, -1
	s_mov_b64 s[36:37], -1
	s_cbranch_scc0 .LBB0_389
	s_lshl_b32 s40, s39, 8
	s_mov_b64 s[36:37], 0

; #define PG8_STAGE(bufoff, gbase, voff) do { _Pragma("unroll") for (int _i = 0; _i < 2; ++_i) \
;         __builtin_amdgcn_global_load_lds((const unsigned*)((const char*)(gbase) + (voff)[_i]), (PG8_LAS unsigned*)(lds + (bufoff) + ldsw + _i * 8192), 16, 0, 0); } while (0)
; #define PG8_LDA(dst, b, h) do { _Pragma("unroll") for (int m = 0; m < 4; ++m) _Pragma("unroll") for (int k = 0; k < 2; ++k) dst[m][k] = *(const PG8_LAS bf16x8*)(lds + PG8_SA(b, h) + aoff + m * 2048 + k * 1024); } while (0)
; #define PG8_LDB(dst, b, h) do { _Pragma("unroll") for (int n = 0; n < 2; ++n) _Pragma("unroll") for (int k = 0; k < 2; ++k) dst[n][k] = *(const PG8_LAS bf16x8*)(lds + PG8_SB(b, h) + boff + n * 2048 + k * 1024); } while (0)
; #define PG8_WAIT_V(n) asm volatile("s_waitcnt vmcnt(" #n ")" ::: "memory")
; #define PG8_WAIT_L(n) asm volatile("s_waitcnt lgkmcnt(" #n ")" ::: "memory")
; #define PG8_BAR __builtin_amdgcn_s_barrier()
; #define PG8_SCHED __builtin_amdgcn_sched_barrier(0)
; template <class Epi, class Sched, bool ALIGN_EPI = false, bool SP2 = false>
; __device__ __forceinline__ void gemm_phase(PG8_LAS unsigned char* lds, const Gemm g, const Sched& S, const Epi& E) {
;     ...
;         const char* nA = has_next ? (const char*)g.A + (size_t)nxt.pm * tstep : cA; const char* nB = has_next ? (const char*)g.Bt + (size_t)nxt.pn * tstep : cB;
;         for (int t = 0; t < nt; t += 2) {
;             const bool last = (t == nt - 2);
;             const char* a1 = cA + (size_t)(t + 1) * kstep;
;             const char* a2 = last ? nA : cA + (size_t)(t + 2) * kstep; const char* b2 = last ? nB : cB + (size_t)(t + 2) * kstep;
;             const char* a3 = a2 + kstep; const char* b3 = b2 + kstep;
;             if (last && has_next) S.a_ready(nxt);
;             if constexpr (SP2) {
;             PG8_LDB(B0, 0, 0); PG8_LDB(B1, 0, 1); PG8_SCHED; PG8_LDA(At, 0, 0); PG8_STAGE(PG8_SA(1, 1), a1 + hstep, voffA);
;             PG8_WAIT_V(8); PG8_WAIT_L(0); PG8_BAR; PG8_MMA(0, 0, At, B0); PG8_MMA(0, 1, At, B1); PG8_BAR; PG8_SCHED;
;             PG8_LDA(At, 0, 1); PG8_STAGE(PG8_SB(0, 0), b2, voffB); PG8_STAGE(PG8_SB(0, 1), b2 + hstep, voffB); PG8_STAGE(PG8_SA(0, 0), a2, voffA);
;             PG8_WAIT_V(8); PG8_WAIT_L(0); PG8_BAR; PG8_MMA(1, 0, At, B0); PG8_MMA(1, 1, At, B1); PG8_BAR; PG8_SCHED;
.LBB0_392:
	s_ashr_i32 s39, s38, 31
	s_lshl_b64 s[42:43], s[38:39], 19
	s_add_u32 s42, s68, s42
	s_addc_u32 s43, s69, s43
	s_and_b64 s[44:45], s[40:41], exec
	s_cselect_b32 s39, s43, s49
	s_cselect_b32 s47, s42, s48
	s_ashr_i32 s37, s36, 31
	s_lshl_b64 s[44:45], s[36:37], 19
	s_add_u32 s44, s23, s44
	s_addc_u32 s45, s24, s45
	s_and_b64 s[52:53], s[40:41], exec
	s_cselect_b32 s37, s45, s51
	s_cselect_b32 s59, s44, s50
	s_add_u32 s48, s48, 0x40080
	s_addc_u32 s49, s49, 0
	s_add_u32 s60, s50, 0x100
	s_addc_u32 s61, s51, 0
	s_mov_b32 s62, -2
	s_waitcnt lgkmcnt(0)
	s_add_u32 s50, s48, 0xfffc0080
	s_addc_u32 s51, s49, -1
	s_cmp_eq_u32 s62, 12
	s_cselect_b32 s53, s39, s51
	s_cselect_b32 s52, s47, s50
	s_cselect_b32 s51, s37, s61
	s_cselect_b32 s50, s59, s60
	v_lshl_add_u64 v[206:207], s[48:49], 0, v[192:193]
	s_add_i32 m0, s26, 0xc000
	global_load_lds_dwordx4 v[206:207], off
	v_lshl_add_u64 v[206:207], s[48:49], 0, v[194:195]
	s_add_i32 m0, s26, 0xe000
	s_nop 0
	global_load_lds_dwordx4 v[206:207], off
	s_waitcnt vmcnt(8)
	s_waitcnt lgkmcnt(0)
	s_barrier
	s_setprio 1
	s_waitcnt lgkmcnt(0)
	v_mfma_f32_16x16x32_bf16 v[128:131], v[124:127], v[160:163], 0
	v_mfma_f32_16x16x32_bf16 v[120:123], v[136:139], v[160:163], 0
	v_mfma_f32_16x16x32_bf16 v[108:111], v[124:127], v[168:171], 0
	v_mfma_f32_16x16x32_bf16 v[104:107], v[136:139], v[168:171], 0
	v_mfma_f32_16x16x32_bf16 v[92:95], v[124:127], v[176:179], 0
	v_mfma_f32_16x16x32_bf16 v[88:91], v[136:139], v[176:179], 0
	v_mfma_f32_16x16x32_bf16 v[76:79], v[124:127], v[198:201], 0
	v_mfma_f32_16x16x32_bf16 v[72:75], v[136:139], v[198:201], 0
	v_mfma_f32_16x16x32_bf16 v[128:131], v[132:135], v[164:167], v[128:131]
	v_mfma_f32_16x16x32_bf16 v[120:123], v[140:143], v[164:167], v[120:123]
	v_mfma_f32_16x16x32_bf16 v[108:111], v[132:135], v[172:175], v[108:111]
	v_mfma_f32_16x16x32_bf16 v[104:107], v[140:143], v[172:175], v[104:107]
	v_mfma_f32_16x16x32_bf16 v[92:95], v[132:135], v[180:183], v[92:95]
	v_mfma_f32_16x16x32_bf16 v[88:91], v[140:143], v[180:183], v[88:91]
	v_mfma_f32_16x16x32_bf16 v[76:79], v[132:135], v[202:205], v[76:79]
	v_mfma_f32_16x16x32_bf16 v[72:75], v[140:143], v[202:205], v[72:75]
	s_setprio 0
	s_setprio 1
	v_mfma_f32_16x16x32_bf16 v[116:119], v[144:147], v[160:163], 0
	v_mfma_f32_16x16x32_bf16 v[112:115], v[152:155], v[160:163], 0
	v_mfma_f32_16x16x32_bf16 v[100:103], v[144:147], v[168:171], 0
	v_mfma_f32_16x16x32_bf16 v[96:99], v[152:155], v[168:171], 0
	v_mfma_f32_16x16x32_bf16 v[84:87], v[144:147], v[176:179], 0
	v_mfma_f32_16x16x32_bf16 v[80:83], v[152:155], v[176:179], 0
	v_mfma_f32_16x16x32_bf16 v[68:71], v[144:147], v[198:201], 0
	v_mfma_f32_16x16x32_bf16 v[64:67], v[152:155], v[198:201], 0
	v_mfma_f32_16x16x32_bf16 v[116:119], v[148:151], v[164:167], v[116:119]
	v_mfma_f32_16x16x32_bf16 v[112:115], v[156:159], v[164:167], v[112:115]
	v_mfma_f32_16x16x32_bf16 v[100:103], v[148:151], v[172:175], v[100:103]
	v_mfma_f32_16x16x32_bf16 v[96:99], v[156:159], v[172:175], v[96:99]
	v_mfma_f32_16x16x32_bf16 v[84:87], v[148:151], v[180:183], v[84:87]
	v_mfma_f32_16x16x32_bf16 v[80:83], v[156:159], v[180:183], v[80:83]
	v_mfma_f32_16x16x32_bf16 v[68:71], v[148:151], v[202:205], v[68:71]
	v_mfma_f32_16x16x32_bf16 v[64:67], v[156:159], v[202:205], v[64:67]
	s_setprio 0
	s_barrier
	s_add_i32 s63, s56, s25
	v_lshl_add_u64 v[206:207], s[50:51], 0, v[186:187]
	s_mov_b32 m0, s63
	ds_read_b128 v[160:163], v236 offset:16384
	ds_read_b128 v[164:167], v236 offset:17408
	ds_read_b128 v[168:171], v236 offset:18432
	ds_read_b128 v[172:175], v236 offset:19456
	ds_read_b128 v[176:179], v236 offset:20480
	ds_read_b128 v[180:183], v236 offset:21504
	ds_read_b128 v[198:201], v236 offset:22528
	ds_read_b128 v[202:205], v236 offset:23552
	global_load_lds_dwordx4 v[206:207], off
	s_add_i32 m0, s63, 0x2000
	s_add_u32 s64, s50, 0x40000
	v_lshl_add_u64 v[208:209], s[50:51], 0, v[190:191]
	s_addc_u32 s65, s51, 0
	s_add_i32 s63, s57, s25
	global_load_lds_dwordx4 v[208:209], off
	v_lshl_add_u64 v[210:211], s[64:65], 0, v[186:187]
	s_mov_b32 m0, s63
	v_lshl_add_u64 v[212:213], s[52:53], 0, v[188:189]
	global_load_lds_dwordx4 v[210:211], off
	v_lshl_add_u64 v[210:211], s[64:65], 0, v[190:191]
	s_add_i32 m0, s63, 0x2000
	s_nop 0
	global_load_lds_dwordx4 v[210:211], off
	v_lshl_add_u64 v[210:211], s[52:53], 0, v[184:185]
	s_mov_b32 m0, s26
	s_nop 0
	global_load_lds_dwordx4 v[210:211], off
	s_mov_b32 m0, s27
	s_nop 0
	global_load_lds_dwordx4 v[212:213], off
	s_waitcnt vmcnt(8)
	s_waitcnt lgkmcnt(0)
	s_barrier
	s_setprio 1
	s_waitcnt lgkmcnt(0)
	v_mfma_f32_16x16x32_bf16 v[60:63], v[124:127], v[160:163], 0
	v_mfma_f32_16x16x32_bf16 v[56:59], v[136:139], v[160:163], 0
	v_mfma_f32_16x16x32_bf16 v[44:47], v[124:127], v[168:171], 0
	v_mfma_f32_16x16x32_bf16 v[40:43], v[136:139], v[168:171], 0
	v_mfma_f32_16x16x32_bf16 v[28:31], v[124:127], v[176:179], 0
	v_mfma_f32_16x16x32_bf16 v[24:27], v[136:139], v[176:179], 0
	v_mfma_f32_16x16x32_bf16 v[12:15], v[124:127], v[198:201], 0
	v_mfma_f32_16x16x32_bf16 v[8:11], v[136:139], v[198:201], 0
	v_mfma_f32_16x16x32_bf16 v[60:63], v[132:135], v[164:167], v[60:63]
	v_mfma_f32_16x16x32_bf16 v[56:59], v[140:143], v[164:167], v[56:59]
	v_mfma_f32_16x16x32_bf16 v[44:47], v[132:135], v[172:175], v[44:47]
	v_mfma_f32_16x16x32_bf16 v[40:43], v[140:143], v[172:175], v[40:43]
	v_mfma_f32_16x16x32_bf16 v[28:31], v[132:135], v[180:183], v[28:31]
	v_mfma_f32_16x16x32_bf16 v[24:27], v[140:143], v[180:183], v[24:27]
	v_mfma_f32_16x16x32_bf16 v[12:15], v[132:135], v[202:205], v[12:15]
	v_mfma_f32_16x16x32_bf16 v[8:11], v[140:143], v[202:205], v[8:11]
	s_setprio 0
	s_setprio 1
	v_mfma_f32_16x16x32_bf16 v[52:55], v[144:147], v[160:163], 0
	v_mfma_f32_16x16x32_bf16 v[48:51], v[152:155], v[160:163], 0
	v_mfma_f32_16x16x32_bf16 v[36:39], v[144:147], v[168:171], 0
	v_mfma_f32_16x16x32_bf16 v[32:35], v[152:155], v[168:171], 0
	v_mfma_f32_16x16x32_bf16 v[20:23], v[144:147], v[176:179], 0
	v_mfma_f32_16x16x32_bf16 v[16:19], v[152:155], v[176:179], 0
	v_mfma_f32_16x16x32_bf16 v[4:7], v[144:147], v[198:201], 0
	v_mfma_f32_16x16x32_bf16 v[0:3], v[152:155], v[198:201], 0
	v_mfma_f32_16x16x32_bf16 v[52:55], v[148:151], v[164:167], v[52:55]
	v_mfma_f32_16x16x32_bf16 v[48:51], v[156:159], v[164:167], v[48:51]
	v_mfma_f32_16x16x32_bf16 v[36:39], v[148:151], v[172:175], v[36:39]
	v_mfma_f32_16x16x32_bf16 v[32:35], v[156:159], v[172:175], v[32:35]
	v_mfma_f32_16x16x32_bf16 v[20:23], v[148:151], v[180:183], v[20:23]
	v_mfma_f32_16x16x32_bf16 v[16:19], v[156:159], v[180:183], v[16:19]
	v_mfma_f32_16x16x32_bf16 v[4:7], v[148:151], v[202:205], v[4:7]
	v_mfma_f32_16x16x32_bf16 v[0:3], v[156:159], v[202:205], v[0:3]
	s_setprio 0
	s_barrier
; #define PG8_STAGE(bufoff, gbase, voff) do { _Pragma("unroll") for (int _i = 0; _i < 2; ++_i) \
;         __builtin_amdgcn_global_load_lds((const unsigned*)((const char*)(gbase) + (voff)[_i]), (PG8_LAS unsigned*)(lds + (bufoff) + ldsw + _i * 8192), 16, 0, 0); } while (0)
; #define PG8_LDA(dst, b, h) do { _Pragma("unroll") for (int m = 0; m < 4; ++m) _Pragma("unroll") for (int k = 0; k < 2; ++k) dst[m][k] = *(const PG8_LAS bf16x8*)(lds + PG8_SA(b, h) + aoff + m * 2048 + k * 1024); } while (0)
; #define PG8_LDB(dst, b, h) do { _Pragma("unroll") for (int n = 0; n < 2; ++n) _Pragma("unroll") for (int k = 0; k < 2; ++k) dst[n][k] = *(const PG8_LAS bf16x8*)(lds + PG8_SB(b, h) + boff + n * 2048 + k * 1024); } while (0)
; #define PG8_MMA(ai, bj, At, Bt) do { __builtin_amdgcn_s_setprio(1); _Pragma("unroll") for (int m = 0; m < 4; ++m) _Pragma("unroll") for (int n = 0; n < 2; ++n) _Pragma("unroll") for (int k = 0; k < 2; ++k) \
;         acc[ai][bj][m][n] = __builtin_amdgcn_mfma_f32_16x16x32_bf16(Bt[n][k], At[m][k], acc[ai][bj][m][n], 0, 0, 0); __builtin_amdgcn_s_setprio(0); } while (0)
; #define PG8_WAIT_V(n) asm volatile("s_waitcnt vmcnt(" #n ")" ::: "memory")
; #define PG8_WAIT_L(n) asm volatile("s_waitcnt lgkmcnt(" #n ")" ::: "memory")
; #define PG8_BAR __builtin_amdgcn_s_barrier()
; #define PG8_SCHED __builtin_amdgcn_sched_barrier(0)
; template <class Epi, class Sched, bool ALIGN_EPI = false, bool SP2 = false>
; __device__ __forceinline__ void gemm_phase(PG8_LAS unsigned char* lds, const Gemm g, const Sched& S, const Epi& E) {
;     ...
;             PG8_LDB(B0, 1, 0); PG8_LDB(B1, 1, 1); PG8_SCHED; PG8_LDA(At, 1, 0); PG8_STAGE(PG8_SA(0, 1), a2 + hstep, voffA);
;             PG8_WAIT_V(8); PG8_WAIT_L(0); PG8_BAR; PG8_MMA(0, 0, At, B0); PG8_MMA(0, 1, At, B1); PG8_BAR; PG8_SCHED;
	s_add_i32 s63, 0, 0x18000
	s_add_i32 s64, 0, 0x1c000
	v_add_u32_e32 v140, s63, v232
	v_add_u32_e32 v156, s64, v232
	ds_read_b128 v[124:127], v140
	ds_read_b128 v[132:135], v140 offset:1024
	ds_read_b128 v[136:139], v140 offset:2048
	ds_read_b128 v[140:143], v140 offset:3072
	ds_read_b128 v[144:147], v156
	ds_read_b128 v[148:151], v156 offset:1024
	ds_read_b128 v[152:155], v156 offset:2048
	ds_read_b128 v[156:159], v156 offset:3072
	s_add_u32 s52, s52, 0x40000
	s_addc_u32 s53, s53, 0
	s_mov_b32 m0, s28
	v_lshl_add_u64 v[214:215], s[52:53], 0, v[184:185]
	ds_read_b128 v[160:163], v236 offset:32768
	ds_read_b128 v[164:167], v236 offset:33792
	ds_read_b128 v[168:171], v236 offset:34816
	ds_read_b128 v[172:175], v236 offset:35840
	ds_read_b128 v[176:179], v236 offset:36864
	ds_read_b128 v[180:183], v236 offset:37888
	ds_read_b128 v[198:201], v236 offset:38912
	ds_read_b128 v[202:205], v236 offset:39936
	global_load_lds_dwordx4 v[214:215], off
	v_lshl_add_u64 v[214:215], s[52:53], 0, v[188:189]
	s_mov_b32 m0, s29
	s_nop 0
	global_load_lds_dwordx4 v[214:215], off
	s_waitcnt vmcnt(8)
	s_waitcnt lgkmcnt(0)
	s_barrier
	s_setprio 1
	s_waitcnt lgkmcnt(0)
	v_mfma_f32_16x16x32_bf16 v[128:131], v[124:127], v[160:163], v[128:131]
	v_mfma_f32_16x16x32_bf16 v[120:123], v[136:139], v[160:163], v[120:123]
	v_mfma_f32_16x16x32_bf16 v[108:111], v[124:127], v[168:171], v[108:111]
	v_mfma_f32_16x16x32_bf16 v[104:107], v[136:139], v[168:171], v[104:107]
	v_mfma_f32_16x16x32_bf16 v[92:95], v[124:127], v[176:179], v[92:95]
	v_mfma_f32_16x16x32_bf16 v[88:91], v[136:139], v[176:179], v[88:91]
	v_mfma_f32_16x16x32_bf16 v[76:79], v[124:127], v[198:201], v[76:79]
	v_mfma_f32_16x16x32_bf16 v[72:75], v[136:139], v[198:201], v[72:75]
	v_mfma_f32_16x16x32_bf16 v[128:131], v[132:135], v[164:167], v[128:131]
	v_mfma_f32_16x16x32_bf16 v[120:123], v[140:143], v[164:167], v[120:123]
	v_mfma_f32_16x16x32_bf16 v[108:111], v[132:135], v[172:175], v[108:111]
	v_mfma_f32_16x16x32_bf16 v[104:107], v[140:143], v[172:175], v[104:107]
	v_mfma_f32_16x16x32_bf16 v[92:95], v[132:135], v[180:183], v[92:95]
	v_mfma_f32_16x16x32_bf16 v[88:91], v[140:143], v[180:183], v[88:91]
	v_mfma_f32_16x16x32_bf16 v[76:79], v[132:135], v[202:205], v[76:79]
	v_mfma_f32_16x16x32_bf16 v[72:75], v[140:143], v[202:205], v[72:75]
	s_setprio 0
	s_setprio 1
	v_mfma_f32_16x16x32_bf16 v[116:119], v[144:147], v[160:163], v[116:119]
	v_mfma_f32_16x16x32_bf16 v[112:115], v[152:155], v[160:163], v[112:115]
	v_mfma_f32_16x16x32_bf16 v[100:103], v[144:147], v[168:171], v[100:103]
	v_mfma_f32_16x16x32_bf16 v[96:99], v[152:155], v[168:171], v[96:99]
	v_mfma_f32_16x16x32_bf16 v[84:87], v[144:147], v[176:179], v[84:87]
	v_mfma_f32_16x16x32_bf16 v[80:83], v[152:155], v[176:179], v[80:83]
	v_mfma_f32_16x16x32_bf16 v[68:71], v[144:147], v[198:201], v[68:71]
	v_mfma_f32_16x16x32_bf16 v[64:67], v[152:155], v[198:201], v[64:67]
	v_mfma_f32_16x16x32_bf16 v[116:119], v[148:151], v[164:167], v[116:119]
	v_mfma_f32_16x16x32_bf16 v[112:115], v[156:159], v[164:167], v[112:115]
	v_mfma_f32_16x16x32_bf16 v[100:103], v[148:151], v[172:175], v[100:103]
	v_mfma_f32_16x16x32_bf16 v[96:99], v[156:159], v[172:175], v[96:99]
	v_mfma_f32_16x16x32_bf16 v[84:87], v[148:151], v[180:183], v[84:87]
	v_mfma_f32_16x16x32_bf16 v[80:83], v[156:159], v[180:183], v[80:83]
	v_mfma_f32_16x16x32_bf16 v[68:71], v[148:151], v[202:205], v[68:71]
	v_mfma_f32_16x16x32_bf16 v[64:67], v[156:159], v[202:205], v[64:67]
	s_setprio 0
	s_barrier
; #define PG8_STAGE(bufoff, gbase, voff) do { _Pragma("unroll") for (int _i = 0; _i < 2; ++_i) \
;         __builtin_amdgcn_global_load_lds((const unsigned*)((const char*)(gbase) + (voff)[_i]), (PG8_LAS unsigned*)(lds + (bufoff) + ldsw + _i * 8192), 16, 0, 0); } while (0)
; #define PG8_LDA(dst, b, h) do { _Pragma("unroll") for (int m = 0; m < 4; ++m) _Pragma("unroll") for (int k = 0; k < 2; ++k) dst[m][k] = *(const PG8_LAS bf16x8*)(lds + PG8_SA(b, h) + aoff + m * 2048 + k * 1024); } while (0)
; #define PG8_MMA(ai, bj, At, Bt) do { __builtin_amdgcn_s_setprio(1); _Pragma("unroll") for (int m = 0; m < 4; ++m) _Pragma("unroll") for (int n = 0; n < 2; ++n) _Pragma("unroll") for (int k = 0; k < 2; ++k) \
;         acc[ai][bj][m][n] = __builtin_amdgcn_mfma_f32_16x16x32_bf16(Bt[n][k], At[m][k], acc[ai][bj][m][n], 0, 0, 0); __builtin_amdgcn_s_setprio(0); } while (0)
; #define PG8_WAIT_V(n) asm volatile("s_waitcnt vmcnt(" #n ")" ::: "memory")
; #define PG8_WAIT_L(n) asm volatile("s_waitcnt lgkmcnt(" #n ")" ::: "memory")
; #define PG8_BAR __builtin_amdgcn_s_barrier()
; #define PG8_SCHED __builtin_amdgcn_sched_barrier(0)
; template <class Epi, class Sched, bool ALIGN_EPI = false, bool SP2 = false>
; __device__ __forceinline__ void gemm_phase(PG8_LAS unsigned char* lds, const Gemm g, const Sched& S, const Epi& E) {
;     ...
;             PG8_LDA(At, 1, 1); PG8_STAGE(PG8_SB(1, 0), b3, voffB); PG8_STAGE(PG8_SB(1, 1), b3 + hstep, voffB); PG8_STAGE(PG8_SA(1, 0), a3, voffA);
;             PG8_WAIT_V(8); PG8_WAIT_L(0); PG8_BAR; PG8_MMA(1, 0, At, B0); PG8_MMA(1, 1, At, B1); PG8_BAR; PG8_SCHED;
	s_add_i32 s52, s63, s25
	v_lshl_add_u64 v[206:207], v[206:207], 0, s[18:19]
	s_mov_b32 m0, s52
	ds_read_b128 v[160:163], v236 offset:49152
	ds_read_b128 v[164:167], v236 offset:50176
	ds_read_b128 v[168:171], v236 offset:51200
	ds_read_b128 v[172:175], v236 offset:52224
	ds_read_b128 v[176:179], v236 offset:53248
	ds_read_b128 v[180:183], v236 offset:54272
	ds_read_b128 v[198:201], v236 offset:55296
	ds_read_b128 v[202:205], v236 offset:56320
	global_load_lds_dwordx4 v[206:207], off
	s_add_i32 m0, s52, 0x2000
	s_add_u32 s50, s50, 0x40080
	v_lshl_add_u64 v[206:207], v[208:209], 0, s[18:19]
	s_addc_u32 s51, s51, 0
	s_add_i32 s52, s64, s25
	global_load_lds_dwordx4 v[206:207], off
	v_lshl_add_u64 v[206:207], s[50:51], 0, v[186:187]
	s_mov_b32 m0, s52
	s_nop 0
	global_load_lds_dwordx4 v[206:207], off
	v_lshl_add_u64 v[206:207], s[50:51], 0, v[190:191]
	s_add_i32 m0, s52, 0x2000
	s_nop 0
	global_load_lds_dwordx4 v[206:207], off
	v_lshl_add_u64 v[206:207], v[210:211], 0, s[18:19]
	s_mov_b32 m0, s31
	s_nop 0
	global_load_lds_dwordx4 v[206:207], off
	v_lshl_add_u64 v[206:207], v[212:213], 0, s[18:19]
	s_mov_b32 m0, s33
	s_nop 0
	global_load_lds_dwordx4 v[206:207], off
	s_waitcnt vmcnt(8)
	s_waitcnt lgkmcnt(0)
	s_barrier
	s_setprio 1
	s_waitcnt lgkmcnt(0)
	v_mfma_f32_16x16x32_bf16 v[60:63], v[124:127], v[160:163], v[60:63]
	v_mfma_f32_16x16x32_bf16 v[56:59], v[136:139], v[160:163], v[56:59]
	v_mfma_f32_16x16x32_bf16 v[44:47], v[124:127], v[168:171], v[44:47]
	v_mfma_f32_16x16x32_bf16 v[40:43], v[136:139], v[168:171], v[40:43]
	v_mfma_f32_16x16x32_bf16 v[28:31], v[124:127], v[176:179], v[28:31]
	v_mfma_f32_16x16x32_bf16 v[24:27], v[136:139], v[176:179], v[24:27]
	v_mfma_f32_16x16x32_bf16 v[12:15], v[124:127], v[198:201], v[12:15]
	v_mfma_f32_16x16x32_bf16 v[8:11], v[136:139], v[198:201], v[8:11]
	v_mfma_f32_16x16x32_bf16 v[60:63], v[132:135], v[164:167], v[60:63]
	v_mfma_f32_16x16x32_bf16 v[56:59], v[140:143], v[164:167], v[56:59]
	v_mfma_f32_16x16x32_bf16 v[44:47], v[132:135], v[172:175], v[44:47]
	v_mfma_f32_16x16x32_bf16 v[40:43], v[140:143], v[172:175], v[40:43]
	v_mfma_f32_16x16x32_bf16 v[28:31], v[132:135], v[180:183], v[28:31]
	v_mfma_f32_16x16x32_bf16 v[24:27], v[140:143], v[180:183], v[24:27]
	v_mfma_f32_16x16x32_bf16 v[12:15], v[132:135], v[202:205], v[12:15]
	v_mfma_f32_16x16x32_bf16 v[8:11], v[140:143], v[202:205], v[8:11]
	s_setprio 0
	s_setprio 1
	v_mfma_f32_16x16x32_bf16 v[52:55], v[144:147], v[160:163], v[52:55]
	v_mfma_f32_16x16x32_bf16 v[48:51], v[152:155], v[160:163], v[48:51]
	v_mfma_f32_16x16x32_bf16 v[36:39], v[144:147], v[168:171], v[36:39]
	v_mfma_f32_16x16x32_bf16 v[32:35], v[152:155], v[168:171], v[32:35]
	v_mfma_f32_16x16x32_bf16 v[20:23], v[144:147], v[176:179], v[20:23]
	v_mfma_f32_16x16x32_bf16 v[16:19], v[152:155], v[176:179], v[16:19]
	v_mfma_f32_16x16x32_bf16 v[4:7], v[144:147], v[198:201], v[4:7]
	v_mfma_f32_16x16x32_bf16 v[0:3], v[152:155], v[198:201], v[0:3]
	v_mfma_f32_16x16x32_bf16 v[52:55], v[148:151], v[164:167], v[52:55]
	v_mfma_f32_16x16x32_bf16 v[48:51], v[156:159], v[164:167], v[48:51]
	v_mfma_f32_16x16x32_bf16 v[36:39], v[148:151], v[172:175], v[36:39]
	v_mfma_f32_16x16x32_bf16 v[32:35], v[156:159], v[172:175], v[32:35]
	v_mfma_f32_16x16x32_bf16 v[20:23], v[148:151], v[180:183], v[20:23]
	v_mfma_f32_16x16x32_bf16 v[16:19], v[156:159], v[180:183], v[16:19]
	v_mfma_f32_16x16x32_bf16 v[4:7], v[148:151], v[202:205], v[4:7]
	v_mfma_f32_16x16x32_bf16 v[0:3], v[156:159], v[202:205], v[0:3]
	s_setprio 0
	s_barrier
	s_add_i32 s62, s62, 2
	s_add_u32 s48, s48, 0x100
	s_addc_u32 s49, s49, 0
	s_add_u32 s60, s60, 0x100
	s_addc_u32 s61, s61, 0
	s_cmp_gt_u32 s62, 13

; #define PG8_STAGE(bufoff, gbase, voff) do { _Pragma("unroll") for (int _i = 0; _i < 2; ++_i) \
;         __builtin_amdgcn_global_load_lds((const unsigned*)((const char*)(gbase) + (voff)[_i]), (PG8_LAS unsigned*)(lds + (bufoff) + ldsw + _i * 8192), 16, 0, 0); } while (0)
; #define PG8_LDA(dst, b, h) do { _Pragma("unroll") for (int m = 0; m < 4; ++m) _Pragma("unroll") for (int k = 0; k < 2; ++k) dst[m][k] = *(const PG8_LAS bf16x8*)(lds + PG8_SA(b, h) + aoff + m * 2048 + k * 1024); } while (0)
; #define PG8_LDB(dst, b, h) do { _Pragma("unroll") for (int n = 0; n < 2; ++n) _Pragma("unroll") for (int k = 0; k < 2; ++k) dst[n][k] = *(const PG8_LAS bf16x8*)(lds + PG8_SB(b, h) + boff + n * 2048 + k * 1024); } while (0)
; #define PG8_SCHED __builtin_amdgcn_sched_barrier(0)
;     __host__ __device__ bool next(int i, Unit& u) const {
;         if (i >= nI) return false;
;         const long L = (long)(rev ? nI - 1 - i : i) * G + c; if (L >= nwg) return false;
;         int wgid = (int)L; { const int q = nwg / NXCD, r = nwg % NXCD, xcd = wgid % NXCD, off = wgid / NXCD; wgid = (xcd < r ? xcd * (q + 1) : r * (q + 1) + (xcd - r) * q) + off; }
;         const int nig = WGM * nN, gid = wgid / nig, fm = gid * WGM, gsz = (nM - fm) < WGM ? (nM - fm) : WGM;
;         u.pm = fm + ((wgid % nig) % gsz); u.pn = (wgid % nig) / gsz; return true;
;     }
; template <class Epi, class Sched, bool ALIGN_EPI = false, bool SP2 = false>
; __device__ __forceinline__ void gemm_phase(PG8_LAS unsigned char* lds, const Gemm g, const Sched& S, const Epi& E) {
;     ...
;             PG8_LDB(B0, 0, 0); PG8_LDB(B1, 0, 1); PG8_SCHED; PG8_LDA(At, 0, 0); PG8_STAGE(PG8_SA(1, 1), a1 + hstep, voffA);
.LBB0_478:
	ds_read_b128 v[144:147], v161
	ds_read_b128 v[170:173], v161 offset:1024
	ds_read_b128 v[178:181], v161 offset:2048
	ds_read_b128 v[182:185], v161 offset:3072
	ds_read_b128 v[186:189], v165
	ds_read_b128 v[190:193], v165 offset:1024
	ds_read_b128 v[194:197], v165 offset:2048
	ds_read_b128 v[198:201], v165 offset:3072
	ds_read_b128 v[202:205], v169
	ds_read_b128 v[206:209], v169 offset:1024
	ds_read_b128 v[210:213], v169 offset:2048
	ds_read_b128 v[214:217], v169 offset:3072
	ds_read_b128 v[218:221], v169 offset:4096
	ds_read_b128 v[222:225], v169 offset:5120
	ds_read_b128 v[226:229], v169 offset:6144
	ds_read_b128 v[232:235], v169 offset:7168
	s_add_i32 s33, s33, 1
	s_cmp_ge_i32 s33, s22
	s_mov_b64 s[20:21], 0
	s_cbranch_scc1 .LBB0_481
	s_mul_i32 s17, s33, s41
	s_mul_hi_u32 s19, s33, s50
	s_add_i32 s19, s19, s17
	s_mul_i32 s17, s33, s50
	s_add_u32 s36, s17, s2
	s_addc_u32 s37, s19, s26
	v_cmp_gt_i64_e32 vcc, s[36:37], v[142:143]
	s_cbranch_vccnz .LBB0_481
	s_ashr_i32 s16, s36, 31
	s_lshr_b32 s16, s16, 29
	s_add_i32 s16, s36, s16
	s_ashr_i32 s17, s16, 3
	s_and_b32 s16, s16, -8
	s_sub_i32 s16, s36, s16
	s_cmp_lt_i32 s16, 0
	s_cselect_b32 s18, s27, 0x580
	s_mul_i32 s16, s16, s18
	s_add_i32 s16, s16, s17
	s_mul_hi_i32 s17, s16, 0x2e8ba2e9
	s_lshr_b32 s18, s17, 31
	s_ashr_i32 s17, s17, 5
	s_add_i32 s17, s17, s18
	s_lshl_b32 s18, s17, 3
	s_sub_i32 s19, 0x200, s18
	s_min_i32 s19, s19, 8
	s_abs_i32 s20, s19
	v_cvt_f32_u32_e32 v0, s20
	s_sub_i32 s36, 0, s20
	s_mulk_i32 s17, 0xb0
	s_sub_i32 s17, s16, s17
	v_rcp_iflag_f32_e32 v0, v0
	s_abs_i32 s16, s17
	s_xor_b32 s21, s17, s19
	s_ashr_i32 s21, s21, 31
	v_mul_f32_e32 v0, 0x4f7ffffe, v0
	v_cvt_u32_f32_e32 v0, v0
	s_nop 0
	v_readfirstlane_b32 s37, v0
	s_mul_i32 s36, s36, s37
	s_mul_hi_u32 s36, s37, s36
	s_add_i32 s37, s37, s36
	s_mul_hi_u32 s36, s16, s37
	s_mul_i32 s37, s36, s20
	s_sub_i32 s16, s16, s37
	s_add_i32 s38, s36, 1
	s_sub_i32 s37, s16, s20
	s_cmp_ge_u32 s16, s20
	s_cselect_b32 s36, s38, s36
	s_cselect_b32 s16, s37, s16
	s_add_i32 s37, s36, 1
	s_cmp_ge_u32 s16, s20
	s_cselect_b32 s16, s37, s36
	s_xor_b32 s16, s16, s21
	s_sub_i32 s16, s16, s21
	s_mul_i32 s19, s16, s19
	s_sub_i32 s17, s17, s19
	s_add_i32 s18, s18, s17
	s_mov_b64 s[20:21], -1
; #define PG8_STAGE(bufoff, gbase, voff) do { _Pragma("unroll") for (int _i = 0; _i < 2; ++_i) \
;         __builtin_amdgcn_global_load_lds((const unsigned*)((const char*)(gbase) + (voff)[_i]), (PG8_LAS unsigned*)(lds + (bufoff) + ldsw + _i * 8192), 16, 0, 0); } while (0)
; #define PG8_LDA(dst, b, h) do { _Pragma("unroll") for (int m = 0; m < 4; ++m) _Pragma("unroll") for (int k = 0; k < 2; ++k) dst[m][k] = *(const PG8_LAS bf16x8*)(lds + PG8_SA(b, h) + aoff + m * 2048 + k * 1024); } while (0)
; #define PG8_LDB(dst, b, h) do { _Pragma("unroll") for (int n = 0; n < 2; ++n) _Pragma("unroll") for (int k = 0; k < 2; ++k) dst[n][k] = *(const PG8_LAS bf16x8*)(lds + PG8_SB(b, h) + boff + n * 2048 + k * 1024); } while (0)
; #define PG8_WAIT_V(n) asm volatile("s_waitcnt vmcnt(" #n ")" ::: "memory")
; #define PG8_WAIT_L(n) asm volatile("s_waitcnt lgkmcnt(" #n ")" ::: "memory")
; #define PG8_BAR __builtin_amdgcn_s_barrier()
; #define PG8_SCHED __builtin_amdgcn_sched_barrier(0)
; template <class Epi, class Sched, bool ALIGN_EPI = false, bool SP2 = false>
; __device__ __forceinline__ void gemm_phase(PG8_LAS unsigned char* lds, const Gemm g, const Sched& S, const Epi& E) {
;     ...
;         const char* nA = has_next ? (const char*)g.A + (size_t)nxt.pm * tstep : cA; const char* nB = has_next ? (const char*)g.Bt + (size_t)nxt.pn * tstep : cB;
;         for (int t = 0; t < nt; t += 2) {
;             const bool last = (t == nt - 2);
;             const char* a1 = cA + (size_t)(t + 1) * kstep;
;             const char* a2 = last ? nA : cA + (size_t)(t + 2) * kstep; const char* b2 = last ? nB : cB + (size_t)(t + 2) * kstep;
;             const char* a3 = a2 + kstep; const char* b3 = b2 + kstep;
;             if (last && has_next) S.a_ready(nxt);
;             if constexpr (SP2) {
;             PG8_LDB(B0, 0, 0); PG8_LDB(B1, 0, 1); PG8_SCHED; PG8_LDA(At, 0, 0); PG8_STAGE(PG8_SA(1, 1), a1 + hstep, voffA);
;             PG8_WAIT_V(8); PG8_WAIT_L(0); PG8_BAR; PG8_MMA(0, 0, At, B0); PG8_MMA(0, 1, At, B1); PG8_BAR; PG8_SCHED;
;             PG8_LDA(At, 0, 1); PG8_STAGE(PG8_SB(0, 0), b2, voffB); PG8_STAGE(PG8_SB(0, 1), b2 + hstep, voffB); PG8_STAGE(PG8_SA(0, 0), a2, voffA);
;             PG8_WAIT_V(8); PG8_WAIT_L(0); PG8_BAR; PG8_MMA(1, 0, At, B0); PG8_MMA(1, 1, At, B1); PG8_BAR; PG8_SCHED;
.LBB0_481:
	s_ashr_i32 s19, s18, 31
	s_lshl_b64 s[36:37], s[18:19], 19
	s_add_u32 s36, s70, s36
	s_addc_u32 s37, s71, s37
	s_and_b64 s[38:39], s[20:21], exec
	s_cselect_b32 s19, s37, s43
	s_cselect_b32 s55, s36, s42
	s_ashr_i32 s17, s16, 31
	s_lshl_b64 s[38:39], s[16:17], 19
	s_add_u32 s38, s23, s38
	s_addc_u32 s39, s24, s39
	s_and_b64 s[46:47], s[20:21], exec
	s_cselect_b32 s17, s39, s45
	s_cselect_b32 s56, s38, s44
	s_add_u32 s42, s42, 0x40080
	s_addc_u32 s43, s43, 0
	s_add_u32 s57, s44, 0x100
	s_addc_u32 s58, s45, 0
	s_mov_b32 s59, -2
	s_add_u32 s44, s42, 0xfffc0080
	s_addc_u32 s45, s43, -1
	s_cmp_eq_u32 s59, 12
	s_cselect_b32 s47, s19, s45
	s_cselect_b32 s46, s55, s44
	s_cselect_b32 s45, s17, s58
	s_cselect_b32 s44, s56, s57
	v_lshl_add_u64 v[150:151], s[42:43], 0, v[138:139]
	s_add_i32 m0, s28, 0xc000
	global_load_lds_dwordx4 v[150:151], off
	v_lshl_add_u64 v[150:151], s[42:43], 0, v[140:141]
	s_add_i32 m0, s28, 0xe000
	s_nop 0
	global_load_lds_dwordx4 v[150:151], off
	s_waitcnt vmcnt(8)
	s_waitcnt lgkmcnt(0)
	s_barrier
	s_setprio 1
	s_waitcnt lgkmcnt(0)
	v_mfma_f32_16x16x32_bf16 v[124:127], v[144:147], v[202:205], 0
	v_mfma_f32_16x16x32_bf16 v[116:119], v[178:181], v[202:205], 0
	v_mfma_f32_16x16x32_bf16 v[108:111], v[144:147], v[210:213], 0
	v_mfma_f32_16x16x32_bf16 v[100:103], v[178:181], v[210:213], 0
	v_mfma_f32_16x16x32_bf16 v[92:95], v[144:147], v[218:221], 0
	v_mfma_f32_16x16x32_bf16 v[84:87], v[178:181], v[218:221], 0
	v_mfma_f32_16x16x32_bf16 v[76:79], v[144:147], v[226:229], 0
	v_mfma_f32_16x16x32_bf16 v[68:71], v[178:181], v[226:229], 0
	v_mfma_f32_16x16x32_bf16 v[124:127], v[170:173], v[206:209], v[124:127]
	v_mfma_f32_16x16x32_bf16 v[116:119], v[182:185], v[206:209], v[116:119]
	v_mfma_f32_16x16x32_bf16 v[108:111], v[170:173], v[214:217], v[108:111]
	v_mfma_f32_16x16x32_bf16 v[100:103], v[182:185], v[214:217], v[100:103]
	v_mfma_f32_16x16x32_bf16 v[92:95], v[170:173], v[222:225], v[92:95]
	v_mfma_f32_16x16x32_bf16 v[84:87], v[182:185], v[222:225], v[84:87]
	v_mfma_f32_16x16x32_bf16 v[76:79], v[170:173], v[232:235], v[76:79]
	v_mfma_f32_16x16x32_bf16 v[68:71], v[182:185], v[232:235], v[68:71]
	s_setprio 0
	s_setprio 1
	v_mfma_f32_16x16x32_bf16 v[120:123], v[186:189], v[202:205], 0
	v_mfma_f32_16x16x32_bf16 v[112:115], v[194:197], v[202:205], 0
	v_mfma_f32_16x16x32_bf16 v[104:107], v[186:189], v[210:213], 0
	v_mfma_f32_16x16x32_bf16 v[96:99], v[194:197], v[210:213], 0
	v_mfma_f32_16x16x32_bf16 v[88:91], v[186:189], v[218:221], 0
	v_mfma_f32_16x16x32_bf16 v[80:83], v[194:197], v[218:221], 0
	v_mfma_f32_16x16x32_bf16 v[72:75], v[186:189], v[226:229], 0
	v_mfma_f32_16x16x32_bf16 v[64:67], v[194:197], v[226:229], 0
	v_mfma_f32_16x16x32_bf16 v[120:123], v[190:193], v[206:209], v[120:123]
	v_mfma_f32_16x16x32_bf16 v[112:115], v[198:201], v[206:209], v[112:115]
	v_mfma_f32_16x16x32_bf16 v[104:107], v[190:193], v[214:217], v[104:107]
	v_mfma_f32_16x16x32_bf16 v[96:99], v[198:201], v[214:217], v[96:99]
	v_mfma_f32_16x16x32_bf16 v[88:91], v[190:193], v[222:225], v[88:91]
	v_mfma_f32_16x16x32_bf16 v[80:83], v[198:201], v[222:225], v[80:83]
	v_mfma_f32_16x16x32_bf16 v[72:75], v[190:193], v[232:235], v[72:75]
	v_mfma_f32_16x16x32_bf16 v[64:67], v[198:201], v[232:235], v[64:67]
	s_setprio 0
	s_barrier
	s_add_i32 s60, s51, s25
	v_lshl_add_u64 v[150:151], s[44:45], 0, v[130:131]
	s_mov_b32 m0, s60
	ds_read_b128 v[202:205], v169 offset:16384
	ds_read_b128 v[206:209], v169 offset:17408
	ds_read_b128 v[210:213], v169 offset:18432
	ds_read_b128 v[214:217], v169 offset:19456
	ds_read_b128 v[218:221], v169 offset:20480
	ds_read_b128 v[222:225], v169 offset:21504
	ds_read_b128 v[226:229], v169 offset:22528
	ds_read_b128 v[232:235], v169 offset:23552
	global_load_lds_dwordx4 v[150:151], off
	s_add_i32 m0, s60, 0x2000
	s_add_u32 s60, s44, 0x40000
	v_lshl_add_u64 v[154:155], s[44:45], 0, v[134:135]
	s_addc_u32 s61, s45, 0
	s_add_i32 s62, s52, s25
	global_load_lds_dwordx4 v[154:155], off
	v_lshl_add_u64 v[158:159], s[60:61], 0, v[130:131]
	s_mov_b32 m0, s62
	v_lshl_add_u64 v[162:163], s[46:47], 0, v[132:133]
	global_load_lds_dwordx4 v[158:159], off
	v_lshl_add_u64 v[158:159], s[60:61], 0, v[134:135]
	s_add_i32 m0, s62, 0x2000
	s_nop 0
	global_load_lds_dwordx4 v[158:159], off
	v_lshl_add_u64 v[158:159], s[46:47], 0, v[128:129]
	s_mov_b32 m0, s28
	s_nop 0
	global_load_lds_dwordx4 v[158:159], off
	s_mov_b32 m0, s29
	s_nop 0
	global_load_lds_dwordx4 v[162:163], off
	s_cmp_lg_i32 s59, -2
	s_cbranch_scc1 .Lrsa_a_pl
	v_lshrrev_b32_e32 v250, 6, v230
	v_lshlrev_b32_e32 v250, 11, v250
	v_and_b32_e32 v251, 63, v230
	v_lshl_or_b32 v250, v251, 4, v250
	v_lshl_add_u32 v250, s40, 14, v250
	v_readfirstlane_b32 s98, v230
	s_lshr_b32 s98, s98, 6
	s_lshl_b32 s98, s98, 11
	s_add_i32 m0, s98, 0x20000
	s_add_u32 s100, s70, 0x3f000000
	s_addc_u32 s101, s71, 0
	global_load_lds_dwordx4 v250, s[100:101]
	global_load_lds_dwordx4 v250, s[100:101] offset:1024
	s_waitcnt vmcnt(10)
	s_branch .Lrsa_b_pl

; #define PG8_STAGE(bufoff, gbase, voff) do { _Pragma("unroll") for (int _i = 0; _i < 2; ++_i) \
;         __builtin_amdgcn_global_load_lds((const unsigned*)((const char*)(gbase) + (voff)[_i]), (PG8_LAS unsigned*)(lds + (bufoff) + ldsw + _i * 8192), 16, 0, 0); } while (0)
; #define PG8_LDA(dst, b, h) do { _Pragma("unroll") for (int m = 0; m < 4; ++m) _Pragma("unroll") for (int k = 0; k < 2; ++k) dst[m][k] = *(const PG8_LAS bf16x8*)(lds + PG8_SA(b, h) + aoff + m * 2048 + k * 1024); } while (0)
; #define PG8_LDB(dst, b, h) do { _Pragma("unroll") for (int n = 0; n < 2; ++n) _Pragma("unroll") for (int k = 0; k < 2; ++k) dst[n][k] = *(const PG8_LAS bf16x8*)(lds + PG8_SB(b, h) + boff + n * 2048 + k * 1024); } while (0)
; #define PG8_SCHED __builtin_amdgcn_sched_barrier(0)
;     __host__ __device__ bool next(int i, Unit& u) const {
;         if (i >= nI) return false;
;         const long L = (long)(rev ? nI - 1 - i : i) * G + c; if (L >= nwg) return false;
;         int wgid = (int)L; { const int q = nwg / NXCD, r = nwg % NXCD, xcd = wgid % NXCD, off = wgid / NXCD; wgid = (xcd < r ? xcd * (q + 1) : r * (q + 1) + (xcd - r) * q) + off; }
;         const int nig = WGM * nN, gid = wgid / nig, fm = gid * WGM, gsz = (nM - fm) < WGM ? (nM - fm) : WGM;
;         u.pm = fm + ((wgid % nig) % gsz); u.pn = (wgid % nig) / gsz; return true;
;     }
; template <class Epi, class Sched, bool ALIGN_EPI = false, bool SP2 = false>
; __device__ __forceinline__ void gemm_phase(PG8_LAS unsigned char* lds, const Gemm g, const Sched& S, const Epi& E) {
;     ...
;             PG8_LDB(B0, 0, 0); PG8_LDB(B1, 0, 1); PG8_SCHED; PG8_LDA(At, 0, 0); PG8_STAGE(PG8_SA(1, 1), a1 + hstep, voffA);
.LBB0_558:
	ds_read_b128 v[124:127], v234
	ds_read_b128 v[132:135], v234 offset:1024
	ds_read_b128 v[136:139], v234 offset:2048
	ds_read_b128 v[140:143], v234 offset:3072
	ds_read_b128 v[144:147], v235
	ds_read_b128 v[148:151], v235 offset:1024
	ds_read_b128 v[152:155], v235 offset:2048
	ds_read_b128 v[156:159], v235 offset:3072
	ds_read_b128 v[160:163], v236
	ds_read_b128 v[164:167], v236 offset:1024
	ds_read_b128 v[168:171], v236 offset:2048
	ds_read_b128 v[172:175], v236 offset:3072
	ds_read_b128 v[176:179], v236 offset:4096
	ds_read_b128 v[180:183], v236 offset:5120
	ds_read_b128 v[198:201], v236 offset:6144
	ds_read_b128 v[202:205], v236 offset:7168
	s_add_i32 s52, s4, 1
	s_cmp_ge_i32 s52, s22
	s_mov_b64 s[38:39], 0
	s_cbranch_scc1 .LBB0_565
	s_sub_i32 s38, s48, s4
	s_and_b64 s[4:5], s[12:13], exec
	s_cselect_b32 s4, s38, s52
	s_mul_hi_i32 s5, s4, s74
	s_mul_i32 s4, s4, s74
	s_add_u32 s4, s4, s2
	s_addc_u32 s5, s5, s49
	v_cmp_gt_i64_e32 vcc, s[4:5], v[196:197]
	s_mov_b64 s[38:39], 0
	s_cbranch_vccnz .LBB0_565
	s_ashr_i32 s5, s4, 31
	s_lshr_b32 s5, s5, 29
	s_add_i32 s38, s4, s5
	s_and_b32 s5, s38, -8
	s_sub_i32 s39, s4, s5
	s_cmp_gt_i32 s39, -1
	s_mov_b64 s[4:5], -1
	s_cbranch_scc0 .LBB0_562
	s_lshl_b32 s40, s39, 8
	s_mov_b64 s[4:5], 0

; #define PG8_STAGE(bufoff, gbase, voff) do { _Pragma("unroll") for (int _i = 0; _i < 2; ++_i) \
;         __builtin_amdgcn_global_load_lds((const unsigned*)((const char*)(gbase) + (voff)[_i]), (PG8_LAS unsigned*)(lds + (bufoff) + ldsw + _i * 8192), 16, 0, 0); } while (0)
; #define PG8_LDA(dst, b, h) do { _Pragma("unroll") for (int m = 0; m < 4; ++m) _Pragma("unroll") for (int k = 0; k < 2; ++k) dst[m][k] = *(const PG8_LAS bf16x8*)(lds + PG8_SA(b, h) + aoff + m * 2048 + k * 1024); } while (0)
; #define PG8_LDB(dst, b, h) do { _Pragma("unroll") for (int n = 0; n < 2; ++n) _Pragma("unroll") for (int k = 0; k < 2; ++k) dst[n][k] = *(const PG8_LAS bf16x8*)(lds + PG8_SB(b, h) + boff + n * 2048 + k * 1024); } while (0)
; #define PG8_MMA(ai, bj, At, Bt) do { __builtin_amdgcn_s_setprio(1); _Pragma("unroll") for (int m = 0; m < 4; ++m) _Pragma("unroll") for (int n = 0; n < 2; ++n) _Pragma("unroll") for (int k = 0; k < 2; ++k) \
;         acc[ai][bj][m][n] = __builtin_amdgcn_mfma_f32_16x16x32_bf16(Bt[n][k], At[m][k], acc[ai][bj][m][n], 0, 0, 0); __builtin_amdgcn_s_setprio(0); } while (0)
; #define PG8_WAIT_V(n) asm volatile("s_waitcnt vmcnt(" #n ")" ::: "memory")
; #define PG8_WAIT_L(n) asm volatile("s_waitcnt lgkmcnt(" #n ")" ::: "memory")
; #define PG8_BAR __builtin_amdgcn_s_barrier()
; #define PG8_SCHED __builtin_amdgcn_sched_barrier(0)
; template <class Epi, class Sched, bool ALIGN_EPI = false, bool SP2 = false>
; __device__ __forceinline__ void gemm_phase(PG8_LAS unsigned char* lds, const Gemm g, const Sched& S, const Epi& E) {
;     ...
;             const char* a2 = last ? nA : cA + (size_t)(t + 2) * kstep; const char* b2 = last ? nB : cB + (size_t)(t + 2) * kstep;
;             const char* a3 = a2 + kstep; const char* b3 = b2 + kstep;
;             if (last && has_next) S.a_ready(nxt);
;             if constexpr (SP2) {
;             PG8_LDB(B0, 0, 0); PG8_LDB(B1, 0, 1); PG8_SCHED; PG8_LDA(At, 0, 0); PG8_STAGE(PG8_SA(1, 1), a1 + hstep, voffA);
;             PG8_WAIT_V(8); PG8_WAIT_L(0); PG8_BAR; PG8_MMA(0, 0, At, B0); PG8_MMA(0, 1, At, B1); PG8_BAR; PG8_SCHED;
;             PG8_LDA(At, 0, 1); PG8_STAGE(PG8_SB(0, 0), b2, voffB); PG8_STAGE(PG8_SB(0, 1), b2 + hstep, voffB); PG8_STAGE(PG8_SA(0, 0), a2, voffA);
;             PG8_WAIT_V(8); PG8_WAIT_L(0); PG8_BAR; PG8_MMA(1, 0, At, B0); PG8_MMA(1, 1, At, B1); PG8_BAR; PG8_SCHED;
.LBB0_569:
	s_add_u32 s42, s42, 0xb0080
	s_addc_u32 s43, s43, 0
	s_add_u32 s56, s44, 0x100
	s_addc_u32 s57, s45, 0
	s_mov_b32 s58, -2
	s_waitcnt lgkmcnt(0)
	s_add_u32 s44, s42, 0xfff50080
	s_addc_u32 s45, s43, -1
	s_cmp_eq_u32 s58, 40
	s_cselect_b32 s47, s39, s45
	s_cselect_b32 s46, s38, s44
	s_cselect_b32 s45, s41, s57
	s_cselect_b32 s44, s40, s56
	v_lshl_add_u64 v[206:207], s[42:43], 0, v[192:193]
	s_add_i32 m0, s26, 0xc000
	global_load_lds_dwordx4 v[206:207], off
	v_lshl_add_u64 v[206:207], s[42:43], 0, v[194:195]
	s_add_i32 m0, s26, 0xe000
	s_nop 0
	global_load_lds_dwordx4 v[206:207], off
	s_waitcnt vmcnt(8)
	s_waitcnt lgkmcnt(0)
	s_barrier
	s_setprio 1
	s_waitcnt lgkmcnt(0)
	v_mfma_f32_16x16x32_bf16 v[128:131], v[124:127], v[160:163], 0
	v_mfma_f32_16x16x32_bf16 v[120:123], v[136:139], v[160:163], 0
	v_mfma_f32_16x16x32_bf16 v[108:111], v[124:127], v[168:171], 0
	v_mfma_f32_16x16x32_bf16 v[104:107], v[136:139], v[168:171], 0
	v_mfma_f32_16x16x32_bf16 v[92:95], v[124:127], v[176:179], 0
	v_mfma_f32_16x16x32_bf16 v[88:91], v[136:139], v[176:179], 0
	v_mfma_f32_16x16x32_bf16 v[76:79], v[124:127], v[198:201], 0
	v_mfma_f32_16x16x32_bf16 v[72:75], v[136:139], v[198:201], 0
	v_mfma_f32_16x16x32_bf16 v[128:131], v[132:135], v[164:167], v[128:131]
	v_mfma_f32_16x16x32_bf16 v[120:123], v[140:143], v[164:167], v[120:123]
	v_mfma_f32_16x16x32_bf16 v[108:111], v[132:135], v[172:175], v[108:111]
	v_mfma_f32_16x16x32_bf16 v[104:107], v[140:143], v[172:175], v[104:107]
	v_mfma_f32_16x16x32_bf16 v[92:95], v[132:135], v[180:183], v[92:95]
	v_mfma_f32_16x16x32_bf16 v[88:91], v[140:143], v[180:183], v[88:91]
	v_mfma_f32_16x16x32_bf16 v[76:79], v[132:135], v[202:205], v[76:79]
	v_mfma_f32_16x16x32_bf16 v[72:75], v[140:143], v[202:205], v[72:75]
	s_setprio 0
	s_setprio 1
	v_mfma_f32_16x16x32_bf16 v[116:119], v[144:147], v[160:163], 0
	v_mfma_f32_16x16x32_bf16 v[112:115], v[152:155], v[160:163], 0
	v_mfma_f32_16x16x32_bf16 v[100:103], v[144:147], v[168:171], 0
	v_mfma_f32_16x16x32_bf16 v[96:99], v[152:155], v[168:171], 0
	v_mfma_f32_16x16x32_bf16 v[84:87], v[144:147], v[176:179], 0
	v_mfma_f32_16x16x32_bf16 v[80:83], v[152:155], v[176:179], 0
	v_mfma_f32_16x16x32_bf16 v[68:71], v[144:147], v[198:201], 0
	v_mfma_f32_16x16x32_bf16 v[64:67], v[152:155], v[198:201], 0
	v_mfma_f32_16x16x32_bf16 v[116:119], v[148:151], v[164:167], v[116:119]
	v_mfma_f32_16x16x32_bf16 v[112:115], v[156:159], v[164:167], v[112:115]
	v_mfma_f32_16x16x32_bf16 v[100:103], v[148:151], v[172:175], v[100:103]
	v_mfma_f32_16x16x32_bf16 v[96:99], v[156:159], v[172:175], v[96:99]
	v_mfma_f32_16x16x32_bf16 v[84:87], v[148:151], v[180:183], v[84:87]
	v_mfma_f32_16x16x32_bf16 v[80:83], v[156:159], v[180:183], v[80:83]
	v_mfma_f32_16x16x32_bf16 v[68:71], v[148:151], v[202:205], v[68:71]
	v_mfma_f32_16x16x32_bf16 v[64:67], v[156:159], v[202:205], v[64:67]
	s_setprio 0
	s_barrier
	s_add_i32 s59, s50, s25
	v_lshl_add_u64 v[206:207], s[44:45], 0, v[186:187]
	s_mov_b32 m0, s59
	ds_read_b128 v[160:163], v236 offset:16384
	ds_read_b128 v[164:167], v236 offset:17408
	ds_read_b128 v[168:171], v236 offset:18432
	ds_read_b128 v[172:175], v236 offset:19456
	ds_read_b128 v[176:179], v236 offset:20480
	ds_read_b128 v[180:183], v236 offset:21504
	ds_read_b128 v[198:201], v236 offset:22528
	ds_read_b128 v[202:205], v236 offset:23552
	global_load_lds_dwordx4 v[206:207], off
	s_add_i32 m0, s59, 0x2000
	s_add_u32 s60, s44, 0xb0000
	v_lshl_add_u64 v[208:209], s[44:45], 0, v[190:191]
	s_addc_u32 s61, s45, 0
	s_add_i32 s59, s51, s25
	global_load_lds_dwordx4 v[208:209], off
	v_lshl_add_u64 v[210:211], s[60:61], 0, v[186:187]
	s_mov_b32 m0, s59
	v_lshl_add_u64 v[212:213], s[46:47], 0, v[188:189]
	global_load_lds_dwordx4 v[210:211], off
	v_lshl_add_u64 v[210:211], s[60:61], 0, v[190:191]
	s_add_i32 m0, s59, 0x2000
	s_nop 0
	global_load_lds_dwordx4 v[210:211], off
	v_lshl_add_u64 v[210:211], s[46:47], 0, v[184:185]
	s_mov_b32 m0, s26
	s_nop 0
	global_load_lds_dwordx4 v[210:211], off
	s_mov_b32 m0, s27
	s_nop 0
	global_load_lds_dwordx4 v[212:213], off
	s_waitcnt vmcnt(8)
	s_waitcnt lgkmcnt(0)
	s_barrier
	s_setprio 1
	s_waitcnt lgkmcnt(0)
	v_mfma_f32_16x16x32_bf16 v[60:63], v[124:127], v[160:163], 0
	v_mfma_f32_16x16x32_bf16 v[56:59], v[136:139], v[160:163], 0
	v_mfma_f32_16x16x32_bf16 v[44:47], v[124:127], v[168:171], 0
	v_mfma_f32_16x16x32_bf16 v[40:43], v[136:139], v[168:171], 0
	v_mfma_f32_16x16x32_bf16 v[28:31], v[124:127], v[176:179], 0
	v_mfma_f32_16x16x32_bf16 v[24:27], v[136:139], v[176:179], 0
	v_mfma_f32_16x16x32_bf16 v[12:15], v[124:127], v[198:201], 0
	v_mfma_f32_16x16x32_bf16 v[8:11], v[136:139], v[198:201], 0
	v_mfma_f32_16x16x32_bf16 v[60:63], v[132:135], v[164:167], v[60:63]
	v_mfma_f32_16x16x32_bf16 v[56:59], v[140:143], v[164:167], v[56:59]
	v_mfma_f32_16x16x32_bf16 v[44:47], v[132:135], v[172:175], v[44:47]
	v_mfma_f32_16x16x32_bf16 v[40:43], v[140:143], v[172:175], v[40:43]
	v_mfma_f32_16x16x32_bf16 v[28:31], v[132:135], v[180:183], v[28:31]
	v_mfma_f32_16x16x32_bf16 v[24:27], v[140:143], v[180:183], v[24:27]
	v_mfma_f32_16x16x32_bf16 v[12:15], v[132:135], v[202:205], v[12:15]
	v_mfma_f32_16x16x32_bf16 v[8:11], v[140:143], v[202:205], v[8:11]
	s_setprio 0
	s_setprio 1
	v_mfma_f32_16x16x32_bf16 v[52:55], v[144:147], v[160:163], 0
	v_mfma_f32_16x16x32_bf16 v[48:51], v[152:155], v[160:163], 0
	v_mfma_f32_16x16x32_bf16 v[36:39], v[144:147], v[168:171], 0
	v_mfma_f32_16x16x32_bf16 v[32:35], v[152:155], v[168:171], 0
	v_mfma_f32_16x16x32_bf16 v[20:23], v[144:147], v[176:179], 0
	v_mfma_f32_16x16x32_bf16 v[16:19], v[152:155], v[176:179], 0
	v_mfma_f32_16x16x32_bf16 v[4:7], v[144:147], v[198:201], 0
	v_mfma_f32_16x16x32_bf16 v[0:3], v[152:155], v[198:201], 0
	v_mfma_f32_16x16x32_bf16 v[52:55], v[148:151], v[164:167], v[52:55]
	v_mfma_f32_16x16x32_bf16 v[48:51], v[156:159], v[164:167], v[48:51]
	v_mfma_f32_16x16x32_bf16 v[36:39], v[148:151], v[172:175], v[36:39]
	v_mfma_f32_16x16x32_bf16 v[32:35], v[156:159], v[172:175], v[32:35]
	v_mfma_f32_16x16x32_bf16 v[20:23], v[148:151], v[180:183], v[20:23]
	v_mfma_f32_16x16x32_bf16 v[16:19], v[156:159], v[180:183], v[16:19]
	v_mfma_f32_16x16x32_bf16 v[4:7], v[148:151], v[202:205], v[4:7]
	v_mfma_f32_16x16x32_bf16 v[0:3], v[156:159], v[202:205], v[0:3]
	s_setprio 0
	s_barrier
; #define PG8_STAGE(bufoff, gbase, voff) do { _Pragma("unroll") for (int _i = 0; _i < 2; ++_i) \
;         __builtin_amdgcn_global_load_lds((const unsigned*)((const char*)(gbase) + (voff)[_i]), (PG8_LAS unsigned*)(lds + (bufoff) + ldsw + _i * 8192), 16, 0, 0); } while (0)
; #define PG8_LDA(dst, b, h) do { _Pragma("unroll") for (int m = 0; m < 4; ++m) _Pragma("unroll") for (int k = 0; k < 2; ++k) dst[m][k] = *(const PG8_LAS bf16x8*)(lds + PG8_SA(b, h) + aoff + m * 2048 + k * 1024); } while (0)
; #define PG8_LDB(dst, b, h) do { _Pragma("unroll") for (int n = 0; n < 2; ++n) _Pragma("unroll") for (int k = 0; k < 2; ++k) dst[n][k] = *(const PG8_LAS bf16x8*)(lds + PG8_SB(b, h) + boff + n * 2048 + k * 1024); } while (0)
; #define PG8_MMA(ai, bj, At, Bt) do { __builtin_amdgcn_s_setprio(1); _Pragma("unroll") for (int m = 0; m < 4; ++m) _Pragma("unroll") for (int n = 0; n < 2; ++n) _Pragma("unroll") for (int k = 0; k < 2; ++k) \
;         acc[ai][bj][m][n] = __builtin_amdgcn_mfma_f32_16x16x32_bf16(Bt[n][k], At[m][k], acc[ai][bj][m][n], 0, 0, 0); __builtin_amdgcn_s_setprio(0); } while (0)
; #define PG8_WAIT_V(n) asm volatile("s_waitcnt vmcnt(" #n ")" ::: "memory")
; #define PG8_WAIT_L(n) asm volatile("s_waitcnt lgkmcnt(" #n ")" ::: "memory")
; #define PG8_BAR __builtin_amdgcn_s_barrier()
; #define PG8_SCHED __builtin_amdgcn_sched_barrier(0)
; template <class Epi, class Sched, bool ALIGN_EPI = false, bool SP2 = false>
; __device__ __forceinline__ void gemm_phase(PG8_LAS unsigned char* lds, const Gemm g, const Sched& S, const Epi& E) {
;     ...
;             PG8_LDB(B0, 1, 0); PG8_LDB(B1, 1, 1); PG8_SCHED; PG8_LDA(At, 1, 0); PG8_STAGE(PG8_SA(0, 1), a2 + hstep, voffA);
;             PG8_WAIT_V(8); PG8_WAIT_L(0); PG8_BAR; PG8_MMA(0, 0, At, B0); PG8_MMA(0, 1, At, B1); PG8_BAR; PG8_SCHED;
	s_add_i32 s59, 0, 0x18000
	s_add_i32 s60, 0, 0x1c000
	v_add_u32_e32 v140, s59, v232
	v_add_u32_e32 v156, s60, v232
	ds_read_b128 v[124:127], v140
	ds_read_b128 v[132:135], v140 offset:1024
	ds_read_b128 v[136:139], v140 offset:2048
	ds_read_b128 v[140:143], v140 offset:3072
	ds_read_b128 v[144:147], v156
	ds_read_b128 v[148:151], v156 offset:1024
	ds_read_b128 v[152:155], v156 offset:2048
	ds_read_b128 v[156:159], v156 offset:3072
	s_add_u32 s46, s46, 0xb0000
	s_addc_u32 s47, s47, 0
	s_mov_b32 m0, s28
	v_lshl_add_u64 v[214:215], s[46:47], 0, v[184:185]
	ds_read_b128 v[160:163], v236 offset:32768
	ds_read_b128 v[164:167], v236 offset:33792
	ds_read_b128 v[168:171], v236 offset:34816
	ds_read_b128 v[172:175], v236 offset:35840
	ds_read_b128 v[176:179], v236 offset:36864
	ds_read_b128 v[180:183], v236 offset:37888
	ds_read_b128 v[198:201], v236 offset:38912
	ds_read_b128 v[202:205], v236 offset:39936
	global_load_lds_dwordx4 v[214:215], off
	v_lshl_add_u64 v[214:215], s[46:47], 0, v[188:189]
	s_mov_b32 m0, s29
	s_nop 0
	global_load_lds_dwordx4 v[214:215], off
	s_waitcnt vmcnt(8)
	s_waitcnt lgkmcnt(0)
	s_barrier
	s_setprio 1
	s_waitcnt lgkmcnt(0)
	v_mfma_f32_16x16x32_bf16 v[128:131], v[124:127], v[160:163], v[128:131]
	v_mfma_f32_16x16x32_bf16 v[120:123], v[136:139], v[160:163], v[120:123]
	v_mfma_f32_16x16x32_bf16 v[108:111], v[124:127], v[168:171], v[108:111]
	v_mfma_f32_16x16x32_bf16 v[104:107], v[136:139], v[168:171], v[104:107]
	v_mfma_f32_16x16x32_bf16 v[92:95], v[124:127], v[176:179], v[92:95]
	v_mfma_f32_16x16x32_bf16 v[88:91], v[136:139], v[176:179], v[88:91]
	v_mfma_f32_16x16x32_bf16 v[76:79], v[124:127], v[198:201], v[76:79]
	v_mfma_f32_16x16x32_bf16 v[72:75], v[136:139], v[198:201], v[72:75]
	v_mfma_f32_16x16x32_bf16 v[128:131], v[132:135], v[164:167], v[128:131]
	v_mfma_f32_16x16x32_bf16 v[120:123], v[140:143], v[164:167], v[120:123]
	v_mfma_f32_16x16x32_bf16 v[108:111], v[132:135], v[172:175], v[108:111]
	v_mfma_f32_16x16x32_bf16 v[104:107], v[140:143], v[172:175], v[104:107]
	v_mfma_f32_16x16x32_bf16 v[92:95], v[132:135], v[180:183], v[92:95]
	v_mfma_f32_16x16x32_bf16 v[88:91], v[140:143], v[180:183], v[88:91]
	v_mfma_f32_16x16x32_bf16 v[76:79], v[132:135], v[202:205], v[76:79]
	v_mfma_f32_16x16x32_bf16 v[72:75], v[140:143], v[202:205], v[72:75]
	s_setprio 0
	s_setprio 1
	v_mfma_f32_16x16x32_bf16 v[116:119], v[144:147], v[160:163], v[116:119]
	v_mfma_f32_16x16x32_bf16 v[112:115], v[152:155], v[160:163], v[112:115]
	v_mfma_f32_16x16x32_bf16 v[100:103], v[144:147], v[168:171], v[100:103]
	v_mfma_f32_16x16x32_bf16 v[96:99], v[152:155], v[168:171], v[96:99]
	v_mfma_f32_16x16x32_bf16 v[84:87], v[144:147], v[176:179], v[84:87]
	v_mfma_f32_16x16x32_bf16 v[80:83], v[152:155], v[176:179], v[80:83]
	v_mfma_f32_16x16x32_bf16 v[68:71], v[144:147], v[198:201], v[68:71]
	v_mfma_f32_16x16x32_bf16 v[64:67], v[152:155], v[198:201], v[64:67]
	v_mfma_f32_16x16x32_bf16 v[116:119], v[148:151], v[164:167], v[116:119]
	v_mfma_f32_16x16x32_bf16 v[112:115], v[156:159], v[164:167], v[112:115]
	v_mfma_f32_16x16x32_bf16 v[100:103], v[148:151], v[172:175], v[100:103]
	v_mfma_f32_16x16x32_bf16 v[96:99], v[156:159], v[172:175], v[96:99]
	v_mfma_f32_16x16x32_bf16 v[84:87], v[148:151], v[180:183], v[84:87]
	v_mfma_f32_16x16x32_bf16 v[80:83], v[156:159], v[180:183], v[80:83]
	v_mfma_f32_16x16x32_bf16 v[68:71], v[148:151], v[202:205], v[68:71]
	v_mfma_f32_16x16x32_bf16 v[64:67], v[156:159], v[202:205], v[64:67]
	s_setprio 0
	s_barrier
; #define PG8_STAGE(bufoff, gbase, voff) do { _Pragma("unroll") for (int _i = 0; _i < 2; ++_i) \
;         __builtin_amdgcn_global_load_lds((const unsigned*)((const char*)(gbase) + (voff)[_i]), (PG8_LAS unsigned*)(lds + (bufoff) + ldsw + _i * 8192), 16, 0, 0); } while (0)
; #define PG8_LDA(dst, b, h) do { _Pragma("unroll") for (int m = 0; m < 4; ++m) _Pragma("unroll") for (int k = 0; k < 2; ++k) dst[m][k] = *(const PG8_LAS bf16x8*)(lds + PG8_SA(b, h) + aoff + m * 2048 + k * 1024); } while (0)
; #define PG8_MMA(ai, bj, At, Bt) do { __builtin_amdgcn_s_setprio(1); _Pragma("unroll") for (int m = 0; m < 4; ++m) _Pragma("unroll") for (int n = 0; n < 2; ++n) _Pragma("unroll") for (int k = 0; k < 2; ++k) \
;         acc[ai][bj][m][n] = __builtin_amdgcn_mfma_f32_16x16x32_bf16(Bt[n][k], At[m][k], acc[ai][bj][m][n], 0, 0, 0); __builtin_amdgcn_s_setprio(0); } while (0)
; #define PG8_WAIT_V(n) asm volatile("s_waitcnt vmcnt(" #n ")" ::: "memory")
; #define PG8_WAIT_L(n) asm volatile("s_waitcnt lgkmcnt(" #n ")" ::: "memory")
; #define PG8_BAR __builtin_amdgcn_s_barrier()
; #define PG8_SCHED __builtin_amdgcn_sched_barrier(0)
; template <class Epi, class Sched, bool ALIGN_EPI = false, bool SP2 = false>
; __device__ __forceinline__ void gemm_phase(PG8_LAS unsigned char* lds, const Gemm g, const Sched& S, const Epi& E) {
;     ...
;             PG8_LDA(At, 1, 1); PG8_STAGE(PG8_SB(1, 0), b3, voffB); PG8_STAGE(PG8_SB(1, 1), b3 + hstep, voffB); PG8_STAGE(PG8_SA(1, 0), a3, voffA);
;             PG8_WAIT_V(8); PG8_WAIT_L(0); PG8_BAR; PG8_MMA(1, 0, At, B0); PG8_MMA(1, 1, At, B1); PG8_BAR; PG8_SCHED;
	s_add_i32 s46, s59, s25
	v_lshl_add_u64 v[206:207], v[206:207], 0, s[20:21]
	s_mov_b32 m0, s46
	ds_read_b128 v[160:163], v236 offset:49152
	ds_read_b128 v[164:167], v236 offset:50176
	ds_read_b128 v[168:171], v236 offset:51200
	ds_read_b128 v[172:175], v236 offset:52224
	ds_read_b128 v[176:179], v236 offset:53248
	ds_read_b128 v[180:183], v236 offset:54272
	ds_read_b128 v[198:201], v236 offset:55296
	ds_read_b128 v[202:205], v236 offset:56320
	global_load_lds_dwordx4 v[206:207], off
	s_add_i32 m0, s46, 0x2000
	s_add_u32 s44, s44, 0xb0080
	v_lshl_add_u64 v[206:207], v[208:209], 0, s[20:21]
	s_addc_u32 s45, s45, 0
	s_add_i32 s46, s60, s25
	global_load_lds_dwordx4 v[206:207], off
	v_lshl_add_u64 v[206:207], s[44:45], 0, v[186:187]
	s_mov_b32 m0, s46
	s_nop 0
	global_load_lds_dwordx4 v[206:207], off
	v_lshl_add_u64 v[206:207], s[44:45], 0, v[190:191]
	s_add_i32 m0, s46, 0x2000
	s_nop 0
	global_load_lds_dwordx4 v[206:207], off
	v_lshl_add_u64 v[206:207], v[210:211], 0, s[20:21]
	s_mov_b32 m0, s31
	s_nop 0
	global_load_lds_dwordx4 v[206:207], off
	v_lshl_add_u64 v[206:207], v[212:213], 0, s[20:21]
	s_mov_b32 m0, s33
	s_nop 0
	global_load_lds_dwordx4 v[206:207], off
	s_waitcnt vmcnt(8)
	s_waitcnt lgkmcnt(0)
	s_barrier
	s_setprio 1
	s_waitcnt lgkmcnt(0)
	v_mfma_f32_16x16x32_bf16 v[60:63], v[124:127], v[160:163], v[60:63]
	v_mfma_f32_16x16x32_bf16 v[56:59], v[136:139], v[160:163], v[56:59]
	v_mfma_f32_16x16x32_bf16 v[44:47], v[124:127], v[168:171], v[44:47]
	v_mfma_f32_16x16x32_bf16 v[40:43], v[136:139], v[168:171], v[40:43]
	v_mfma_f32_16x16x32_bf16 v[28:31], v[124:127], v[176:179], v[28:31]
	v_mfma_f32_16x16x32_bf16 v[24:27], v[136:139], v[176:179], v[24:27]
	v_mfma_f32_16x16x32_bf16 v[12:15], v[124:127], v[198:201], v[12:15]
	v_mfma_f32_16x16x32_bf16 v[8:11], v[136:139], v[198:201], v[8:11]
	v_mfma_f32_16x16x32_bf16 v[60:63], v[132:135], v[164:167], v[60:63]
	v_mfma_f32_16x16x32_bf16 v[56:59], v[140:143], v[164:167], v[56:59]
	v_mfma_f32_16x16x32_bf16 v[44:47], v[132:135], v[172:175], v[44:47]
	v_mfma_f32_16x16x32_bf16 v[40:43], v[140:143], v[172:175], v[40:43]
	v_mfma_f32_16x16x32_bf16 v[28:31], v[132:135], v[180:183], v[28:31]
	v_mfma_f32_16x16x32_bf16 v[24:27], v[140:143], v[180:183], v[24:27]
	v_mfma_f32_16x16x32_bf16 v[12:15], v[132:135], v[202:205], v[12:15]
	v_mfma_f32_16x16x32_bf16 v[8:11], v[140:143], v[202:205], v[8:11]
	s_setprio 0
	s_setprio 1
	v_mfma_f32_16x16x32_bf16 v[52:55], v[144:147], v[160:163], v[52:55]
	v_mfma_f32_16x16x32_bf16 v[48:51], v[152:155], v[160:163], v[48:51]
	v_mfma_f32_16x16x32_bf16 v[36:39], v[144:147], v[168:171], v[36:39]
	v_mfma_f32_16x16x32_bf16 v[32:35], v[152:155], v[168:171], v[32:35]
	v_mfma_f32_16x16x32_bf16 v[20:23], v[144:147], v[176:179], v[20:23]
	v_mfma_f32_16x16x32_bf16 v[16:19], v[152:155], v[176:179], v[16:19]
	v_mfma_f32_16x16x32_bf16 v[4:7], v[144:147], v[198:201], v[4:7]
	v_mfma_f32_16x16x32_bf16 v[0:3], v[152:155], v[198:201], v[0:3]
	v_mfma_f32_16x16x32_bf16 v[52:55], v[148:151], v[164:167], v[52:55]
	v_mfma_f32_16x16x32_bf16 v[48:51], v[156:159], v[164:167], v[48:51]
	v_mfma_f32_16x16x32_bf16 v[36:39], v[148:151], v[172:175], v[36:39]
	v_mfma_f32_16x16x32_bf16 v[32:35], v[156:159], v[172:175], v[32:35]
	v_mfma_f32_16x16x32_bf16 v[20:23], v[148:151], v[180:183], v[20:23]
	v_mfma_f32_16x16x32_bf16 v[16:19], v[156:159], v[180:183], v[16:19]
	v_mfma_f32_16x16x32_bf16 v[4:7], v[148:151], v[202:205], v[4:7]
	v_mfma_f32_16x16x32_bf16 v[0:3], v[156:159], v[202:205], v[0:3]
	s_setprio 0
	s_barrier
	s_add_i32 s58, s58, 2
	s_add_u32 s42, s42, 0x100
	s_addc_u32 s43, s43, 0
	s_add_u32 s56, s56, 0x100
	s_addc_u32 s57, s57, 0
	s_cmp_gt_u32 s58, 41

; #define PG8_STAGE(bufoff, gbase, voff) do { _Pragma("unroll") for (int _i = 0; _i < 2; ++_i) \
;         __builtin_amdgcn_global_load_lds((const unsigned*)((const char*)(gbase) + (voff)[_i]), (PG8_LAS unsigned*)(lds + (bufoff) + ldsw + _i * 8192), 16, 0, 0); } while (0)
; #define PG8_LDA(dst, b, h) do { _Pragma("unroll") for (int m = 0; m < 4; ++m) _Pragma("unroll") for (int k = 0; k < 2; ++k) dst[m][k] = *(const PG8_LAS bf16x8*)(lds + PG8_SA(b, h) + aoff + m * 2048 + k * 1024); } while (0)
; #define PG8_LDB(dst, b, h) do { _Pragma("unroll") for (int n = 0; n < 2; ++n) _Pragma("unroll") for (int k = 0; k < 2; ++k) dst[n][k] = *(const PG8_LAS bf16x8*)(lds + PG8_SB(b, h) + boff + n * 2048 + k * 1024); } while (0)
; #define PG8_SCHED __builtin_amdgcn_sched_barrier(0)
;     __host__ __device__ bool next(int i, Unit& u) const {
;         if (i >= nI) return false;
;         const long L = (long)(rev ? nI - 1 - i : i) * G + c; if (L >= nwg) return false;
;         int wgid = (int)L; { const int q = nwg / NXCD, r = nwg % NXCD, xcd = wgid % NXCD, off = wgid / NXCD; wgid = (xcd < r ? xcd * (q + 1) : r * (q + 1) + (xcd - r) * q) + off; }
;         const int nig = WGM * nN, gid = wgid / nig, fm = gid * WGM, gsz = (nM - fm) < WGM ? (nM - fm) : WGM;
;         u.pm = fm + ((wgid % nig) % gsz); u.pn = (wgid % nig) / gsz; return true;
;     }
; template <class Epi, class Sched, bool ALIGN_EPI = false, bool SP2 = false>
; __device__ __forceinline__ void gemm_phase(PG8_LAS unsigned char* lds, const Gemm g, const Sched& S, const Epi& E) {
;     ...
;             PG8_LDB(B0, 0, 0); PG8_LDB(B1, 0, 1); PG8_SCHED; PG8_LDA(At, 0, 0); PG8_STAGE(PG8_SA(1, 1), a1 + hstep, voffA);
.LBB0_656:
	ds_read_b128 v[146:149], v165
	ds_read_b128 v[150:153], v165 offset:1024
	ds_read_b128 v[154:157], v165 offset:2048
	ds_read_b128 v[170:173], v165 offset:3072
	ds_read_b128 v[174:177], v166
	ds_read_b128 v[178:181], v166 offset:1024
	ds_read_b128 v[182:185], v166 offset:2048
	ds_read_b128 v[186:189], v166 offset:3072
	ds_read_b128 v[190:193], v167
	ds_read_b128 v[194:197], v167 offset:1024
	ds_read_b128 v[198:201], v167 offset:2048
	ds_read_b128 v[202:205], v167 offset:3072
	ds_read_b128 v[206:209], v167 offset:4096
	ds_read_b128 v[210:213], v167 offset:5120
	ds_read_b128 v[214:217], v167 offset:6144
	ds_read_b128 v[218:221], v167 offset:7168
	s_add_i32 s30, s30, 1
	s_cmp_ge_i32 s30, s22
	s_mov_b64 s[38:39], 0
	s_cbranch_scc1 .LBB0_659
	s_mul_i32 s5, s30, s52
	s_mul_hi_u32 s21, s30, s53
	s_add_i32 s21, s21, s5
	s_mul_i32 s5, s30, s53
	s_add_u32 s40, s5, s2
	s_addc_u32 s41, s21, s54
	v_cmp_gt_i64_e32 vcc, s[40:41], v[144:145]
	s_cbranch_vccnz .LBB0_659
	s_ashr_i32 s5, s40, 31
	s_lshr_b32 s5, s5, 29
	s_add_i32 s5, s40, s5
	s_ashr_i32 s20, s5, 3
	s_and_b32 s5, s5, -8
	s_sub_i32 s5, s40, s5
	s_cmp_lt_i32 s5, 0
	s_cselect_b32 s21, s55, 0x280
	s_mul_i32 s5, s5, s21
	s_add_i32 s5, s5, s20
	s_mul_hi_i32 s20, s5, 0x66666667
	s_lshr_b32 s21, s20, 31
	s_ashr_i32 s20, s20, 5
	s_add_i32 s20, s20, s21
	s_lshl_b32 s21, s20, 3
	s_sub_i32 s36, 0x200, s21
	s_min_i32 s36, s36, 8
	s_abs_i32 s37, s36
	v_cvt_f32_u32_e32 v0, s37
	s_sub_i32 s39, 0, s37
	s_mulk_i32 s20, 0x50
	s_sub_i32 s5, s5, s20
	v_rcp_iflag_f32_e32 v0, v0
	s_abs_i32 s20, s5
	s_xor_b32 s38, s5, s36
	s_ashr_i32 s38, s38, 31
	v_mul_f32_e32 v0, 0x4f7ffffe, v0
	v_cvt_u32_f32_e32 v0, v0
	s_nop 0
	v_readfirstlane_b32 s40, v0
	s_mul_i32 s39, s39, s40
	s_mul_hi_u32 s39, s40, s39
	s_add_i32 s40, s40, s39
	s_mul_hi_u32 s39, s20, s40
	s_mul_i32 s40, s39, s37
	s_sub_i32 s20, s20, s40
	s_add_i32 s41, s39, 1
	s_sub_i32 s40, s20, s37
	s_cmp_ge_u32 s20, s37
	s_cselect_b32 s39, s41, s39
	s_cselect_b32 s20, s40, s20
	s_add_i32 s40, s39, 1
	s_cmp_ge_u32 s20, s37
	s_cselect_b32 s20, s40, s39
	s_xor_b32 s20, s20, s38
	s_sub_i32 s20, s20, s38
	s_mul_i32 s36, s20, s36
	s_sub_i32 s5, s5, s36
	s_add_i32 s36, s21, s5
	s_mov_b64 s[38:39], -1
; #define PG8_STAGE(bufoff, gbase, voff) do { _Pragma("unroll") for (int _i = 0; _i < 2; ++_i) \
;         __builtin_amdgcn_global_load_lds((const unsigned*)((const char*)(gbase) + (voff)[_i]), (PG8_LAS unsigned*)(lds + (bufoff) + ldsw + _i * 8192), 16, 0, 0); } while (0)
; #define PG8_LDA(dst, b, h) do { _Pragma("unroll") for (int m = 0; m < 4; ++m) _Pragma("unroll") for (int k = 0; k < 2; ++k) dst[m][k] = *(const PG8_LAS bf16x8*)(lds + PG8_SA(b, h) + aoff + m * 2048 + k * 1024); } while (0)
; #define PG8_LDB(dst, b, h) do { _Pragma("unroll") for (int n = 0; n < 2; ++n) _Pragma("unroll") for (int k = 0; k < 2; ++k) dst[n][k] = *(const PG8_LAS bf16x8*)(lds + PG8_SB(b, h) + boff + n * 2048 + k * 1024); } while (0)
; #define PG8_WAIT_V(n) asm volatile("s_waitcnt vmcnt(" #n ")" ::: "memory")
; #define PG8_WAIT_L(n) asm volatile("s_waitcnt lgkmcnt(" #n ")" ::: "memory")
; #define PG8_BAR __builtin_amdgcn_s_barrier()
; #define PG8_SCHED __builtin_amdgcn_sched_barrier(0)
; template <class Epi, class Sched, bool ALIGN_EPI = false, bool SP2 = false>
; __device__ __forceinline__ void gemm_phase(PG8_LAS unsigned char* lds, const Gemm g, const Sched& S, const Epi& E) {
;     ...
;         const char* nA = has_next ? (const char*)g.A + (size_t)nxt.pm * tstep : cA; const char* nB = has_next ? (const char*)g.Bt + (size_t)nxt.pn * tstep : cB;
;         for (int t = 0; t < nt; t += 2) {
;             const bool last = (t == nt - 2);
;             const char* a1 = cA + (size_t)(t + 1) * kstep;
;             const char* a2 = last ? nA : cA + (size_t)(t + 2) * kstep; const char* b2 = last ? nB : cB + (size_t)(t + 2) * kstep;
;             const char* a3 = a2 + kstep; const char* b3 = b2 + kstep;
;             if (last && has_next) S.a_ready(nxt);
;             if constexpr (SP2) {
;             PG8_LDB(B0, 0, 0); PG8_LDB(B1, 0, 1); PG8_SCHED; PG8_LDA(At, 0, 0); PG8_STAGE(PG8_SA(1, 1), a1 + hstep, voffA);
;             PG8_WAIT_V(8); PG8_WAIT_L(0); PG8_BAR; PG8_MMA(0, 0, At, B0); PG8_MMA(0, 1, At, B1); PG8_BAR; PG8_SCHED;
;             PG8_LDA(At, 0, 1); PG8_STAGE(PG8_SB(0, 0), b2, voffB); PG8_STAGE(PG8_SB(0, 1), b2 + hstep, voffB); PG8_STAGE(PG8_SA(0, 0), a2, voffA);
;             PG8_WAIT_V(8); PG8_WAIT_L(0); PG8_BAR; PG8_MMA(1, 0, At, B0); PG8_MMA(1, 1, At, B1); PG8_BAR; PG8_SCHED;
.LBB0_659:
	s_ashr_i32 s37, s36, 31
	s_lshl_b64 s[40:41], s[36:37], 19
	s_add_u32 s40, s70, s40
	s_addc_u32 s41, s71, s41
	s_and_b64 s[42:43], s[38:39], exec
	s_cselect_b32 s5, s41, s1
	s_cselect_b32 s37, s40, s0
	s_ashr_i32 s21, s20, 31
	s_lshl_b64 s[42:43], s[20:21], 19
	s_add_u32 s42, s23, s42
	s_addc_u32 s43, s24, s43
	s_and_b64 s[48:49], s[38:39], exec
	s_cselect_b32 s21, s43, s47
	s_cselect_b32 s45, s42, s46
	s_add_u32 s0, s0, 0x40080
	s_addc_u32 s1, s1, 0
	s_add_u32 s50, s46, 0x100
	s_addc_u32 s51, s47, 0
	s_mov_b32 s59, -2
	s_add_u32 s46, s0, 0xfffc0080
	s_addc_u32 s47, s1, -1
	s_cmp_eq_u32 s59, 12
	s_cselect_b32 s49, s5, s47
	s_cselect_b32 s48, s37, s46
	s_cselect_b32 s47, s21, s51
	s_cselect_b32 s46, s45, s50
	v_lshl_add_u64 v[158:159], s[0:1], 0, v[140:141]
	s_add_i32 m0, s26, 0xc000
	global_load_lds_dwordx4 v[158:159], off
	v_lshl_add_u64 v[158:159], s[0:1], 0, v[142:143]
	s_add_i32 m0, s26, 0xe000
	s_nop 0
	global_load_lds_dwordx4 v[158:159], off
	s_waitcnt vmcnt(8)
	s_waitcnt lgkmcnt(0)
	s_barrier
	s_setprio 1
	s_waitcnt lgkmcnt(0)
	v_mfma_f32_16x16x32_bf16 v[124:127], v[146:149], v[190:193], 0
	v_mfma_f32_16x16x32_bf16 v[120:123], v[154:157], v[190:193], 0
	v_mfma_f32_16x16x32_bf16 v[108:111], v[146:149], v[198:201], 0
	v_mfma_f32_16x16x32_bf16 v[104:107], v[154:157], v[198:201], 0
	v_mfma_f32_16x16x32_bf16 v[92:95], v[146:149], v[206:209], 0
	v_mfma_f32_16x16x32_bf16 v[88:91], v[154:157], v[206:209], 0
	v_mfma_f32_16x16x32_bf16 v[76:79], v[146:149], v[214:217], 0
	v_mfma_f32_16x16x32_bf16 v[72:75], v[154:157], v[214:217], 0
	v_mfma_f32_16x16x32_bf16 v[124:127], v[150:153], v[194:197], v[124:127]
	v_mfma_f32_16x16x32_bf16 v[120:123], v[170:173], v[194:197], v[120:123]
	v_mfma_f32_16x16x32_bf16 v[108:111], v[150:153], v[202:205], v[108:111]
	v_mfma_f32_16x16x32_bf16 v[104:107], v[170:173], v[202:205], v[104:107]
	v_mfma_f32_16x16x32_bf16 v[92:95], v[150:153], v[210:213], v[92:95]
	v_mfma_f32_16x16x32_bf16 v[88:91], v[170:173], v[210:213], v[88:91]
	v_mfma_f32_16x16x32_bf16 v[76:79], v[150:153], v[218:221], v[76:79]
	v_mfma_f32_16x16x32_bf16 v[72:75], v[170:173], v[218:221], v[72:75]
	s_setprio 0
	s_setprio 1
	v_mfma_f32_16x16x32_bf16 v[116:119], v[174:177], v[190:193], 0
	v_mfma_f32_16x16x32_bf16 v[112:115], v[182:185], v[190:193], 0
	v_mfma_f32_16x16x32_bf16 v[100:103], v[174:177], v[198:201], 0
	v_mfma_f32_16x16x32_bf16 v[96:99], v[182:185], v[198:201], 0
	v_mfma_f32_16x16x32_bf16 v[84:87], v[174:177], v[206:209], 0
	v_mfma_f32_16x16x32_bf16 v[80:83], v[182:185], v[206:209], 0
	v_mfma_f32_16x16x32_bf16 v[68:71], v[174:177], v[214:217], 0
	v_mfma_f32_16x16x32_bf16 v[64:67], v[182:185], v[214:217], 0
	v_mfma_f32_16x16x32_bf16 v[116:119], v[178:181], v[194:197], v[116:119]
	v_mfma_f32_16x16x32_bf16 v[112:115], v[186:189], v[194:197], v[112:115]
	v_mfma_f32_16x16x32_bf16 v[100:103], v[178:181], v[202:205], v[100:103]
	v_mfma_f32_16x16x32_bf16 v[96:99], v[186:189], v[202:205], v[96:99]
	v_mfma_f32_16x16x32_bf16 v[84:87], v[178:181], v[210:213], v[84:87]
	v_mfma_f32_16x16x32_bf16 v[80:83], v[186:189], v[210:213], v[80:83]
	v_mfma_f32_16x16x32_bf16 v[68:71], v[178:181], v[218:221], v[68:71]
	v_mfma_f32_16x16x32_bf16 v[64:67], v[186:189], v[218:221], v[64:67]
	s_setprio 0
	s_barrier
	s_add_i32 s60, s56, s25
	v_lshl_add_u64 v[158:159], s[46:47], 0, v[130:131]
	s_mov_b32 m0, s60
	ds_read_b128 v[190:193], v167 offset:16384
	ds_read_b128 v[194:197], v167 offset:17408
	ds_read_b128 v[198:201], v167 offset:18432
	ds_read_b128 v[202:205], v167 offset:19456
	ds_read_b128 v[206:209], v167 offset:20480
	ds_read_b128 v[210:213], v167 offset:21504
	ds_read_b128 v[214:217], v167 offset:22528
	ds_read_b128 v[218:221], v167 offset:23552
	global_load_lds_dwordx4 v[158:159], off
	s_add_i32 m0, s60, 0x2000
	s_add_u32 s60, s46, 0x40000
	v_lshl_add_u64 v[162:163], s[46:47], 0, v[134:135]
	s_addc_u32 s61, s47, 0
	s_add_i32 s62, s57, s25
	global_load_lds_dwordx4 v[162:163], off
	v_lshl_add_u64 v[222:223], s[60:61], 0, v[130:131]
	s_mov_b32 m0, s62
	v_lshl_add_u64 v[224:225], s[48:49], 0, v[132:133]
	global_load_lds_dwordx4 v[222:223], off
	v_lshl_add_u64 v[222:223], s[60:61], 0, v[134:135]
	s_add_i32 m0, s62, 0x2000
	s_nop 0
	global_load_lds_dwordx4 v[222:223], off
	v_lshl_add_u64 v[222:223], s[48:49], 0, v[128:129]
	s_mov_b32 m0, s26
	s_nop 0
	global_load_lds_dwordx4 v[222:223], off
	s_mov_b32 m0, s27
	s_nop 0
	global_load_lds_dwordx4 v[224:225], off
	s_cmp_lg_i32 s59, -2
	s_cbranch_scc1 .Lrsc_a_pl
	v_lshrrev_b32_e32 v250, 6, v230
	v_lshlrev_b32_e32 v250, 11, v250
	v_and_b32_e32 v251, 63, v230
	v_lshl_or_b32 v250, v251, 4, v250
	v_lshl_add_u32 v250, s44, 14, v250
	v_readfirstlane_b32 s98, v230
	s_lshr_b32 s98, s98, 6
	s_lshl_b32 s98, s98, 11
	s_add_i32 m0, s98, 0x20000
	s_add_u32 s100, s70, 0x3f000000
	s_addc_u32 s101, s71, 0
	global_load_lds_dwordx4 v250, s[100:101]
	global_load_lds_dwordx4 v250, s[100:101] offset:1024
	s_waitcnt vmcnt(10)
	s_branch .Lrsc_b_pl

; #define PG8_STAGE(bufoff, gbase, voff) do { _Pragma("unroll") for (int _i = 0; _i < 2; ++_i) \
;         __builtin_amdgcn_global_load_lds((const unsigned*)((const char*)(gbase) + (voff)[_i]), (PG8_LAS unsigned*)(lds + (bufoff) + ldsw + _i * 8192), 16, 0, 0); } while (0)
; #define PG8_LDA(dst, b, h) do { _Pragma("unroll") for (int m = 0; m < 4; ++m) _Pragma("unroll") for (int k = 0; k < 2; ++k) dst[m][k] = *(const PG8_LAS bf16x8*)(lds + PG8_SA(b, h) + aoff + m * 2048 + k * 1024); } while (0)
; #define PG8_LDB(dst, b, h) do { _Pragma("unroll") for (int n = 0; n < 2; ++n) _Pragma("unroll") for (int k = 0; k < 2; ++k) dst[n][k] = *(const PG8_LAS bf16x8*)(lds + PG8_SB(b, h) + boff + n * 2048 + k * 1024); } while (0)
; #define PG8_SCHED __builtin_amdgcn_sched_barrier(0)
;     __host__ __device__ bool next(int i, Unit& u) const {
;         if (i >= nI) return false;
;         const long L = (long)(rev ? nI - 1 - i : i) * G + c; if (L >= nwg) return false;
;         int wgid = (int)L; { const int q = nwg / NXCD, r = nwg % NXCD, xcd = wgid % NXCD, off = wgid / NXCD; wgid = (xcd < r ? xcd * (q + 1) : r * (q + 1) + (xcd - r) * q) + off; }
;         const int nig = WGM * nN, gid = wgid / nig, fm = gid * WGM, gsz = (nM - fm) < WGM ? (nM - fm) : WGM;
;         u.pm = fm + ((wgid % nig) % gsz); u.pn = (wgid % nig) / gsz; return true;
;     }
; template <class Epi, class Sched, bool ALIGN_EPI = false, bool SP2 = false>
; __device__ __forceinline__ void gemm_phase(PG8_LAS unsigned char* lds, const Gemm g, const Sched& S, const Epi& E) {
;     ...
;             PG8_LDB(B0, 0, 0); PG8_LDB(B1, 0, 1); PG8_SCHED; PG8_LDA(At, 0, 0); PG8_STAGE(PG8_SA(1, 1), a1 + hstep, voffA);
.LBB0_880:
	ds_read_b128 v[124:127], v234
	ds_read_b128 v[132:135], v234 offset:1024
	ds_read_b128 v[136:139], v234 offset:2048
	ds_read_b128 v[140:143], v234 offset:3072
	ds_read_b128 v[144:147], v235
	ds_read_b128 v[148:151], v235 offset:1024
	ds_read_b128 v[152:155], v235 offset:2048
	ds_read_b128 v[156:159], v235 offset:3072
	ds_read_b128 v[160:163], v236
	ds_read_b128 v[164:167], v236 offset:1024
	ds_read_b128 v[168:171], v236 offset:2048
	ds_read_b128 v[172:175], v236 offset:3072
	ds_read_b128 v[176:179], v236 offset:4096
	ds_read_b128 v[180:183], v236 offset:5120
	ds_read_b128 v[198:201], v236 offset:6144
	ds_read_b128 v[202:205], v236 offset:7168
	s_add_i32 s57, s57, 1
	s_cmp_ge_i32 s57, s33
	s_mov_b64 s[24:25], 0
	s_cbranch_scc1 .LBB0_887
	s_mul_i32 s21, s57, s52
	s_mul_hi_u32 s23, s57, s53
	s_add_i32 s23, s23, s21
	s_mul_i32 s21, s57, s53
	s_add_u32 s26, s21, s2
	s_addc_u32 s27, s23, s54
	v_cmp_gt_i64_e32 vcc, s[26:27], v[196:197]
	s_cbranch_vccnz .LBB0_887
	s_ashr_i32 s20, s26, 31
	s_lshr_b32 s20, s20, 29
	s_add_i32 s22, s26, s20
	s_and_b32 s20, s22, -8
	s_sub_i32 s23, s26, s20
	s_cmp_gt_i32 s23, -1
	s_mov_b64 s[20:21], -1
	s_cbranch_scc0 .LBB0_884
	s_lshl_b32 s24, s23, 8
	s_mov_b64 s[20:21], 0

; #define PG8_STAGE(bufoff, gbase, voff) do { _Pragma("unroll") for (int _i = 0; _i < 2; ++_i) \
;         __builtin_amdgcn_global_load_lds((const unsigned*)((const char*)(gbase) + (voff)[_i]), (PG8_LAS unsigned*)(lds + (bufoff) + ldsw + _i * 8192), 16, 0, 0); } while (0)
; #define PG8_LDA(dst, b, h) do { _Pragma("unroll") for (int m = 0; m < 4; ++m) _Pragma("unroll") for (int k = 0; k < 2; ++k) dst[m][k] = *(const PG8_LAS bf16x8*)(lds + PG8_SA(b, h) + aoff + m * 2048 + k * 1024); } while (0)
; #define PG8_LDB(dst, b, h) do { _Pragma("unroll") for (int n = 0; n < 2; ++n) _Pragma("unroll") for (int k = 0; k < 2; ++k) dst[n][k] = *(const PG8_LAS bf16x8*)(lds + PG8_SB(b, h) + boff + n * 2048 + k * 1024); } while (0)
; #define PG8_WAIT_V(n) asm volatile("s_waitcnt vmcnt(" #n ")" ::: "memory")
; #define PG8_WAIT_L(n) asm volatile("s_waitcnt lgkmcnt(" #n ")" ::: "memory")
; #define PG8_BAR __builtin_amdgcn_s_barrier()
; #define PG8_SCHED __builtin_amdgcn_sched_barrier(0)
; template <class Epi, class Sched, bool ALIGN_EPI = false, bool SP2 = false>
; __device__ __forceinline__ void gemm_phase(PG8_LAS unsigned char* lds, const Gemm g, const Sched& S, const Epi& E) {
;     ...
;         const char* nA = has_next ? (const char*)g.A + (size_t)nxt.pm * tstep : cA; const char* nB = has_next ? (const char*)g.Bt + (size_t)nxt.pn * tstep : cB;
;         for (int t = 0; t < nt; t += 2) {
;             const bool last = (t == nt - 2);
;             const char* a1 = cA + (size_t)(t + 1) * kstep;
;             const char* a2 = last ? nA : cA + (size_t)(t + 2) * kstep; const char* b2 = last ? nB : cB + (size_t)(t + 2) * kstep;
;             const char* a3 = a2 + kstep; const char* b3 = b2 + kstep;
;             if (last && has_next) S.a_ready(nxt);
;             if constexpr (SP2) {
;             PG8_LDB(B0, 0, 0); PG8_LDB(B1, 0, 1); PG8_SCHED; PG8_LDA(At, 0, 0); PG8_STAGE(PG8_SA(1, 1), a1 + hstep, voffA);
;             PG8_WAIT_V(8); PG8_WAIT_L(0); PG8_BAR; PG8_MMA(0, 0, At, B0); PG8_MMA(0, 1, At, B1); PG8_BAR; PG8_SCHED;
;             PG8_LDA(At, 0, 1); PG8_STAGE(PG8_SB(0, 0), b2, voffB); PG8_STAGE(PG8_SB(0, 1), b2 + hstep, voffB); PG8_STAGE(PG8_SA(0, 0), a2, voffA);
;             PG8_WAIT_V(8); PG8_WAIT_L(0); PG8_BAR; PG8_MMA(1, 0, At, B0); PG8_MMA(1, 1, At, B1); PG8_BAR; PG8_SCHED;
.LBB0_887:
	s_ashr_i32 s23, s22, 31
	s_lshl_b64 s[26:27], s[22:23], 19
	s_add_u32 s26, s68, s26
	s_addc_u32 s27, s69, s27
	s_and_b64 s[28:29], s[24:25], exec
	s_cselect_b32 s23, s27, s37
	s_cselect_b32 s31, s26, s36
	s_ashr_i32 s21, s20, 31
	s_lshl_b64 s[28:29], s[20:21], 19
	s_add_u32 s28, s42, s28
	s_addc_u32 s29, s43, s29
	s_and_b64 s[40:41], s[24:25], exec
	s_cselect_b32 s21, s29, s39
	s_cselect_b32 s58, s28, s38
	s_add_u32 s36, s36, 0x40080
	s_addc_u32 s37, s37, 0
	s_add_u32 s59, s38, 0x100
	s_addc_u32 s60, s39, 0
	s_mov_b32 s61, -2
	s_waitcnt lgkmcnt(0)
	s_add_u32 s38, s36, 0xfffc0080
	s_addc_u32 s39, s37, -1
	s_cmp_eq_u32 s61, 12
	s_cselect_b32 s41, s23, s39
	s_cselect_b32 s40, s31, s38
	s_cselect_b32 s39, s21, s60
	s_cselect_b32 s38, s58, s59
	v_lshl_add_u64 v[206:207], s[36:37], 0, v[192:193]
	s_add_i32 m0, s45, 0xc000
	global_load_lds_dwordx4 v[206:207], off
	v_lshl_add_u64 v[206:207], s[36:37], 0, v[194:195]
	s_add_i32 m0, s45, 0xe000
	s_nop 0
	global_load_lds_dwordx4 v[206:207], off
	s_waitcnt vmcnt(8)
	s_waitcnt lgkmcnt(0)
	s_barrier
	s_setprio 1
	s_waitcnt lgkmcnt(0)
	v_mfma_f32_16x16x32_bf16 v[128:131], v[124:127], v[160:163], 0
	v_mfma_f32_16x16x32_bf16 v[120:123], v[136:139], v[160:163], 0
	v_mfma_f32_16x16x32_bf16 v[108:111], v[124:127], v[168:171], 0
	v_mfma_f32_16x16x32_bf16 v[104:107], v[136:139], v[168:171], 0
	v_mfma_f32_16x16x32_bf16 v[92:95], v[124:127], v[176:179], 0
	v_mfma_f32_16x16x32_bf16 v[88:91], v[136:139], v[176:179], 0
	v_mfma_f32_16x16x32_bf16 v[76:79], v[124:127], v[198:201], 0
	v_mfma_f32_16x16x32_bf16 v[72:75], v[136:139], v[198:201], 0
	v_mfma_f32_16x16x32_bf16 v[128:131], v[132:135], v[164:167], v[128:131]
	v_mfma_f32_16x16x32_bf16 v[120:123], v[140:143], v[164:167], v[120:123]
	v_mfma_f32_16x16x32_bf16 v[108:111], v[132:135], v[172:175], v[108:111]
	v_mfma_f32_16x16x32_bf16 v[104:107], v[140:143], v[172:175], v[104:107]
	v_mfma_f32_16x16x32_bf16 v[92:95], v[132:135], v[180:183], v[92:95]
	v_mfma_f32_16x16x32_bf16 v[88:91], v[140:143], v[180:183], v[88:91]
	v_mfma_f32_16x16x32_bf16 v[76:79], v[132:135], v[202:205], v[76:79]
	v_mfma_f32_16x16x32_bf16 v[72:75], v[140:143], v[202:205], v[72:75]
	s_setprio 0
	s_setprio 1
	v_mfma_f32_16x16x32_bf16 v[116:119], v[144:147], v[160:163], 0
	v_mfma_f32_16x16x32_bf16 v[112:115], v[152:155], v[160:163], 0
	v_mfma_f32_16x16x32_bf16 v[100:103], v[144:147], v[168:171], 0
	v_mfma_f32_16x16x32_bf16 v[96:99], v[152:155], v[168:171], 0
	v_mfma_f32_16x16x32_bf16 v[84:87], v[144:147], v[176:179], 0
	v_mfma_f32_16x16x32_bf16 v[80:83], v[152:155], v[176:179], 0
	v_mfma_f32_16x16x32_bf16 v[68:71], v[144:147], v[198:201], 0
	v_mfma_f32_16x16x32_bf16 v[64:67], v[152:155], v[198:201], 0
	v_mfma_f32_16x16x32_bf16 v[116:119], v[148:151], v[164:167], v[116:119]
	v_mfma_f32_16x16x32_bf16 v[112:115], v[156:159], v[164:167], v[112:115]
	v_mfma_f32_16x16x32_bf16 v[100:103], v[148:151], v[172:175], v[100:103]
	v_mfma_f32_16x16x32_bf16 v[96:99], v[156:159], v[172:175], v[96:99]
	v_mfma_f32_16x16x32_bf16 v[84:87], v[148:151], v[180:183], v[84:87]
	v_mfma_f32_16x16x32_bf16 v[80:83], v[156:159], v[180:183], v[80:83]
	v_mfma_f32_16x16x32_bf16 v[68:71], v[148:151], v[202:205], v[68:71]
	v_mfma_f32_16x16x32_bf16 v[64:67], v[156:159], v[202:205], v[64:67]
	s_setprio 0
	s_barrier
	s_add_i32 s62, s55, s44
	v_lshl_add_u64 v[206:207], s[38:39], 0, v[186:187]
	s_mov_b32 m0, s62
	ds_read_b128 v[160:163], v236 offset:16384
	ds_read_b128 v[164:167], v236 offset:17408
	ds_read_b128 v[168:171], v236 offset:18432
	ds_read_b128 v[172:175], v236 offset:19456
	ds_read_b128 v[176:179], v236 offset:20480
	ds_read_b128 v[180:183], v236 offset:21504
	ds_read_b128 v[198:201], v236 offset:22528
	ds_read_b128 v[202:205], v236 offset:23552
	global_load_lds_dwordx4 v[206:207], off
	s_add_i32 m0, s62, 0x2000
	s_add_u32 s62, s38, 0x40000
	v_lshl_add_u64 v[208:209], s[38:39], 0, v[190:191]
	s_addc_u32 s63, s39, 0
	s_add_i32 s64, s56, s44
	global_load_lds_dwordx4 v[208:209], off
	v_lshl_add_u64 v[210:211], s[62:63], 0, v[186:187]
	s_mov_b32 m0, s64
	v_lshl_add_u64 v[212:213], s[40:41], 0, v[188:189]
	global_load_lds_dwordx4 v[210:211], off
	v_lshl_add_u64 v[210:211], s[62:63], 0, v[190:191]
	s_add_i32 m0, s64, 0x2000
	s_nop 0
	global_load_lds_dwordx4 v[210:211], off
	v_lshl_add_u64 v[210:211], s[40:41], 0, v[184:185]
	s_mov_b32 m0, s45
	s_nop 0
	global_load_lds_dwordx4 v[210:211], off
	s_mov_b32 m0, s46
	s_nop 0
	global_load_lds_dwordx4 v[212:213], off
	s_waitcnt vmcnt(8)
	s_waitcnt lgkmcnt(0)
	s_barrier
	s_setprio 1
	s_waitcnt lgkmcnt(0)
	v_mfma_f32_16x16x32_bf16 v[60:63], v[124:127], v[160:163], 0
	v_mfma_f32_16x16x32_bf16 v[56:59], v[136:139], v[160:163], 0
	v_mfma_f32_16x16x32_bf16 v[44:47], v[124:127], v[168:171], 0
	v_mfma_f32_16x16x32_bf16 v[40:43], v[136:139], v[168:171], 0
	v_mfma_f32_16x16x32_bf16 v[28:31], v[124:127], v[176:179], 0
	v_mfma_f32_16x16x32_bf16 v[24:27], v[136:139], v[176:179], 0
	v_mfma_f32_16x16x32_bf16 v[12:15], v[124:127], v[198:201], 0
	v_mfma_f32_16x16x32_bf16 v[8:11], v[136:139], v[198:201], 0
	v_mfma_f32_16x16x32_bf16 v[60:63], v[132:135], v[164:167], v[60:63]
	v_mfma_f32_16x16x32_bf16 v[56:59], v[140:143], v[164:167], v[56:59]
	v_mfma_f32_16x16x32_bf16 v[44:47], v[132:135], v[172:175], v[44:47]
	v_mfma_f32_16x16x32_bf16 v[40:43], v[140:143], v[172:175], v[40:43]
	v_mfma_f32_16x16x32_bf16 v[28:31], v[132:135], v[180:183], v[28:31]
	v_mfma_f32_16x16x32_bf16 v[24:27], v[140:143], v[180:183], v[24:27]
	v_mfma_f32_16x16x32_bf16 v[12:15], v[132:135], v[202:205], v[12:15]
	v_mfma_f32_16x16x32_bf16 v[8:11], v[140:143], v[202:205], v[8:11]
	s_setprio 0
	s_setprio 1
	v_mfma_f32_16x16x32_bf16 v[52:55], v[144:147], v[160:163], 0
	v_mfma_f32_16x16x32_bf16 v[48:51], v[152:155], v[160:163], 0
	v_mfma_f32_16x16x32_bf16 v[36:39], v[144:147], v[168:171], 0
	v_mfma_f32_16x16x32_bf16 v[32:35], v[152:155], v[168:171], 0
	v_mfma_f32_16x16x32_bf16 v[20:23], v[144:147], v[176:179], 0
	v_mfma_f32_16x16x32_bf16 v[16:19], v[152:155], v[176:179], 0
	v_mfma_f32_16x16x32_bf16 v[4:7], v[144:147], v[198:201], 0
	v_mfma_f32_16x16x32_bf16 v[0:3], v[152:155], v[198:201], 0
	v_mfma_f32_16x16x32_bf16 v[52:55], v[148:151], v[164:167], v[52:55]
	v_mfma_f32_16x16x32_bf16 v[48:51], v[156:159], v[164:167], v[48:51]
	v_mfma_f32_16x16x32_bf16 v[36:39], v[148:151], v[172:175], v[36:39]
	v_mfma_f32_16x16x32_bf16 v[32:35], v[156:159], v[172:175], v[32:35]
	v_mfma_f32_16x16x32_bf16 v[20:23], v[148:151], v[180:183], v[20:23]
	v_mfma_f32_16x16x32_bf16 v[16:19], v[156:159], v[180:183], v[16:19]
	v_mfma_f32_16x16x32_bf16 v[4:7], v[148:151], v[202:205], v[4:7]
	v_mfma_f32_16x16x32_bf16 v[0:3], v[156:159], v[202:205], v[0:3]
	s_setprio 0
	s_barrier
; #define PG8_STAGE(bufoff, gbase, voff) do { _Pragma("unroll") for (int _i = 0; _i < 2; ++_i) \
;         __builtin_amdgcn_global_load_lds((const unsigned*)((const char*)(gbase) + (voff)[_i]), (PG8_LAS unsigned*)(lds + (bufoff) + ldsw + _i * 8192), 16, 0, 0); } while (0)
; #define PG8_LDA(dst, b, h) do { _Pragma("unroll") for (int m = 0; m < 4; ++m) _Pragma("unroll") for (int k = 0; k < 2; ++k) dst[m][k] = *(const PG8_LAS bf16x8*)(lds + PG8_SA(b, h) + aoff + m * 2048 + k * 1024); } while (0)
; #define PG8_LDB(dst, b, h) do { _Pragma("unroll") for (int n = 0; n < 2; ++n) _Pragma("unroll") for (int k = 0; k < 2; ++k) dst[n][k] = *(const PG8_LAS bf16x8*)(lds + PG8_SB(b, h) + boff + n * 2048 + k * 1024); } while (0)
; #define PG8_MMA(ai, bj, At, Bt) do { __builtin_amdgcn_s_setprio(1); _Pragma("unroll") for (int m = 0; m < 4; ++m) _Pragma("unroll") for (int n = 0; n < 2; ++n) _Pragma("unroll") for (int k = 0; k < 2; ++k) \
;         acc[ai][bj][m][n] = __builtin_amdgcn_mfma_f32_16x16x32_bf16(Bt[n][k], At[m][k], acc[ai][bj][m][n], 0, 0, 0); __builtin_amdgcn_s_setprio(0); } while (0)
; #define PG8_WAIT_V(n) asm volatile("s_waitcnt vmcnt(" #n ")" ::: "memory")
; #define PG8_WAIT_L(n) asm volatile("s_waitcnt lgkmcnt(" #n ")" ::: "memory")
; #define PG8_BAR __builtin_amdgcn_s_barrier()
; #define PG8_SCHED __builtin_amdgcn_sched_barrier(0)
; template <class Epi, class Sched, bool ALIGN_EPI = false, bool SP2 = false>
; __device__ __forceinline__ void gemm_phase(PG8_LAS unsigned char* lds, const Gemm g, const Sched& S, const Epi& E) {
;     ...
;             PG8_LDB(B0, 1, 0); PG8_LDB(B1, 1, 1); PG8_SCHED; PG8_LDA(At, 1, 0); PG8_STAGE(PG8_SA(0, 1), a2 + hstep, voffA);
;             PG8_WAIT_V(8); PG8_WAIT_L(0); PG8_BAR; PG8_MMA(0, 0, At, B0); PG8_MMA(0, 1, At, B1); PG8_BAR; PG8_SCHED;
	s_add_i32 s62, 0, 0x18000
	s_add_i32 s63, 0, 0x1c000
	v_add_u32_e32 v140, s62, v232
	v_add_u32_e32 v156, s63, v232
	ds_read_b128 v[124:127], v140
	ds_read_b128 v[132:135], v140 offset:1024
	ds_read_b128 v[136:139], v140 offset:2048
	ds_read_b128 v[140:143], v140 offset:3072
	ds_read_b128 v[144:147], v156
	ds_read_b128 v[148:151], v156 offset:1024
	ds_read_b128 v[152:155], v156 offset:2048
	ds_read_b128 v[156:159], v156 offset:3072
	s_add_u32 s40, s40, 0x40000
	s_addc_u32 s41, s41, 0
	s_mov_b32 m0, s47
	v_lshl_add_u64 v[214:215], s[40:41], 0, v[184:185]
	ds_read_b128 v[160:163], v236 offset:32768
	ds_read_b128 v[164:167], v236 offset:33792
	ds_read_b128 v[168:171], v236 offset:34816
	ds_read_b128 v[172:175], v236 offset:35840
	ds_read_b128 v[176:179], v236 offset:36864
	ds_read_b128 v[180:183], v236 offset:37888
	ds_read_b128 v[198:201], v236 offset:38912
	ds_read_b128 v[202:205], v236 offset:39936
	global_load_lds_dwordx4 v[214:215], off
	v_lshl_add_u64 v[214:215], s[40:41], 0, v[188:189]
	s_mov_b32 m0, s48
	s_nop 0
	global_load_lds_dwordx4 v[214:215], off
	s_waitcnt vmcnt(8)
	s_waitcnt lgkmcnt(0)
	s_barrier
	s_setprio 1
	s_waitcnt lgkmcnt(0)
	v_mfma_f32_16x16x32_bf16 v[128:131], v[124:127], v[160:163], v[128:131]
	v_mfma_f32_16x16x32_bf16 v[120:123], v[136:139], v[160:163], v[120:123]
	v_mfma_f32_16x16x32_bf16 v[108:111], v[124:127], v[168:171], v[108:111]
	v_mfma_f32_16x16x32_bf16 v[104:107], v[136:139], v[168:171], v[104:107]
	v_mfma_f32_16x16x32_bf16 v[92:95], v[124:127], v[176:179], v[92:95]
	v_mfma_f32_16x16x32_bf16 v[88:91], v[136:139], v[176:179], v[88:91]
	v_mfma_f32_16x16x32_bf16 v[76:79], v[124:127], v[198:201], v[76:79]
	v_mfma_f32_16x16x32_bf16 v[72:75], v[136:139], v[198:201], v[72:75]
	v_mfma_f32_16x16x32_bf16 v[128:131], v[132:135], v[164:167], v[128:131]
	v_mfma_f32_16x16x32_bf16 v[120:123], v[140:143], v[164:167], v[120:123]
	v_mfma_f32_16x16x32_bf16 v[108:111], v[132:135], v[172:175], v[108:111]
	v_mfma_f32_16x16x32_bf16 v[104:107], v[140:143], v[172:175], v[104:107]
	v_mfma_f32_16x16x32_bf16 v[92:95], v[132:135], v[180:183], v[92:95]
	v_mfma_f32_16x16x32_bf16 v[88:91], v[140:143], v[180:183], v[88:91]
	v_mfma_f32_16x16x32_bf16 v[76:79], v[132:135], v[202:205], v[76:79]
	v_mfma_f32_16x16x32_bf16 v[72:75], v[140:143], v[202:205], v[72:75]
	s_setprio 0
	s_setprio 1
	v_mfma_f32_16x16x32_bf16 v[116:119], v[144:147], v[160:163], v[116:119]
	v_mfma_f32_16x16x32_bf16 v[112:115], v[152:155], v[160:163], v[112:115]
	v_mfma_f32_16x16x32_bf16 v[100:103], v[144:147], v[168:171], v[100:103]
	v_mfma_f32_16x16x32_bf16 v[96:99], v[152:155], v[168:171], v[96:99]
	v_mfma_f32_16x16x32_bf16 v[84:87], v[144:147], v[176:179], v[84:87]
	v_mfma_f32_16x16x32_bf16 v[80:83], v[152:155], v[176:179], v[80:83]
	v_mfma_f32_16x16x32_bf16 v[68:71], v[144:147], v[198:201], v[68:71]
	v_mfma_f32_16x16x32_bf16 v[64:67], v[152:155], v[198:201], v[64:67]
	v_mfma_f32_16x16x32_bf16 v[116:119], v[148:151], v[164:167], v[116:119]
	v_mfma_f32_16x16x32_bf16 v[112:115], v[156:159], v[164:167], v[112:115]
	v_mfma_f32_16x16x32_bf16 v[100:103], v[148:151], v[172:175], v[100:103]
	v_mfma_f32_16x16x32_bf16 v[96:99], v[156:159], v[172:175], v[96:99]
	v_mfma_f32_16x16x32_bf16 v[84:87], v[148:151], v[180:183], v[84:87]
	v_mfma_f32_16x16x32_bf16 v[80:83], v[156:159], v[180:183], v[80:83]
	v_mfma_f32_16x16x32_bf16 v[68:71], v[148:151], v[202:205], v[68:71]
	v_mfma_f32_16x16x32_bf16 v[64:67], v[156:159], v[202:205], v[64:67]
	s_setprio 0
	s_barrier
; #define PG8_STAGE(bufoff, gbase, voff) do { _Pragma("unroll") for (int _i = 0; _i < 2; ++_i) \
;         __builtin_amdgcn_global_load_lds((const unsigned*)((const char*)(gbase) + (voff)[_i]), (PG8_LAS unsigned*)(lds + (bufoff) + ldsw + _i * 8192), 16, 0, 0); } while (0)
; #define PG8_LDA(dst, b, h) do { _Pragma("unroll") for (int m = 0; m < 4; ++m) _Pragma("unroll") for (int k = 0; k < 2; ++k) dst[m][k] = *(const PG8_LAS bf16x8*)(lds + PG8_SA(b, h) + aoff + m * 2048 + k * 1024); } while (0)
; #define PG8_MMA(ai, bj, At, Bt) do { __builtin_amdgcn_s_setprio(1); _Pragma("unroll") for (int m = 0; m < 4; ++m) _Pragma("unroll") for (int n = 0; n < 2; ++n) _Pragma("unroll") for (int k = 0; k < 2; ++k) \
;         acc[ai][bj][m][n] = __builtin_amdgcn_mfma_f32_16x16x32_bf16(Bt[n][k], At[m][k], acc[ai][bj][m][n], 0, 0, 0); __builtin_amdgcn_s_setprio(0); } while (0)
; #define PG8_WAIT_V(n) asm volatile("s_waitcnt vmcnt(" #n ")" ::: "memory")
; #define PG8_WAIT_L(n) asm volatile("s_waitcnt lgkmcnt(" #n ")" ::: "memory")
; #define PG8_BAR __builtin_amdgcn_s_barrier()
; #define PG8_SCHED __builtin_amdgcn_sched_barrier(0)
; template <class Epi, class Sched, bool ALIGN_EPI = false, bool SP2 = false>
; __device__ __forceinline__ void gemm_phase(PG8_LAS unsigned char* lds, const Gemm g, const Sched& S, const Epi& E) {
;     ...
;             PG8_LDA(At, 1, 1); PG8_STAGE(PG8_SB(1, 0), b3, voffB); PG8_STAGE(PG8_SB(1, 1), b3 + hstep, voffB); PG8_STAGE(PG8_SA(1, 0), a3, voffA);
;             PG8_WAIT_V(8); PG8_WAIT_L(0); PG8_BAR; PG8_MMA(1, 0, At, B0); PG8_MMA(1, 1, At, B1); PG8_BAR; PG8_SCHED;
	s_add_i32 s40, s62, s44
	v_lshl_add_u64 v[206:207], v[206:207], 0, s[16:17]
	s_mov_b32 m0, s40
	ds_read_b128 v[160:163], v236 offset:49152
	ds_read_b128 v[164:167], v236 offset:50176
	ds_read_b128 v[168:171], v236 offset:51200
	ds_read_b128 v[172:175], v236 offset:52224
	ds_read_b128 v[176:179], v236 offset:53248
	ds_read_b128 v[180:183], v236 offset:54272
	ds_read_b128 v[198:201], v236 offset:55296
	ds_read_b128 v[202:205], v236 offset:56320
	global_load_lds_dwordx4 v[206:207], off
	s_add_i32 m0, s40, 0x2000
	s_add_u32 s38, s38, 0x40080
	v_lshl_add_u64 v[206:207], v[208:209], 0, s[16:17]
	s_addc_u32 s39, s39, 0
	s_add_i32 s40, s63, s44
	global_load_lds_dwordx4 v[206:207], off
	v_lshl_add_u64 v[206:207], s[38:39], 0, v[186:187]
	s_mov_b32 m0, s40
	s_nop 0
	global_load_lds_dwordx4 v[206:207], off
	v_lshl_add_u64 v[206:207], s[38:39], 0, v[190:191]
	s_add_i32 m0, s40, 0x2000
	s_nop 0
	global_load_lds_dwordx4 v[206:207], off
	v_lshl_add_u64 v[206:207], v[210:211], 0, s[16:17]
	s_mov_b32 m0, s50
	s_nop 0
	global_load_lds_dwordx4 v[206:207], off
	v_lshl_add_u64 v[206:207], v[212:213], 0, s[16:17]
	s_mov_b32 m0, s51
	s_nop 0
	global_load_lds_dwordx4 v[206:207], off
	s_waitcnt vmcnt(8)
	s_waitcnt lgkmcnt(0)
	s_barrier
	s_setprio 1
	s_waitcnt lgkmcnt(0)
	v_mfma_f32_16x16x32_bf16 v[60:63], v[124:127], v[160:163], v[60:63]
	v_mfma_f32_16x16x32_bf16 v[56:59], v[136:139], v[160:163], v[56:59]
	v_mfma_f32_16x16x32_bf16 v[44:47], v[124:127], v[168:171], v[44:47]
	v_mfma_f32_16x16x32_bf16 v[40:43], v[136:139], v[168:171], v[40:43]
	v_mfma_f32_16x16x32_bf16 v[28:31], v[124:127], v[176:179], v[28:31]
	v_mfma_f32_16x16x32_bf16 v[24:27], v[136:139], v[176:179], v[24:27]
	v_mfma_f32_16x16x32_bf16 v[12:15], v[124:127], v[198:201], v[12:15]
	v_mfma_f32_16x16x32_bf16 v[8:11], v[136:139], v[198:201], v[8:11]
	v_mfma_f32_16x16x32_bf16 v[60:63], v[132:135], v[164:167], v[60:63]
	v_mfma_f32_16x16x32_bf16 v[56:59], v[140:143], v[164:167], v[56:59]
	v_mfma_f32_16x16x32_bf16 v[44:47], v[132:135], v[172:175], v[44:47]
	v_mfma_f32_16x16x32_bf16 v[40:43], v[140:143], v[172:175], v[40:43]
	v_mfma_f32_16x16x32_bf16 v[28:31], v[132:135], v[180:183], v[28:31]
	v_mfma_f32_16x16x32_bf16 v[24:27], v[140:143], v[180:183], v[24:27]
	v_mfma_f32_16x16x32_bf16 v[12:15], v[132:135], v[202:205], v[12:15]
	v_mfma_f32_16x16x32_bf16 v[8:11], v[140:143], v[202:205], v[8:11]
	s_setprio 0
	s_setprio 1
	v_mfma_f32_16x16x32_bf16 v[52:55], v[144:147], v[160:163], v[52:55]
	v_mfma_f32_16x16x32_bf16 v[48:51], v[152:155], v[160:163], v[48:51]
	v_mfma_f32_16x16x32_bf16 v[36:39], v[144:147], v[168:171], v[36:39]
	v_mfma_f32_16x16x32_bf16 v[32:35], v[152:155], v[168:171], v[32:35]
	v_mfma_f32_16x16x32_bf16 v[20:23], v[144:147], v[176:179], v[20:23]
	v_mfma_f32_16x16x32_bf16 v[16:19], v[152:155], v[176:179], v[16:19]
	v_mfma_f32_16x16x32_bf16 v[4:7], v[144:147], v[198:201], v[4:7]
	v_mfma_f32_16x16x32_bf16 v[0:3], v[152:155], v[198:201], v[0:3]
	v_mfma_f32_16x16x32_bf16 v[52:55], v[148:151], v[164:167], v[52:55]
	v_mfma_f32_16x16x32_bf16 v[48:51], v[156:159], v[164:167], v[48:51]
	v_mfma_f32_16x16x32_bf16 v[36:39], v[148:151], v[172:175], v[36:39]
	v_mfma_f32_16x16x32_bf16 v[32:35], v[156:159], v[172:175], v[32:35]
	v_mfma_f32_16x16x32_bf16 v[20:23], v[148:151], v[180:183], v[20:23]
	v_mfma_f32_16x16x32_bf16 v[16:19], v[156:159], v[180:183], v[16:19]
	v_mfma_f32_16x16x32_bf16 v[4:7], v[148:151], v[202:205], v[4:7]
	v_mfma_f32_16x16x32_bf16 v[0:3], v[156:159], v[202:205], v[0:3]
	s_setprio 0
	s_barrier
	s_add_i32 s61, s61, 2
	s_add_u32 s36, s36, 0x100
	s_addc_u32 s37, s37, 0
	s_add_u32 s59, s59, 0x100
	s_addc_u32 s60, s60, 0
	s_cmp_gt_u32 s61, 13

; #define PG8_STAGE(bufoff, gbase, voff) do { _Pragma("unroll") for (int _i = 0; _i < 2; ++_i) \
;         __builtin_amdgcn_global_load_lds((const unsigned*)((const char*)(gbase) + (voff)[_i]), (PG8_LAS unsigned*)(lds + (bufoff) + ldsw + _i * 8192), 16, 0, 0); } while (0)
; #define PG8_LDA(dst, b, h) do { _Pragma("unroll") for (int m = 0; m < 4; ++m) _Pragma("unroll") for (int k = 0; k < 2; ++k) dst[m][k] = *(const PG8_LAS bf16x8*)(lds + PG8_SA(b, h) + aoff + m * 2048 + k * 1024); } while (0)
; #define PG8_LDB(dst, b, h) do { _Pragma("unroll") for (int n = 0; n < 2; ++n) _Pragma("unroll") for (int k = 0; k < 2; ++k) dst[n][k] = *(const PG8_LAS bf16x8*)(lds + PG8_SB(b, h) + boff + n * 2048 + k * 1024); } while (0)
; #define PG8_SCHED __builtin_amdgcn_sched_barrier(0)
;     __host__ __device__ bool next(int i, Unit& u) const {
;         if (i >= nI) return false;
;         const long L = (long)(rev ? nI - 1 - i : i) * G + c; if (L >= nwg) return false;
;         int wgid = (int)L; { const int q = nwg / NXCD, r = nwg % NXCD, xcd = wgid % NXCD, off = wgid / NXCD; wgid = (xcd < r ? xcd * (q + 1) : r * (q + 1) + (xcd - r) * q) + off; }
;         const int nig = WGM * nN, gid = wgid / nig, fm = gid * WGM, gsz = (nM - fm) < WGM ? (nM - fm) : WGM;
;         u.pm = fm + ((wgid % nig) % gsz); u.pn = (wgid % nig) / gsz; return true;
;     }
; template <class Epi, class Sched, bool ALIGN_EPI = false, bool SP2 = false>
; __device__ __forceinline__ void gemm_phase(PG8_LAS unsigned char* lds, const Gemm g, const Sched& S, const Epi& E) {
;     ...
;             PG8_LDB(B0, 0, 0); PG8_LDB(B1, 0, 1); PG8_SCHED; PG8_LDA(At, 0, 0); PG8_STAGE(PG8_SA(1, 1), a1 + hstep, voffA);
.LBB0_973:
	ds_read_b128 v[144:147], v161
	ds_read_b128 v[170:173], v161 offset:1024
	ds_read_b128 v[178:181], v161 offset:2048
	ds_read_b128 v[182:185], v161 offset:3072
	ds_read_b128 v[186:189], v165
	ds_read_b128 v[190:193], v165 offset:1024
	ds_read_b128 v[194:197], v165 offset:2048
	ds_read_b128 v[198:201], v165 offset:3072
	ds_read_b128 v[202:205], v169
	ds_read_b128 v[206:209], v169 offset:1024
	ds_read_b128 v[210:213], v169 offset:2048
	ds_read_b128 v[214:217], v169 offset:3072
	ds_read_b128 v[218:221], v169 offset:4096
	ds_read_b128 v[222:225], v169 offset:5120
	ds_read_b128 v[226:229], v169 offset:6144
	ds_read_b128 v[232:235], v169 offset:7168
	s_add_i32 s53, s19, 1
	s_cmp_ge_i32 s53, s33
	s_mov_b64 s[22:23], 0
	s_cbranch_scc1 .LBB0_976
	s_sub_i32 s19, s49, s19
	s_and_b64 s[22:23], s[4:5], exec
	s_cselect_b32 s19, s19, s53
	s_mul_hi_i32 s21, s19, s74
	s_mul_i32 s19, s19, s74
	s_add_u32 s24, s19, s2
	s_addc_u32 s25, s21, s40
	v_cmp_gt_i64_e32 vcc, s[24:25], v[142:143]
	s_mov_b64 s[22:23], 0
	s_cbranch_vccnz .LBB0_976
	s_ashr_i32 s18, s24, 31
	s_lshr_b32 s18, s18, 29
	s_add_i32 s18, s24, s18
	s_ashr_i32 s19, s18, 3
	s_and_b32 s18, s18, -8
	s_sub_i32 s18, s24, s18
	s_cmp_lt_i32 s18, 0
	s_cselect_b32 s20, s44, 0x580
	s_mul_i32 s18, s18, s20
	s_add_i32 s18, s18, s19
	s_mul_hi_i32 s19, s18, 0x2e8ba2e9
	s_lshr_b32 s20, s19, 31
	s_ashr_i32 s19, s19, 5
	s_add_i32 s19, s19, s20
	s_lshl_b32 s20, s19, 3
	s_sub_i32 s21, 0x200, s20
	s_min_i32 s21, s21, 8
	s_abs_i32 s22, s21
	v_cvt_f32_u32_e32 v0, s22
	s_sub_i32 s24, 0, s22
	s_mulk_i32 s19, 0xb0
	s_sub_i32 s19, s18, s19
	v_rcp_iflag_f32_e32 v0, v0
	s_abs_i32 s18, s19
	s_xor_b32 s23, s19, s21
	s_ashr_i32 s23, s23, 31
	v_mul_f32_e32 v0, 0x4f7ffffe, v0
	v_cvt_u32_f32_e32 v0, v0
	s_nop 0
	v_readfirstlane_b32 s25, v0
	s_mul_i32 s24, s24, s25
	s_mul_hi_u32 s24, s25, s24
	s_add_i32 s25, s25, s24
	s_mul_hi_u32 s24, s18, s25
	s_mul_i32 s25, s24, s22
	s_sub_i32 s18, s18, s25
	s_add_i32 s26, s24, 1
	s_sub_i32 s25, s18, s22
	s_cmp_ge_u32 s18, s22
	s_cselect_b32 s24, s26, s24
	s_cselect_b32 s18, s25, s18
	s_add_i32 s25, s24, 1
	s_cmp_ge_u32 s18, s22
	s_cselect_b32 s18, s25, s24
	s_xor_b32 s18, s18, s23
	s_sub_i32 s18, s18, s23
	s_mul_i32 s21, s18, s21
	s_sub_i32 s19, s19, s21
	s_add_i32 s20, s20, s19
	s_mov_b64 s[22:23], -1
; #define PG8_STAGE(bufoff, gbase, voff) do { _Pragma("unroll") for (int _i = 0; _i < 2; ++_i) \
;         __builtin_amdgcn_global_load_lds((const unsigned*)((const char*)(gbase) + (voff)[_i]), (PG8_LAS unsigned*)(lds + (bufoff) + ldsw + _i * 8192), 16, 0, 0); } while (0)
; #define PG8_LDA(dst, b, h) do { _Pragma("unroll") for (int m = 0; m < 4; ++m) _Pragma("unroll") for (int k = 0; k < 2; ++k) dst[m][k] = *(const PG8_LAS bf16x8*)(lds + PG8_SA(b, h) + aoff + m * 2048 + k * 1024); } while (0)
; #define PG8_LDB(dst, b, h) do { _Pragma("unroll") for (int n = 0; n < 2; ++n) _Pragma("unroll") for (int k = 0; k < 2; ++k) dst[n][k] = *(const PG8_LAS bf16x8*)(lds + PG8_SB(b, h) + boff + n * 2048 + k * 1024); } while (0)
; #define PG8_WAIT_V(n) asm volatile("s_waitcnt vmcnt(" #n ")" ::: "memory")
; #define PG8_WAIT_L(n) asm volatile("s_waitcnt lgkmcnt(" #n ")" ::: "memory")
; #define PG8_BAR __builtin_amdgcn_s_barrier()
; #define PG8_SCHED __builtin_amdgcn_sched_barrier(0)
; template <class Epi, class Sched, bool ALIGN_EPI = false, bool SP2 = false>
; __device__ __forceinline__ void gemm_phase(PG8_LAS unsigned char* lds, const Gemm g, const Sched& S, const Epi& E) {
;     ...
;         const char* nA = has_next ? (const char*)g.A + (size_t)nxt.pm * tstep : cA; const char* nB = has_next ? (const char*)g.Bt + (size_t)nxt.pn * tstep : cB;
;         for (int t = 0; t < nt; t += 2) {
;             const bool last = (t == nt - 2);
;             const char* a1 = cA + (size_t)(t + 1) * kstep;
;             const char* a2 = last ? nA : cA + (size_t)(t + 2) * kstep; const char* b2 = last ? nB : cB + (size_t)(t + 2) * kstep;
;             const char* a3 = a2 + kstep; const char* b3 = b2 + kstep;
;             if (last && has_next) S.a_ready(nxt);
;             if constexpr (SP2) {
;             PG8_LDB(B0, 0, 0); PG8_LDB(B1, 0, 1); PG8_SCHED; PG8_LDA(At, 0, 0); PG8_STAGE(PG8_SA(1, 1), a1 + hstep, voffA);
;             PG8_WAIT_V(8); PG8_WAIT_L(0); PG8_BAR; PG8_MMA(0, 0, At, B0); PG8_MMA(0, 1, At, B1); PG8_BAR; PG8_SCHED;
;             PG8_LDA(At, 0, 1); PG8_STAGE(PG8_SB(0, 0), b2, voffB); PG8_STAGE(PG8_SB(0, 1), b2 + hstep, voffB); PG8_STAGE(PG8_SA(0, 0), a2, voffA);
;             PG8_WAIT_V(8); PG8_WAIT_L(0); PG8_BAR; PG8_MMA(1, 0, At, B0); PG8_MMA(1, 1, At, B1); PG8_BAR; PG8_SCHED;
.LBB0_976:
	s_ashr_i32 s21, s20, 31
	s_lshl_b64 s[24:25], s[20:21], 19
	s_add_u32 s24, s70, s24
	s_addc_u32 s25, s71, s25
	s_and_b64 s[26:27], s[22:23], exec
	s_cselect_b32 s21, s25, s39
	s_cselect_b32 s54, s24, s38
	s_ashr_i32 s19, s18, 31
	s_lshl_b64 s[26:27], s[18:19], 19
	s_add_u32 s26, s41, s26
	s_addc_u32 s27, s42, s27
	s_and_b64 s[34:35], s[22:23], exec
	s_cselect_b32 s19, s27, s37
	s_cselect_b32 s55, s26, s36
	s_add_u32 s34, s38, 0x40080
	s_addc_u32 s35, s39, 0
	s_add_u32 s56, s36, 0x100
	s_addc_u32 s57, s37, 0
	s_mov_b32 s58, -2
	s_add_u32 s36, s34, 0xfffc0080
	s_addc_u32 s37, s35, -1
	s_cmp_eq_u32 s58, 12
	s_cselect_b32 s39, s21, s37
	s_cselect_b32 s38, s54, s36
	s_cselect_b32 s37, s19, s57
	s_cselect_b32 s36, s55, s56
	v_lshl_add_u64 v[150:151], s[34:35], 0, v[138:139]
	s_add_i32 m0, s29, 0xc000
	global_load_lds_dwordx4 v[150:151], off
	v_lshl_add_u64 v[150:151], s[34:35], 0, v[140:141]
	s_add_i32 m0, s29, 0xe000
	s_nop 0
	global_load_lds_dwordx4 v[150:151], off
	s_waitcnt vmcnt(8)
	s_waitcnt lgkmcnt(0)
	s_barrier
	s_setprio 1
	s_waitcnt lgkmcnt(0)
	v_mfma_f32_16x16x32_bf16 v[124:127], v[144:147], v[202:205], 0
	v_mfma_f32_16x16x32_bf16 v[116:119], v[178:181], v[202:205], 0
	v_mfma_f32_16x16x32_bf16 v[108:111], v[144:147], v[210:213], 0
	v_mfma_f32_16x16x32_bf16 v[100:103], v[178:181], v[210:213], 0
	v_mfma_f32_16x16x32_bf16 v[92:95], v[144:147], v[218:221], 0
	v_mfma_f32_16x16x32_bf16 v[84:87], v[178:181], v[218:221], 0
	v_mfma_f32_16x16x32_bf16 v[76:79], v[144:147], v[226:229], 0
	v_mfma_f32_16x16x32_bf16 v[68:71], v[178:181], v[226:229], 0
	v_mfma_f32_16x16x32_bf16 v[124:127], v[170:173], v[206:209], v[124:127]
	v_mfma_f32_16x16x32_bf16 v[116:119], v[182:185], v[206:209], v[116:119]
	v_mfma_f32_16x16x32_bf16 v[108:111], v[170:173], v[214:217], v[108:111]
	v_mfma_f32_16x16x32_bf16 v[100:103], v[182:185], v[214:217], v[100:103]
	v_mfma_f32_16x16x32_bf16 v[92:95], v[170:173], v[222:225], v[92:95]
	v_mfma_f32_16x16x32_bf16 v[84:87], v[182:185], v[222:225], v[84:87]
	v_mfma_f32_16x16x32_bf16 v[76:79], v[170:173], v[232:235], v[76:79]
	v_mfma_f32_16x16x32_bf16 v[68:71], v[182:185], v[232:235], v[68:71]
	s_setprio 0
	s_setprio 1
	v_mfma_f32_16x16x32_bf16 v[120:123], v[186:189], v[202:205], 0
	v_mfma_f32_16x16x32_bf16 v[112:115], v[194:197], v[202:205], 0
	v_mfma_f32_16x16x32_bf16 v[104:107], v[186:189], v[210:213], 0
	v_mfma_f32_16x16x32_bf16 v[96:99], v[194:197], v[210:213], 0
	v_mfma_f32_16x16x32_bf16 v[88:91], v[186:189], v[218:221], 0
	v_mfma_f32_16x16x32_bf16 v[80:83], v[194:197], v[218:221], 0
	v_mfma_f32_16x16x32_bf16 v[72:75], v[186:189], v[226:229], 0
	v_mfma_f32_16x16x32_bf16 v[64:67], v[194:197], v[226:229], 0
	v_mfma_f32_16x16x32_bf16 v[120:123], v[190:193], v[206:209], v[120:123]
	v_mfma_f32_16x16x32_bf16 v[112:115], v[198:201], v[206:209], v[112:115]
	v_mfma_f32_16x16x32_bf16 v[104:107], v[190:193], v[214:217], v[104:107]
	v_mfma_f32_16x16x32_bf16 v[96:99], v[198:201], v[214:217], v[96:99]
	v_mfma_f32_16x16x32_bf16 v[88:91], v[190:193], v[222:225], v[88:91]
	v_mfma_f32_16x16x32_bf16 v[80:83], v[198:201], v[222:225], v[80:83]
	v_mfma_f32_16x16x32_bf16 v[72:75], v[190:193], v[232:235], v[72:75]
	v_mfma_f32_16x16x32_bf16 v[64:67], v[198:201], v[232:235], v[64:67]
	s_setprio 0
	s_barrier
	s_add_i32 s59, s50, s43
	v_lshl_add_u64 v[150:151], s[36:37], 0, v[130:131]
	s_mov_b32 m0, s59
	ds_read_b128 v[202:205], v169 offset:16384
	ds_read_b128 v[206:209], v169 offset:17408
	ds_read_b128 v[210:213], v169 offset:18432
	ds_read_b128 v[214:217], v169 offset:19456
	ds_read_b128 v[218:221], v169 offset:20480
	ds_read_b128 v[222:225], v169 offset:21504
	ds_read_b128 v[226:229], v169 offset:22528
	ds_read_b128 v[232:235], v169 offset:23552
	global_load_lds_dwordx4 v[150:151], off
	s_add_i32 m0, s59, 0x2000
	s_add_u32 s60, s36, 0x40000
	v_lshl_add_u64 v[154:155], s[36:37], 0, v[134:135]
	s_addc_u32 s61, s37, 0
	s_add_i32 s59, s51, s43
	global_load_lds_dwordx4 v[154:155], off
	v_lshl_add_u64 v[158:159], s[60:61], 0, v[130:131]
	s_mov_b32 m0, s59
	v_lshl_add_u64 v[162:163], s[38:39], 0, v[132:133]
	global_load_lds_dwordx4 v[158:159], off
	v_lshl_add_u64 v[158:159], s[60:61], 0, v[134:135]
	s_add_i32 m0, s59, 0x2000
	s_nop 0
	global_load_lds_dwordx4 v[158:159], off
	v_lshl_add_u64 v[158:159], s[38:39], 0, v[128:129]
	s_mov_b32 m0, s29
	s_nop 0
	global_load_lds_dwordx4 v[158:159], off
	s_mov_b32 m0, s31
	s_nop 0
	global_load_lds_dwordx4 v[162:163], off
	s_cmp_lg_i32 s58, -2
	s_cbranch_scc1 .Lrsb_a_pl
	v_lshrrev_b32_e32 v250, 6, v230
	v_lshlrev_b32_e32 v250, 11, v250
	v_and_b32_e32 v251, 63, v230
	v_lshl_or_b32 v250, v251, 4, v250
	v_lshl_add_u32 v250, s30, 14, v250
	v_readfirstlane_b32 s98, v230
	s_lshr_b32 s98, s98, 6
	s_lshl_b32 s98, s98, 11
	s_add_i32 m0, s98, 0x20000
	s_add_u32 s100, s70, 0x3f000000
	s_addc_u32 s101, s71, 0
	global_load_lds_dwordx4 v250, s[100:101]
	global_load_lds_dwordx4 v250, s[100:101] offset:1024
	s_waitcnt vmcnt(10)
	s_branch .Lrsb_b_pl

; #define PG8_STAGE(bufoff, gbase, voff) do { _Pragma("unroll") for (int _i = 0; _i < 2; ++_i) \
;         __builtin_amdgcn_global_load_lds((const unsigned*)((const char*)(gbase) + (voff)[_i]), (PG8_LAS unsigned*)(lds + (bufoff) + ldsw + _i * 8192), 16, 0, 0); } while (0)
; #define PG8_LDA(dst, b, h) do { _Pragma("unroll") for (int m = 0; m < 4; ++m) _Pragma("unroll") for (int k = 0; k < 2; ++k) dst[m][k] = *(const PG8_LAS bf16x8*)(lds + PG8_SA(b, h) + aoff + m * 2048 + k * 1024); } while (0)
; #define PG8_LDB(dst, b, h) do { _Pragma("unroll") for (int n = 0; n < 2; ++n) _Pragma("unroll") for (int k = 0; k < 2; ++k) dst[n][k] = *(const PG8_LAS bf16x8*)(lds + PG8_SB(b, h) + boff + n * 2048 + k * 1024); } while (0)
; #define PG8_SCHED __builtin_amdgcn_sched_barrier(0)
;     __host__ __device__ bool next(int i, Unit& u) const {
;         if (i >= nI) return false;
;         const long L = (long)(rev ? nI - 1 - i : i) * G + c; if (L >= nwg) return false;
;         int wgid = (int)L; { const int q = nwg / NXCD, r = nwg % NXCD, xcd = wgid % NXCD, off = wgid / NXCD; wgid = (xcd < r ? xcd * (q + 1) : r * (q + 1) + (xcd - r) * q) + off; }
;         const int nig = WGM * nN, gid = wgid / nig, fm = gid * WGM, gsz = (nM - fm) < WGM ? (nM - fm) : WGM;
;         u.pm = fm + ((wgid % nig) % gsz); u.pn = (wgid % nig) / gsz; return true;
;     }
; template <class Epi, class Sched, bool ALIGN_EPI = false, bool SP2 = false>
; __device__ __forceinline__ void gemm_phase(PG8_LAS unsigned char* lds, const Gemm g, const Sched& S, const Epi& E) {
;     ...
;             PG8_LDB(B0, 0, 0); PG8_LDB(B1, 0, 1); PG8_SCHED; PG8_LDA(At, 0, 0); PG8_STAGE(PG8_SA(1, 1), a1 + hstep, voffA);
.LBB0_1050:
	ds_read_b128 v[128:131], v189
	ds_read_b128 v[132:135], v189 offset:1024
	ds_read_b128 v[136:139], v189 offset:2048
	ds_read_b128 v[140:143], v189 offset:3072
	ds_read_b128 v[144:147], v190
	ds_read_b128 v[148:151], v190 offset:1024
	ds_read_b128 v[152:155], v190 offset:2048
	ds_read_b128 v[156:159], v190 offset:3072
	ds_read_b128 v[174:177], v191
	ds_read_b128 v[178:181], v191 offset:1024
	ds_read_b128 v[182:185], v191 offset:2048
	ds_read_b128 v[192:195], v191 offset:3072
	ds_read_b128 v[196:199], v191 offset:4096
	ds_read_b128 v[200:203], v191 offset:5120
	ds_read_b128 v[204:207], v191 offset:6144
	ds_read_b128 v[208:211], v191 offset:7168
	s_add_i32 s30, s30, 1
	s_cmp_ge_i32 s30, s3
	s_mov_b64 s[12:13], 0
	s_cbranch_scc1 .LBB0_1057
	s_mul_i32 s0, s30, s31
	s_mul_hi_u32 s1, s30, s74
	s_add_i32 s1, s1, s0
	s_mul_i32 s0, s30, s74
	s_add_u32 s0, s0, s2
	s_addc_u32 s1, s1, s22
	v_cmp_gt_i64_e32 vcc, s[0:1], v[172:173]
	s_cbranch_vccnz .LBB0_1057
	s_ashr_i32 s1, s0, 31
	s_lshr_b32 s1, s1, 29
	s_add_i32 s12, s0, s1
	s_and_b32 s1, s12, -8
	s_sub_i32 s13, s0, s1
	s_cmp_gt_i32 s13, -1
	s_mov_b64 s[0:1], -1
	s_cbranch_scc0 .LBB0_1054
	s_lshl_b32 s14, s13, 8
	s_mov_b64 s[0:1], 0

; #define PG8_STAGE(bufoff, gbase, voff) do { _Pragma("unroll") for (int _i = 0; _i < 2; ++_i) \
;         __builtin_amdgcn_global_load_lds((const unsigned*)((const char*)(gbase) + (voff)[_i]), (PG8_LAS unsigned*)(lds + (bufoff) + ldsw + _i * 8192), 16, 0, 0); } while (0)
; #define PG8_LDA(dst, b, h) do { _Pragma("unroll") for (int m = 0; m < 4; ++m) _Pragma("unroll") for (int k = 0; k < 2; ++k) dst[m][k] = *(const PG8_LAS bf16x8*)(lds + PG8_SA(b, h) + aoff + m * 2048 + k * 1024); } while (0)
; #define PG8_LDB(dst, b, h) do { _Pragma("unroll") for (int n = 0; n < 2; ++n) _Pragma("unroll") for (int k = 0; k < 2; ++k) dst[n][k] = *(const PG8_LAS bf16x8*)(lds + PG8_SB(b, h) + boff + n * 2048 + k * 1024); } while (0)
; #define PG8_MMA(ai, bj, At, Bt) do { __builtin_amdgcn_s_setprio(1); _Pragma("unroll") for (int m = 0; m < 4; ++m) _Pragma("unroll") for (int n = 0; n < 2; ++n) _Pragma("unroll") for (int k = 0; k < 2; ++k) \
;         acc[ai][bj][m][n] = __builtin_amdgcn_mfma_f32_16x16x32_bf16(Bt[n][k], At[m][k], acc[ai][bj][m][n], 0, 0, 0); __builtin_amdgcn_s_setprio(0); } while (0)
; #define PG8_WAIT_V(n) asm volatile("s_waitcnt vmcnt(" #n ")" ::: "memory")
; #define PG8_WAIT_L(n) asm volatile("s_waitcnt lgkmcnt(" #n ")" ::: "memory")
; #define PG8_BAR __builtin_amdgcn_s_barrier()
; #define PG8_SCHED __builtin_amdgcn_sched_barrier(0)
; template <class Epi, class Sched, bool ALIGN_EPI = false, bool SP2 = false>
; __device__ __forceinline__ void gemm_phase(PG8_LAS unsigned char* lds, const Gemm g, const Sched& S, const Epi& E) {
;     ...
;             const char* a2 = last ? nA : cA + (size_t)(t + 2) * kstep; const char* b2 = last ? nB : cB + (size_t)(t + 2) * kstep;
;             const char* a3 = a2 + kstep; const char* b3 = b2 + kstep;
;             if (last && has_next) S.a_ready(nxt);
;             if constexpr (SP2) {
;             PG8_LDB(B0, 0, 0); PG8_LDB(B1, 0, 1); PG8_SCHED; PG8_LDA(At, 0, 0); PG8_STAGE(PG8_SA(1, 1), a1 + hstep, voffA);
;             PG8_WAIT_V(8); PG8_WAIT_L(0); PG8_BAR; PG8_MMA(0, 0, At, B0); PG8_MMA(0, 1, At, B1); PG8_BAR; PG8_SCHED;
;             PG8_LDA(At, 0, 1); PG8_STAGE(PG8_SB(0, 0), b2, voffB); PG8_STAGE(PG8_SB(0, 1), b2 + hstep, voffB); PG8_STAGE(PG8_SA(0, 0), a2, voffA);
;             PG8_WAIT_V(8); PG8_WAIT_L(0); PG8_BAR; PG8_MMA(1, 0, At, B0); PG8_MMA(1, 1, At, B1); PG8_BAR; PG8_SCHED;
.LBB0_1061:
	s_add_u32 s16, s16, 0xb0080
	s_addc_u32 s17, s17, 0
	s_add_u32 s41, s18, 0x100
	s_addc_u32 s42, s19, 0
	s_mov_b32 s43, -2
	s_add_u32 s18, s16, 0xfff50080
	s_addc_u32 s19, s17, -1
	s_cmp_eq_u32 s43, 40
	s_cselect_b32 s21, s13, s19
	s_cselect_b32 s20, s12, s18
	s_cselect_b32 s19, s15, s42
	s_cselect_b32 s18, s14, s41
	v_lshl_add_u64 v[212:213], s[16:17], 0, v[168:169]
	s_add_i32 m0, s26, 0xc000
	global_load_lds_dwordx4 v[212:213], off
	v_lshl_add_u64 v[212:213], s[16:17], 0, v[170:171]
	s_add_i32 m0, s26, 0xe000
	s_nop 0
	global_load_lds_dwordx4 v[212:213], off
	s_waitcnt vmcnt(8)
	s_waitcnt lgkmcnt(0)
	s_barrier
	s_setprio 1
	s_waitcnt lgkmcnt(0)
	v_mfma_f32_16x16x32_bf16 v[124:127], v[128:131], v[174:177], 0
	v_mfma_f32_16x16x32_bf16 v[120:123], v[136:139], v[174:177], 0
	v_mfma_f32_16x16x32_bf16 v[116:119], v[128:131], v[182:185], 0
	v_mfma_f32_16x16x32_bf16 v[104:107], v[136:139], v[182:185], 0
	v_mfma_f32_16x16x32_bf16 v[96:99], v[128:131], v[196:199], 0
	v_mfma_f32_16x16x32_bf16 v[88:91], v[136:139], v[196:199], 0
	v_mfma_f32_16x16x32_bf16 v[80:83], v[128:131], v[204:207], 0
	v_mfma_f32_16x16x32_bf16 v[72:75], v[136:139], v[204:207], 0
	v_mfma_f32_16x16x32_bf16 v[124:127], v[132:135], v[178:181], v[124:127]
	v_mfma_f32_16x16x32_bf16 v[120:123], v[140:143], v[178:181], v[120:123]
	v_mfma_f32_16x16x32_bf16 v[116:119], v[132:135], v[192:195], v[116:119]
	v_mfma_f32_16x16x32_bf16 v[104:107], v[140:143], v[192:195], v[104:107]
	v_mfma_f32_16x16x32_bf16 v[96:99], v[132:135], v[200:203], v[96:99]
	v_mfma_f32_16x16x32_bf16 v[88:91], v[140:143], v[200:203], v[88:91]
	v_mfma_f32_16x16x32_bf16 v[80:83], v[132:135], v[208:211], v[80:83]
	v_mfma_f32_16x16x32_bf16 v[72:75], v[140:143], v[208:211], v[72:75]
	s_setprio 0
	s_setprio 1
	v_mfma_f32_16x16x32_bf16 v[112:115], v[144:147], v[174:177], 0
	v_mfma_f32_16x16x32_bf16 v[108:111], v[152:155], v[174:177], 0
	v_mfma_f32_16x16x32_bf16 v[100:103], v[144:147], v[182:185], 0
	v_mfma_f32_16x16x32_bf16 v[92:95], v[152:155], v[182:185], 0
	v_mfma_f32_16x16x32_bf16 v[84:87], v[144:147], v[196:199], 0
	v_mfma_f32_16x16x32_bf16 v[76:79], v[152:155], v[196:199], 0
	v_mfma_f32_16x16x32_bf16 v[68:71], v[144:147], v[204:207], 0
	v_mfma_f32_16x16x32_bf16 v[64:67], v[152:155], v[204:207], 0
	v_mfma_f32_16x16x32_bf16 v[112:115], v[148:151], v[178:181], v[112:115]
	v_mfma_f32_16x16x32_bf16 v[108:111], v[156:159], v[178:181], v[108:111]
	v_mfma_f32_16x16x32_bf16 v[100:103], v[148:151], v[192:195], v[100:103]
	v_mfma_f32_16x16x32_bf16 v[92:95], v[156:159], v[192:195], v[92:95]
	v_mfma_f32_16x16x32_bf16 v[84:87], v[148:151], v[200:203], v[84:87]
	v_mfma_f32_16x16x32_bf16 v[76:79], v[156:159], v[200:203], v[76:79]
	v_mfma_f32_16x16x32_bf16 v[68:71], v[148:151], v[208:211], v[68:71]
	v_mfma_f32_16x16x32_bf16 v[64:67], v[156:159], v[208:211], v[64:67]
	s_setprio 0
	s_barrier
	s_add_i32 s44, s35, s25
	v_lshl_add_u64 v[212:213], s[18:19], 0, v[162:163]
	s_mov_b32 m0, s44
	ds_read_b128 v[174:177], v191 offset:16384
	ds_read_b128 v[178:181], v191 offset:17408
	ds_read_b128 v[182:185], v191 offset:18432
	ds_read_b128 v[192:195], v191 offset:19456
	ds_read_b128 v[196:199], v191 offset:20480
	ds_read_b128 v[200:203], v191 offset:21504
	ds_read_b128 v[204:207], v191 offset:22528
	ds_read_b128 v[208:211], v191 offset:23552
	global_load_lds_dwordx4 v[212:213], off
	s_add_i32 m0, s44, 0x2000
	s_add_u32 s44, s18, 0xb0000
	v_lshl_add_u64 v[214:215], s[18:19], 0, v[166:167]
	s_addc_u32 s45, s19, 0
	s_add_i32 s46, s36, s25
	global_load_lds_dwordx4 v[214:215], off
	v_lshl_add_u64 v[216:217], s[44:45], 0, v[162:163]
	s_mov_b32 m0, s46
	v_lshl_add_u64 v[218:219], s[20:21], 0, v[164:165]
	global_load_lds_dwordx4 v[216:217], off
	v_lshl_add_u64 v[216:217], s[44:45], 0, v[166:167]
	s_add_i32 m0, s46, 0x2000
	s_nop 0
	global_load_lds_dwordx4 v[216:217], off
	v_lshl_add_u64 v[216:217], s[20:21], 0, v[160:161]
	s_mov_b32 m0, s26
	s_nop 0
	global_load_lds_dwordx4 v[216:217], off
	s_mov_b32 m0, s27
	s_nop 0
	global_load_lds_dwordx4 v[218:219], off
	s_waitcnt vmcnt(8)
	s_waitcnt lgkmcnt(0)
	s_barrier
	s_setprio 1
	s_waitcnt lgkmcnt(0)
	v_mfma_f32_16x16x32_bf16 v[60:63], v[128:131], v[174:177], 0
	v_mfma_f32_16x16x32_bf16 v[56:59], v[136:139], v[174:177], 0
	v_mfma_f32_16x16x32_bf16 v[48:51], v[128:131], v[182:185], 0
	v_mfma_f32_16x16x32_bf16 v[40:43], v[136:139], v[182:185], 0
	v_mfma_f32_16x16x32_bf16 v[32:35], v[128:131], v[196:199], 0
	v_mfma_f32_16x16x32_bf16 v[24:27], v[136:139], v[196:199], 0
	v_mfma_f32_16x16x32_bf16 v[16:19], v[128:131], v[204:207], 0
	v_mfma_f32_16x16x32_bf16 v[8:11], v[136:139], v[204:207], 0
	v_mfma_f32_16x16x32_bf16 v[60:63], v[132:135], v[178:181], v[60:63]
	v_mfma_f32_16x16x32_bf16 v[56:59], v[140:143], v[178:181], v[56:59]
	v_mfma_f32_16x16x32_bf16 v[48:51], v[132:135], v[192:195], v[48:51]
	v_mfma_f32_16x16x32_bf16 v[40:43], v[140:143], v[192:195], v[40:43]
	v_mfma_f32_16x16x32_bf16 v[32:35], v[132:135], v[200:203], v[32:35]
	v_mfma_f32_16x16x32_bf16 v[24:27], v[140:143], v[200:203], v[24:27]
	v_mfma_f32_16x16x32_bf16 v[16:19], v[132:135], v[208:211], v[16:19]
	v_mfma_f32_16x16x32_bf16 v[8:11], v[140:143], v[208:211], v[8:11]
	s_setprio 0
	s_setprio 1
	v_mfma_f32_16x16x32_bf16 v[52:55], v[144:147], v[174:177], 0
	v_mfma_f32_16x16x32_bf16 v[44:47], v[152:155], v[174:177], 0
	v_mfma_f32_16x16x32_bf16 v[36:39], v[144:147], v[182:185], 0
	v_mfma_f32_16x16x32_bf16 v[28:31], v[152:155], v[182:185], 0
	v_mfma_f32_16x16x32_bf16 v[20:23], v[144:147], v[196:199], 0
	v_mfma_f32_16x16x32_bf16 v[12:15], v[152:155], v[196:199], 0
	v_mfma_f32_16x16x32_bf16 v[4:7], v[144:147], v[204:207], 0
	v_mfma_f32_16x16x32_bf16 v[0:3], v[152:155], v[204:207], 0
	v_mfma_f32_16x16x32_bf16 v[52:55], v[148:151], v[178:181], v[52:55]
	v_mfma_f32_16x16x32_bf16 v[44:47], v[156:159], v[178:181], v[44:47]
	v_mfma_f32_16x16x32_bf16 v[36:39], v[148:151], v[192:195], v[36:39]
	v_mfma_f32_16x16x32_bf16 v[28:31], v[156:159], v[192:195], v[28:31]
	v_mfma_f32_16x16x32_bf16 v[20:23], v[148:151], v[200:203], v[20:23]
	v_mfma_f32_16x16x32_bf16 v[12:15], v[156:159], v[200:203], v[12:15]
	v_mfma_f32_16x16x32_bf16 v[4:7], v[148:151], v[208:211], v[4:7]
	v_mfma_f32_16x16x32_bf16 v[0:3], v[156:159], v[208:211], v[0:3]
	s_setprio 0
	s_barrier
; #define PG8_STAGE(bufoff, gbase, voff) do { _Pragma("unroll") for (int _i = 0; _i < 2; ++_i) \
;         __builtin_amdgcn_global_load_lds((const unsigned*)((const char*)(gbase) + (voff)[_i]), (PG8_LAS unsigned*)(lds + (bufoff) + ldsw + _i * 8192), 16, 0, 0); } while (0)
; #define PG8_LDA(dst, b, h) do { _Pragma("unroll") for (int m = 0; m < 4; ++m) _Pragma("unroll") for (int k = 0; k < 2; ++k) dst[m][k] = *(const PG8_LAS bf16x8*)(lds + PG8_SA(b, h) + aoff + m * 2048 + k * 1024); } while (0)
; #define PG8_LDB(dst, b, h) do { _Pragma("unroll") for (int n = 0; n < 2; ++n) _Pragma("unroll") for (int k = 0; k < 2; ++k) dst[n][k] = *(const PG8_LAS bf16x8*)(lds + PG8_SB(b, h) + boff + n * 2048 + k * 1024); } while (0)
; #define PG8_MMA(ai, bj, At, Bt) do { __builtin_amdgcn_s_setprio(1); _Pragma("unroll") for (int m = 0; m < 4; ++m) _Pragma("unroll") for (int n = 0; n < 2; ++n) _Pragma("unroll") for (int k = 0; k < 2; ++k) \
;         acc[ai][bj][m][n] = __builtin_amdgcn_mfma_f32_16x16x32_bf16(Bt[n][k], At[m][k], acc[ai][bj][m][n], 0, 0, 0); __builtin_amdgcn_s_setprio(0); } while (0)
; #define PG8_WAIT_V(n) asm volatile("s_waitcnt vmcnt(" #n ")" ::: "memory")
; #define PG8_WAIT_L(n) asm volatile("s_waitcnt lgkmcnt(" #n ")" ::: "memory")
; #define PG8_BAR __builtin_amdgcn_s_barrier()
; #define PG8_SCHED __builtin_amdgcn_sched_barrier(0)
; template <class Epi, class Sched, bool ALIGN_EPI = false, bool SP2 = false>
; __device__ __forceinline__ void gemm_phase(PG8_LAS unsigned char* lds, const Gemm g, const Sched& S, const Epi& E) {
;     ...
;             PG8_LDB(B0, 1, 0); PG8_LDB(B1, 1, 1); PG8_SCHED; PG8_LDA(At, 1, 0); PG8_STAGE(PG8_SA(0, 1), a2 + hstep, voffA);
;             PG8_WAIT_V(8); PG8_WAIT_L(0); PG8_BAR; PG8_MMA(0, 0, At, B0); PG8_MMA(0, 1, At, B1); PG8_BAR; PG8_SCHED;
	s_add_i32 s44, 0, 0x18000
	s_add_i32 s45, 0, 0x1c000
	v_add_u32_e32 v140, s44, v187
	v_add_u32_e32 v156, s45, v187
	ds_read_b128 v[128:131], v140
	ds_read_b128 v[132:135], v140 offset:1024
	ds_read_b128 v[136:139], v140 offset:2048
	ds_read_b128 v[140:143], v140 offset:3072
	ds_read_b128 v[144:147], v156
	ds_read_b128 v[148:151], v156 offset:1024
	ds_read_b128 v[152:155], v156 offset:2048
	ds_read_b128 v[156:159], v156 offset:3072
	s_add_u32 s20, s20, 0xb0000
	s_addc_u32 s21, s21, 0
	s_mov_b32 m0, s28
	v_lshl_add_u64 v[220:221], s[20:21], 0, v[160:161]
	ds_read_b128 v[174:177], v191 offset:32768
	ds_read_b128 v[178:181], v191 offset:33792
	ds_read_b128 v[182:185], v191 offset:34816
	ds_read_b128 v[192:195], v191 offset:35840
	ds_read_b128 v[196:199], v191 offset:36864
	ds_read_b128 v[200:203], v191 offset:37888
	ds_read_b128 v[204:207], v191 offset:38912
	ds_read_b128 v[208:211], v191 offset:39936
	global_load_lds_dwordx4 v[220:221], off
	v_lshl_add_u64 v[220:221], s[20:21], 0, v[164:165]
	s_mov_b32 m0, s29
	s_nop 0
	global_load_lds_dwordx4 v[220:221], off
	s_waitcnt vmcnt(8)
	s_waitcnt lgkmcnt(0)
	s_barrier
	s_setprio 1
	s_waitcnt lgkmcnt(0)
	v_mfma_f32_16x16x32_bf16 v[124:127], v[128:131], v[174:177], v[124:127]
	v_mfma_f32_16x16x32_bf16 v[120:123], v[136:139], v[174:177], v[120:123]
	v_mfma_f32_16x16x32_bf16 v[116:119], v[128:131], v[182:185], v[116:119]
	v_mfma_f32_16x16x32_bf16 v[104:107], v[136:139], v[182:185], v[104:107]
	v_mfma_f32_16x16x32_bf16 v[96:99], v[128:131], v[196:199], v[96:99]
	v_mfma_f32_16x16x32_bf16 v[88:91], v[136:139], v[196:199], v[88:91]
	v_mfma_f32_16x16x32_bf16 v[80:83], v[128:131], v[204:207], v[80:83]
	v_mfma_f32_16x16x32_bf16 v[72:75], v[136:139], v[204:207], v[72:75]
	v_mfma_f32_16x16x32_bf16 v[124:127], v[132:135], v[178:181], v[124:127]
	v_mfma_f32_16x16x32_bf16 v[120:123], v[140:143], v[178:181], v[120:123]
	v_mfma_f32_16x16x32_bf16 v[116:119], v[132:135], v[192:195], v[116:119]
	v_mfma_f32_16x16x32_bf16 v[104:107], v[140:143], v[192:195], v[104:107]
	v_mfma_f32_16x16x32_bf16 v[96:99], v[132:135], v[200:203], v[96:99]
	v_mfma_f32_16x16x32_bf16 v[88:91], v[140:143], v[200:203], v[88:91]
	v_mfma_f32_16x16x32_bf16 v[80:83], v[132:135], v[208:211], v[80:83]
	v_mfma_f32_16x16x32_bf16 v[72:75], v[140:143], v[208:211], v[72:75]
	s_setprio 0
	s_setprio 1
	v_mfma_f32_16x16x32_bf16 v[112:115], v[144:147], v[174:177], v[112:115]
	v_mfma_f32_16x16x32_bf16 v[108:111], v[152:155], v[174:177], v[108:111]
	v_mfma_f32_16x16x32_bf16 v[100:103], v[144:147], v[182:185], v[100:103]
	v_mfma_f32_16x16x32_bf16 v[92:95], v[152:155], v[182:185], v[92:95]
	v_mfma_f32_16x16x32_bf16 v[84:87], v[144:147], v[196:199], v[84:87]
	v_mfma_f32_16x16x32_bf16 v[76:79], v[152:155], v[196:199], v[76:79]
	v_mfma_f32_16x16x32_bf16 v[68:71], v[144:147], v[204:207], v[68:71]
	v_mfma_f32_16x16x32_bf16 v[64:67], v[152:155], v[204:207], v[64:67]
	v_mfma_f32_16x16x32_bf16 v[112:115], v[148:151], v[178:181], v[112:115]
	v_mfma_f32_16x16x32_bf16 v[108:111], v[156:159], v[178:181], v[108:111]
	v_mfma_f32_16x16x32_bf16 v[100:103], v[148:151], v[192:195], v[100:103]
	v_mfma_f32_16x16x32_bf16 v[92:95], v[156:159], v[192:195], v[92:95]
	v_mfma_f32_16x16x32_bf16 v[84:87], v[148:151], v[200:203], v[84:87]
	v_mfma_f32_16x16x32_bf16 v[76:79], v[156:159], v[200:203], v[76:79]
	v_mfma_f32_16x16x32_bf16 v[68:71], v[148:151], v[208:211], v[68:71]
	v_mfma_f32_16x16x32_bf16 v[64:67], v[156:159], v[208:211], v[64:67]
	s_setprio 0
	s_barrier
; #define PG8_STAGE(bufoff, gbase, voff) do { _Pragma("unroll") for (int _i = 0; _i < 2; ++_i) \
;         __builtin_amdgcn_global_load_lds((const unsigned*)((const char*)(gbase) + (voff)[_i]), (PG8_LAS unsigned*)(lds + (bufoff) + ldsw + _i * 8192), 16, 0, 0); } while (0)
; #define PG8_LDA(dst, b, h) do { _Pragma("unroll") for (int m = 0; m < 4; ++m) _Pragma("unroll") for (int k = 0; k < 2; ++k) dst[m][k] = *(const PG8_LAS bf16x8*)(lds + PG8_SA(b, h) + aoff + m * 2048 + k * 1024); } while (0)
; #define PG8_MMA(ai, bj, At, Bt) do { __builtin_amdgcn_s_setprio(1); _Pragma("unroll") for (int m = 0; m < 4; ++m) _Pragma("unroll") for (int n = 0; n < 2; ++n) _Pragma("unroll") for (int k = 0; k < 2; ++k) \
;         acc[ai][bj][m][n] = __builtin_amdgcn_mfma_f32_16x16x32_bf16(Bt[n][k], At[m][k], acc[ai][bj][m][n], 0, 0, 0); __builtin_amdgcn_s_setprio(0); } while (0)
; #define PG8_WAIT_V(n) asm volatile("s_waitcnt vmcnt(" #n ")" ::: "memory")
; #define PG8_WAIT_L(n) asm volatile("s_waitcnt lgkmcnt(" #n ")" ::: "memory")
; #define PG8_BAR __builtin_amdgcn_s_barrier()
; #define PG8_SCHED __builtin_amdgcn_sched_barrier(0)
; template <class Epi, class Sched, bool ALIGN_EPI = false, bool SP2 = false>
; __device__ __forceinline__ void gemm_phase(PG8_LAS unsigned char* lds, const Gemm g, const Sched& S, const Epi& E) {
;     ...
;             PG8_LDA(At, 1, 1); PG8_STAGE(PG8_SB(1, 0), b3, voffB); PG8_STAGE(PG8_SB(1, 1), b3 + hstep, voffB); PG8_STAGE(PG8_SA(1, 0), a3, voffA);
;             PG8_WAIT_V(8); PG8_WAIT_L(0); PG8_BAR; PG8_MMA(1, 0, At, B0); PG8_MMA(1, 1, At, B1); PG8_BAR; PG8_SCHED;
	s_add_i32 s20, s44, s25
	v_lshl_add_u64 v[212:213], v[212:213], 0, s[8:9]
	s_mov_b32 m0, s20
	ds_read_b128 v[174:177], v191 offset:49152
	ds_read_b128 v[178:181], v191 offset:50176
	ds_read_b128 v[182:185], v191 offset:51200
	ds_read_b128 v[192:195], v191 offset:52224
	ds_read_b128 v[196:199], v191 offset:53248
	ds_read_b128 v[200:203], v191 offset:54272
	ds_read_b128 v[204:207], v191 offset:55296
	ds_read_b128 v[208:211], v191 offset:56320
	global_load_lds_dwordx4 v[212:213], off
	s_add_i32 m0, s20, 0x2000
	s_add_u32 s18, s18, 0xb0080
	v_lshl_add_u64 v[212:213], v[214:215], 0, s[8:9]
	s_addc_u32 s19, s19, 0
	s_add_i32 s20, s45, s25
	global_load_lds_dwordx4 v[212:213], off
	v_lshl_add_u64 v[212:213], s[18:19], 0, v[162:163]
	s_mov_b32 m0, s20
	s_nop 0
	global_load_lds_dwordx4 v[212:213], off
	v_lshl_add_u64 v[212:213], s[18:19], 0, v[166:167]
	s_add_i32 m0, s20, 0x2000
	s_nop 0
	global_load_lds_dwordx4 v[212:213], off
	v_lshl_add_u64 v[212:213], v[216:217], 0, s[8:9]
	s_mov_b32 m0, s33
	s_nop 0
	global_load_lds_dwordx4 v[212:213], off
	v_lshl_add_u64 v[212:213], v[218:219], 0, s[8:9]
	s_mov_b32 m0, s34
	s_nop 0
	global_load_lds_dwordx4 v[212:213], off
	s_waitcnt vmcnt(8)
	s_waitcnt lgkmcnt(0)
	s_barrier
	s_setprio 1
	s_waitcnt lgkmcnt(0)
	v_mfma_f32_16x16x32_bf16 v[60:63], v[128:131], v[174:177], v[60:63]
	v_mfma_f32_16x16x32_bf16 v[56:59], v[136:139], v[174:177], v[56:59]
	v_mfma_f32_16x16x32_bf16 v[48:51], v[128:131], v[182:185], v[48:51]
	v_mfma_f32_16x16x32_bf16 v[40:43], v[136:139], v[182:185], v[40:43]
	v_mfma_f32_16x16x32_bf16 v[32:35], v[128:131], v[196:199], v[32:35]
	v_mfma_f32_16x16x32_bf16 v[24:27], v[136:139], v[196:199], v[24:27]
	v_mfma_f32_16x16x32_bf16 v[16:19], v[128:131], v[204:207], v[16:19]
	v_mfma_f32_16x16x32_bf16 v[8:11], v[136:139], v[204:207], v[8:11]
	v_mfma_f32_16x16x32_bf16 v[60:63], v[132:135], v[178:181], v[60:63]
	v_mfma_f32_16x16x32_bf16 v[56:59], v[140:143], v[178:181], v[56:59]
	v_mfma_f32_16x16x32_bf16 v[48:51], v[132:135], v[192:195], v[48:51]
	v_mfma_f32_16x16x32_bf16 v[40:43], v[140:143], v[192:195], v[40:43]
	v_mfma_f32_16x16x32_bf16 v[32:35], v[132:135], v[200:203], v[32:35]
	v_mfma_f32_16x16x32_bf16 v[24:27], v[140:143], v[200:203], v[24:27]
	v_mfma_f32_16x16x32_bf16 v[16:19], v[132:135], v[208:211], v[16:19]
	v_mfma_f32_16x16x32_bf16 v[8:11], v[140:143], v[208:211], v[8:11]
	s_setprio 0
	s_setprio 1
	v_mfma_f32_16x16x32_bf16 v[52:55], v[144:147], v[174:177], v[52:55]
	v_mfma_f32_16x16x32_bf16 v[44:47], v[152:155], v[174:177], v[44:47]
	v_mfma_f32_16x16x32_bf16 v[36:39], v[144:147], v[182:185], v[36:39]
	v_mfma_f32_16x16x32_bf16 v[28:31], v[152:155], v[182:185], v[28:31]
	v_mfma_f32_16x16x32_bf16 v[20:23], v[144:147], v[196:199], v[20:23]
	v_mfma_f32_16x16x32_bf16 v[12:15], v[152:155], v[196:199], v[12:15]
	v_mfma_f32_16x16x32_bf16 v[4:7], v[144:147], v[204:207], v[4:7]
	v_mfma_f32_16x16x32_bf16 v[0:3], v[152:155], v[204:207], v[0:3]
	v_mfma_f32_16x16x32_bf16 v[52:55], v[148:151], v[178:181], v[52:55]
	v_mfma_f32_16x16x32_bf16 v[44:47], v[156:159], v[178:181], v[44:47]
	v_mfma_f32_16x16x32_bf16 v[36:39], v[148:151], v[192:195], v[36:39]
	v_mfma_f32_16x16x32_bf16 v[28:31], v[156:159], v[192:195], v[28:31]
	v_mfma_f32_16x16x32_bf16 v[20:23], v[148:151], v[200:203], v[20:23]
	v_mfma_f32_16x16x32_bf16 v[12:15], v[156:159], v[200:203], v[12:15]
	v_mfma_f32_16x16x32_bf16 v[4:7], v[148:151], v[208:211], v[4:7]
	v_mfma_f32_16x16x32_bf16 v[0:3], v[156:159], v[208:211], v[0:3]
	s_setprio 0
	s_barrier
	s_add_i32 s43, s43, 2
	s_add_u32 s16, s16, 0x100
	s_addc_u32 s17, s17, 0
	s_add_u32 s41, s41, 0x100
	s_addc_u32 s42, s42, 0
	s_cmp_gt_u32 s43, 41
